# P0: single-pass int8 conversion of the FFN1-in / merge-gate / mixer-in weights with workgroup-local column absmax (weights read once; old absmax items and conversion blocks bypassed)
# speedup vs baseline: 1.0136x; 1.0089x over previous
.Lcolmax_next:
	s_add_i32 s23, s23, s42
	s_add_i32 s2, s2, s42
	s_add_i32 s3, s3, s14
	s_add_i32 s10, s10, s14
	s_add_i32 s15, s15, s42
	s_add_i32 s18, s18, s42
	s_add_i32 s19, s19, s14
	s_add_i32 s20, s20, s14
	s_cmpk_gt_i32 s23, 0x3cff
	s_cbranch_scc1 .LBB0_34
.LBB0_14:
	s_cmpk_gt_i32 s23, 0x157f
	s_mov_b64 s[0:1], -1
	s_cbranch_scc0 .Lcolmax_next
	s_cmpk_gt_u32 s23, 0x2aff
	s_cbranch_scc0 .LBB0_25
	s_cmpk_gt_u32 s23, 0x32ff
	s_cbranch_scc0 .Lcolmax_next
	s_branch .Lcolmax_next
	s_and_b32 s0, 0xffff, s2
	s_mul_hi_u32 s0, s0, 0x6666667
	s_mul_hi_u32 s4, s0, 0x280000
	s_mul_i32 s5, s0, 0x280000
	s_mulk_i32 s0, 0x2800
	s_sub_i32 s0, s3, s0
	s_ashr_i32 s1, s0, 31
	s_lshl_b64 s[0:1], s[0:1], 2
	s_add_u32 s0, s5, s0
	s_addc_u32 s1, s4, s1
	v_lshl_add_u64 v[0:1], v[14:15], 0, s[0:1]
	v_mov_b32_e32 v5, 0
	s_mov_b32 s6, -16
	v_mov_b32_e32 v26, 0
	v_mov_b32_e32 v25, 0
	v_mov_b32_e32 v24, 0

.LBB0_88:
	s_or_b64 exec, exec, s[0:1]
	v_readlane_b32 s0, v254, 15
	s_lshl_b32 s21, s0, 9
	s_mov_b32 s14, s90
	s_cmpk_gt_i32 s90, 0x69ff
	s_waitcnt lgkmcnt(0)
	s_barrier
	s_cbranch_scc1 .LBB0_115
	v_mbcnt_lo_u32_b32 v135, -1, 0
	v_mbcnt_hi_u32_b32 v135, -1, v135
	v_lshrrev_b32_e32 v136, 2, v135
	v_and_b32_e32 v137, 3, v135
	v_lshlrev_b32_e32 v230, 4, v137
	v_readlane_b32 s62, v254, 17
	v_readlane_b32 s1, v254, 16
	v_readlane_b32 s72, v254, 15
	s_mov_b32 s74, 0x42fe0000
	s_mov_b32 s11, 0
	v_lshlrev_b32_e32 v139, 11, v137
	v_lshl_add_u32 v139, v136, 2, v139
	s_nop 1
	v_add_u32_e32 v139, s62, v139
	v_lshlrev_b32_e32 v174, 2, v135
	v_xor_b32_e32 v192, 0x10, v174
	v_xor_b32_e32 v193, 0x20, v174
	v_xor_b32_e32 v194, 0x40, v174
	v_xor_b32_e32 v195, 0x80, v174
	v_lshrrev_b32_e32 v175, 5, v135
	v_and_b32_e32 v176, 31, v135
	v_lshlrev_b32_e32 v212, 9, v175
	v_lshl_add_u32 v212, v176, 4, v212
	v_add_u32_e32 v212, s62, v212
	v_lshlrev_b32_e32 v213, 12, v175
	v_lshl_add_u32 v213, v176, 4, v213
	v_readlane_b32 s48, v255, 47
	v_readlane_b32 s49, v255, 48
	s_add_u32 s50, s34, 0x5100000
	s_addc_u32 s51, s35, 0
	s_add_u32 s52, s34, 0x80000
	s_addc_u32 s53, s35, 0
	v_mul_u32_u24_e32 v138, 0x20000, v136
	v_lshl_add_u32 v138, v137, 4, v138
	s_mul_i32 s3, s1, 0x1000000
	s_nop 1
	s_add_u32 s48, s48, s3
	s_addc_u32 s49, s49, 0
	s_mov_b32 s0, s72
	s_movk_i32 s61, 0x200
.Lc16_gates_loop:
	s_cmp_ge_u32 s0, s61
	s_cbranch_scc1 .Lc16_gates_done
	s_lshl_b32 s2, s0, 4
	s_lshl_b32 s3, s0, 6
	s_add_u32 s56, s48, s3
	s_addc_u32 s57, s49, 0
	global_load_dwordx4 v[6:9], v138, s[56:57] nt
	s_add_u32 s56, s56, 0x8000
	s_addc_u32 s57, s57, 0
	global_load_dwordx4 v[10:13], v138, s[56:57] nt
	s_add_u32 s56, s56, 0x8000
	s_addc_u32 s57, s57, 0
	global_load_dwordx4 v[14:17], v138, s[56:57] nt
	s_add_u32 s56, s56, 0x8000
	s_addc_u32 s57, s57, 0
	global_load_dwordx4 v[18:21], v138, s[56:57] nt
	s_add_u32 s56, s56, 0x1e8000
	s_addc_u32 s57, s57, 0
	global_load_dwordx4 v[22:25], v138, s[56:57] nt
	s_add_u32 s56, s56, 0x8000
	s_addc_u32 s57, s57, 0
	global_load_dwordx4 v[26:29], v138, s[56:57] nt
	s_add_u32 s56, s56, 0x8000
	s_addc_u32 s57, s57, 0
	global_load_dwordx4 v[30:33], v138, s[56:57] nt
	s_add_u32 s56, s56, 0x8000
	s_addc_u32 s57, s57, 0
	global_load_dwordx4 v[34:37], v138, s[56:57] nt
	s_add_u32 s56, s56, 0x1e8000
	s_addc_u32 s57, s57, 0
	global_load_dwordx4 v[38:41], v138, s[56:57] nt
	s_add_u32 s56, s56, 0x8000
	s_addc_u32 s57, s57, 0
	global_load_dwordx4 v[42:45], v138, s[56:57] nt
	s_add_u32 s56, s56, 0x8000
	s_addc_u32 s57, s57, 0
	global_load_dwordx4 v[46:49], v138, s[56:57] nt
	s_add_u32 s56, s56, 0x8000
	s_addc_u32 s57, s57, 0
	global_load_dwordx4 v[50:53], v138, s[56:57] nt
	s_add_u32 s56, s56, 0x1e8000
	s_addc_u32 s57, s57, 0
	global_load_dwordx4 v[54:57], v138, s[56:57] nt
	s_add_u32 s56, s56, 0x8000
	s_addc_u32 s57, s57, 0
	global_load_dwordx4 v[58:61], v138, s[56:57] nt
	s_add_u32 s56, s56, 0x8000
	s_addc_u32 s57, s57, 0
	global_load_dwordx4 v[62:65], v138, s[56:57] nt
	s_add_u32 s56, s56, 0x8000
	s_addc_u32 s57, s57, 0
	global_load_dwordx4 v[66:69], v138, s[56:57] nt
	s_add_u32 s56, s56, 0x1e8000
	s_addc_u32 s57, s57, 0
	global_load_dwordx4 v[70:73], v138, s[56:57] nt
	s_add_u32 s56, s56, 0x8000
	s_addc_u32 s57, s57, 0
	global_load_dwordx4 v[74:77], v138, s[56:57] nt
	s_add_u32 s56, s56, 0x8000
	s_addc_u32 s57, s57, 0
	global_load_dwordx4 v[78:81], v138, s[56:57] nt
	s_add_u32 s56, s56, 0x8000
	s_addc_u32 s57, s57, 0
	global_load_dwordx4 v[82:85], v138, s[56:57] nt
	s_add_u32 s56, s56, 0x1e8000
	s_addc_u32 s57, s57, 0
	global_load_dwordx4 v[86:89], v138, s[56:57] nt
	s_add_u32 s56, s56, 0x8000
	s_addc_u32 s57, s57, 0
	global_load_dwordx4 v[90:93], v138, s[56:57] nt
	s_add_u32 s56, s56, 0x8000
	s_addc_u32 s57, s57, 0
	global_load_dwordx4 v[94:97], v138, s[56:57] nt
	s_add_u32 s56, s56, 0x8000
	s_addc_u32 s57, s57, 0
	global_load_dwordx4 v[98:101], v138, s[56:57] nt
	s_add_u32 s56, s56, 0x1e8000
	s_addc_u32 s57, s57, 0
	global_load_dwordx4 v[102:105], v138, s[56:57] nt
	s_add_u32 s56, s56, 0x8000
	s_addc_u32 s57, s57, 0
	global_load_dwordx4 v[106:109], v138, s[56:57] nt
	s_add_u32 s56, s56, 0x8000
	s_addc_u32 s57, s57, 0
	global_load_dwordx4 v[110:113], v138, s[56:57] nt
	s_add_u32 s56, s56, 0x8000
	s_addc_u32 s57, s57, 0
	global_load_dwordx4 v[114:117], v138, s[56:57] nt
	s_add_u32 s56, s56, 0x1e8000
	s_addc_u32 s57, s57, 0
	global_load_dwordx4 v[118:121], v138, s[56:57] nt
	s_add_u32 s56, s56, 0x8000
	s_addc_u32 s57, s57, 0
	global_load_dwordx4 v[122:125], v138, s[56:57] nt
	s_add_u32 s56, s56, 0x8000
	s_addc_u32 s57, s57, 0
	global_load_dwordx4 v[126:129], v138, s[56:57] nt
	s_add_u32 s56, s56, 0x8000
	s_addc_u32 s57, s57, 0
	global_load_dwordx4 v[130:133], v138, s[56:57] nt
	s_mov_b32 s60, s2
	s_lshl_b32 s63, s11, 9
	s_add_u32 s63, s63, 0x21000
	s_lshl_b32 s3, s1, 6
	s_add_u32 s3, s3, s63
	v_add_u32_e32 v172, s3, v230
	v_add_u32_e32 v173, s63, v230
	s_waitcnt vmcnt(0)
	v_max3_f32 v216, |v6|, |v10|, |v14|
	v_max3_f32 v216, v216, |v18|, |v22|
	v_max3_f32 v216, v216, |v26|, |v30|
	v_max3_f32 v216, v216, |v34|, |v38|
	v_max3_f32 v216, v216, |v42|, |v46|
	v_max3_f32 v216, v216, |v50|, |v54|
	v_max3_f32 v216, v216, |v58|, |v62|
	v_max3_f32 v216, v216, |v66|, |v70|
	v_max3_f32 v216, v216, |v74|, |v78|
	v_max3_f32 v216, v216, |v82|, |v86|
	v_max3_f32 v216, v216, |v90|, |v94|
	v_max3_f32 v216, v216, |v98|, |v102|
	v_max3_f32 v216, v216, |v106|, |v110|
	v_max3_f32 v216, v216, |v114|, |v118|
	v_max3_f32 v216, v216, |v122|, |v126|
	v_max_f32_e64 v216, v216, |v130|
	v_max3_f32 v217, |v7|, |v11|, |v15|
	v_max3_f32 v217, v217, |v19|, |v23|
	v_max3_f32 v217, v217, |v27|, |v31|
	v_max3_f32 v217, v217, |v35|, |v39|
	v_max3_f32 v217, v217, |v43|, |v47|
	v_max3_f32 v217, v217, |v51|, |v55|
	v_max3_f32 v217, v217, |v59|, |v63|
	v_max3_f32 v217, v217, |v67|, |v71|
	v_max3_f32 v217, v217, |v75|, |v79|
	v_max3_f32 v217, v217, |v83|, |v87|
	v_max3_f32 v217, v217, |v91|, |v95|
	v_max3_f32 v217, v217, |v99|, |v103|
	v_max3_f32 v217, v217, |v107|, |v111|
	v_max3_f32 v217, v217, |v115|, |v119|
	v_max3_f32 v217, v217, |v123|, |v127|
	v_max_f32_e64 v217, v217, |v131|
	v_max3_f32 v218, |v8|, |v12|, |v16|
	v_max3_f32 v218, v218, |v20|, |v24|
	v_max3_f32 v218, v218, |v28|, |v32|
	v_max3_f32 v218, v218, |v36|, |v40|
	v_max3_f32 v218, v218, |v44|, |v48|
	v_max3_f32 v218, v218, |v52|, |v56|
	v_max3_f32 v218, v218, |v60|, |v64|
	v_max3_f32 v218, v218, |v68|, |v72|
	v_max3_f32 v218, v218, |v76|, |v80|
	v_max3_f32 v218, v218, |v84|, |v88|
	v_max3_f32 v218, v218, |v92|, |v96|
	v_max3_f32 v218, v218, |v100|, |v104|
	v_max3_f32 v218, v218, |v108|, |v112|
	v_max3_f32 v218, v218, |v116|, |v120|
	v_max3_f32 v218, v218, |v124|, |v128|
	v_max_f32_e64 v218, v218, |v132|
	v_max3_f32 v219, |v9|, |v13|, |v17|
	v_max3_f32 v219, v219, |v21|, |v25|
	v_max3_f32 v219, v219, |v29|, |v33|
	v_max3_f32 v219, v219, |v37|, |v41|
	v_max3_f32 v219, v219, |v45|, |v49|
	v_max3_f32 v219, v219, |v53|, |v57|
	v_max3_f32 v219, v219, |v61|, |v65|
	v_max3_f32 v219, v219, |v69|, |v73|
	v_max3_f32 v219, v219, |v77|, |v81|
	v_max3_f32 v219, v219, |v85|, |v89|
	v_max3_f32 v219, v219, |v93|, |v97|
	v_max3_f32 v219, v219, |v101|, |v105|
	v_max3_f32 v219, v219, |v109|, |v113|
	v_max3_f32 v219, v219, |v117|, |v121|
	v_max3_f32 v219, v219, |v125|, |v129|
	v_max_f32_e64 v219, v219, |v133|
	ds_bpermute_b32 v174, v192, v216
	ds_bpermute_b32 v175, v192, v217
	ds_bpermute_b32 v176, v192, v218
	ds_bpermute_b32 v177, v192, v219
	s_waitcnt lgkmcnt(0)
	v_max_f32_e32 v216, v216, v174
	v_max_f32_e32 v217, v217, v175
	v_max_f32_e32 v218, v218, v176
	v_max_f32_e32 v219, v219, v177
	ds_bpermute_b32 v174, v193, v216
	ds_bpermute_b32 v175, v193, v217
	ds_bpermute_b32 v176, v193, v218
	ds_bpermute_b32 v177, v193, v219
	s_waitcnt lgkmcnt(0)
	v_max_f32_e32 v216, v216, v174
	v_max_f32_e32 v217, v217, v175
	v_max_f32_e32 v218, v218, v176
	v_max_f32_e32 v219, v219, v177
	ds_bpermute_b32 v174, v194, v216
	ds_bpermute_b32 v175, v194, v217
	ds_bpermute_b32 v176, v194, v218
	ds_bpermute_b32 v177, v194, v219
	s_waitcnt lgkmcnt(0)
	v_max_f32_e32 v216, v216, v174
	v_max_f32_e32 v217, v217, v175
	v_max_f32_e32 v218, v218, v176
	v_max_f32_e32 v219, v219, v177
	ds_bpermute_b32 v174, v195, v216
	ds_bpermute_b32 v175, v195, v217
	ds_bpermute_b32 v176, v195, v218
	ds_bpermute_b32 v177, v195, v219
	s_waitcnt lgkmcnt(0)
	v_max_f32_e32 v216, v216, v174
	v_max_f32_e32 v217, v217, v175
	v_max_f32_e32 v218, v218, v176
	v_max_f32_e32 v219, v219, v177
	s_mov_b64 s[70:71], exec
	s_mov_b64 exec, 15
	ds_write_b128 v172, v[216:219]
	s_mov_b64 exec, s[70:71]
	s_waitcnt lgkmcnt(0)
	s_barrier
	ds_read_b128 v[140:143], v173 offset:0
	ds_read_b128 v[144:147], v173 offset:64
	ds_read_b128 v[148:151], v173 offset:128
	ds_read_b128 v[152:155], v173 offset:192
	ds_read_b128 v[156:159], v173 offset:256
	ds_read_b128 v[160:163], v173 offset:320
	ds_read_b128 v[164:167], v173 offset:384
	ds_read_b128 v[232:235], v173 offset:448
	s_waitcnt lgkmcnt(0)
	v_max3_f32 v220, v140, v144, v148
	v_max3_f32 v220, v220, v152, v156
	v_max3_f32 v220, v220, v160, v164
	v_max_f32_e32 v220, v220, v232
	v_max3_f32 v221, v141, v145, v149
	v_max3_f32 v221, v221, v153, v157
	v_max3_f32 v221, v221, v161, v165
	v_max_f32_e32 v221, v221, v233
	v_max3_f32 v222, v142, v146, v150
	v_max3_f32 v222, v222, v154, v158
	v_max3_f32 v222, v222, v162, v166
	v_max_f32_e32 v222, v222, v234
	v_max3_f32 v223, v143, v147, v151
	v_max3_f32 v223, v223, v155, v159
	v_max3_f32 v223, v223, v163, v167
	v_max_f32_e32 v223, v223, v235
	s_cmp_lg_u32 s1, 0
	s_cbranch_scc1 .Lc16_gates_nocm
	s_lshl_b32 s3, s2, 2
	s_add_u32 s56, s52, s3
	s_addc_u32 s57, s53, 0
	s_mov_b64 s[70:71], exec
	s_mov_b64 exec, 15
	global_store_dwordx4 v230, v[220:223], s[56:57]
	s_mov_b64 exec, s[70:71]
.Lc16_gates_nocm:
	v_div_scale_f32 v175, s[70:71], v220, v220, s74
	v_rcp_f32_e32 v176, v175
	s_nop 0
	v_fma_f32 v177, -v175, v176, 1.0
	v_fmac_f32_e32 v176, v177, v176
	v_div_scale_f32 v177, vcc, s74, v220, s74
	v_mul_f32_e32 v178, v177, v176
	v_fma_f32 v180, -v175, v178, v177
	v_fmac_f32_e32 v178, v180, v176
	v_fma_f32 v175, -v175, v178, v177
	s_nop 0
	v_div_fmas_f32 v175, v175, v176, v178
	v_div_fixup_f32 v175, v175, v220, s74
	v_cmp_lt_f32_e32 vcc, 0, v220
	s_nop 1
	v_cndmask_b32_e32 v226, 0, v175, vcc
	v_div_scale_f32 v175, s[70:71], v221, v221, s74
	v_rcp_f32_e32 v176, v175
	s_nop 0
	v_fma_f32 v177, -v175, v176, 1.0
	v_fmac_f32_e32 v176, v177, v176
	v_div_scale_f32 v177, vcc, s74, v221, s74
	v_mul_f32_e32 v178, v177, v176
	v_fma_f32 v180, -v175, v178, v177
	v_fmac_f32_e32 v178, v180, v176
	v_fma_f32 v175, -v175, v178, v177
	s_nop 0
	v_div_fmas_f32 v175, v175, v176, v178
	v_div_fixup_f32 v175, v175, v221, s74
	v_cmp_lt_f32_e32 vcc, 0, v221
	s_nop 1
	v_cndmask_b32_e32 v227, 0, v175, vcc
	v_div_scale_f32 v175, s[70:71], v222, v222, s74
	v_rcp_f32_e32 v176, v175
	s_nop 0
	v_fma_f32 v177, -v175, v176, 1.0
	v_fmac_f32_e32 v176, v177, v176
	v_div_scale_f32 v177, vcc, s74, v222, s74
	v_mul_f32_e32 v178, v177, v176
	v_fma_f32 v180, -v175, v178, v177
	v_fmac_f32_e32 v178, v180, v176
	v_fma_f32 v175, -v175, v178, v177
	s_nop 0
	v_div_fmas_f32 v175, v175, v176, v178
	v_div_fixup_f32 v175, v175, v222, s74
	v_cmp_lt_f32_e32 vcc, 0, v222
	s_nop 1
	v_cndmask_b32_e32 v228, 0, v175, vcc
	v_div_scale_f32 v175, s[70:71], v223, v223, s74
	v_rcp_f32_e32 v176, v175
	s_nop 0
	v_fma_f32 v177, -v175, v176, 1.0
	v_fmac_f32_e32 v176, v177, v176
	v_div_scale_f32 v177, vcc, s74, v223, s74
	v_mul_f32_e32 v178, v177, v176
	v_fma_f32 v180, -v175, v178, v177
	v_fmac_f32_e32 v178, v180, v176
	v_fma_f32 v175, -v175, v178, v177
	s_nop 0
	v_div_fmas_f32 v175, v175, v176, v178
	v_div_fixup_f32 v175, v175, v223, s74
	v_cmp_lt_f32_e32 vcc, 0, v223
	s_nop 1
	v_cndmask_b32_e32 v229, 0, v175, vcc
	v_mul_f32_e32 v186, v6, v226
	v_rndne_f32_e32 v186, v186
	v_cvt_i32_f32_e32 v186, v186
	v_mul_f32_e32 v187, v10, v226
	v_rndne_f32_e32 v187, v187
	v_cvt_i32_f32_e32 v187, v187
	v_mul_f32_e32 v188, v14, v226
	v_rndne_f32_e32 v188, v188
	v_cvt_i32_f32_e32 v188, v188
	v_mul_f32_e32 v189, v18, v226
	v_rndne_f32_e32 v189, v189
	v_cvt_i32_f32_e32 v189, v189
	v_and_b32_e32 v186, 0xff, v186
	v_and_b32_e32 v187, 0xff, v187
	v_and_b32_e32 v188, 0xff, v188
	v_lshl_or_b32 v190, v187, 8, v186
	v_lshl_or_b32 v190, v188, 16, v190
	v_lshl_or_b32 v190, v189, 24, v190
	ds_write_b32 v139, v190 offset:0
	v_mul_f32_e32 v186, v7, v227
	v_rndne_f32_e32 v186, v186
	v_cvt_i32_f32_e32 v186, v186
	v_mul_f32_e32 v187, v11, v227
	v_rndne_f32_e32 v187, v187
	v_cvt_i32_f32_e32 v187, v187
	v_mul_f32_e32 v188, v15, v227
	v_rndne_f32_e32 v188, v188
	v_cvt_i32_f32_e32 v188, v188
	v_mul_f32_e32 v189, v19, v227
	v_rndne_f32_e32 v189, v189
	v_cvt_i32_f32_e32 v189, v189
	v_and_b32_e32 v186, 0xff, v186
	v_and_b32_e32 v187, 0xff, v187
	v_and_b32_e32 v188, 0xff, v188
	v_lshl_or_b32 v190, v187, 8, v186
	v_lshl_or_b32 v190, v188, 16, v190
	v_lshl_or_b32 v190, v189, 24, v190
	ds_write_b32 v139, v190 offset:512
	v_mul_f32_e32 v186, v8, v228
	v_rndne_f32_e32 v186, v186
	v_cvt_i32_f32_e32 v186, v186
	v_mul_f32_e32 v187, v12, v228
	v_rndne_f32_e32 v187, v187
	v_cvt_i32_f32_e32 v187, v187
	v_mul_f32_e32 v188, v16, v228
	v_rndne_f32_e32 v188, v188
	v_cvt_i32_f32_e32 v188, v188
	v_mul_f32_e32 v189, v20, v228
	v_rndne_f32_e32 v189, v189
	v_cvt_i32_f32_e32 v189, v189
	v_and_b32_e32 v186, 0xff, v186
	v_and_b32_e32 v187, 0xff, v187
	v_and_b32_e32 v188, 0xff, v188
	v_lshl_or_b32 v190, v187, 8, v186
	v_lshl_or_b32 v190, v188, 16, v190
	v_lshl_or_b32 v190, v189, 24, v190
	ds_write_b32 v139, v190 offset:1024
	v_mul_f32_e32 v186, v9, v229
	v_rndne_f32_e32 v186, v186
	v_cvt_i32_f32_e32 v186, v186
	v_mul_f32_e32 v187, v13, v229
	v_rndne_f32_e32 v187, v187
	v_cvt_i32_f32_e32 v187, v187
	v_mul_f32_e32 v188, v17, v229
	v_rndne_f32_e32 v188, v188
	v_cvt_i32_f32_e32 v188, v188
	v_mul_f32_e32 v189, v21, v229
	v_rndne_f32_e32 v189, v189
	v_cvt_i32_f32_e32 v189, v189
	v_and_b32_e32 v186, 0xff, v186
	v_and_b32_e32 v187, 0xff, v187
	v_and_b32_e32 v188, 0xff, v188
	v_lshl_or_b32 v190, v187, 8, v186
	v_lshl_or_b32 v190, v188, 16, v190
	v_lshl_or_b32 v190, v189, 24, v190
	ds_write_b32 v139, v190 offset:1536
	v_mul_f32_e32 v186, v22, v226
	v_rndne_f32_e32 v186, v186
	v_cvt_i32_f32_e32 v186, v186
	v_mul_f32_e32 v187, v26, v226
	v_rndne_f32_e32 v187, v187
	v_cvt_i32_f32_e32 v187, v187
	v_mul_f32_e32 v188, v30, v226
	v_rndne_f32_e32 v188, v188
	v_cvt_i32_f32_e32 v188, v188
	v_mul_f32_e32 v189, v34, v226
	v_rndne_f32_e32 v189, v189
	v_cvt_i32_f32_e32 v189, v189
	v_and_b32_e32 v186, 0xff, v186
	v_and_b32_e32 v187, 0xff, v187
	v_and_b32_e32 v188, 0xff, v188
	v_lshl_or_b32 v190, v187, 8, v186
	v_lshl_or_b32 v190, v188, 16, v190
	v_lshl_or_b32 v190, v189, 24, v190
	ds_write_b32 v139, v190 offset:64
	v_mul_f32_e32 v186, v23, v227
	v_rndne_f32_e32 v186, v186
	v_cvt_i32_f32_e32 v186, v186
	v_mul_f32_e32 v187, v27, v227
	v_rndne_f32_e32 v187, v187
	v_cvt_i32_f32_e32 v187, v187
	v_mul_f32_e32 v188, v31, v227
	v_rndne_f32_e32 v188, v188
	v_cvt_i32_f32_e32 v188, v188
	v_mul_f32_e32 v189, v35, v227
	v_rndne_f32_e32 v189, v189
	v_cvt_i32_f32_e32 v189, v189
	v_and_b32_e32 v186, 0xff, v186
	v_and_b32_e32 v187, 0xff, v187
	v_and_b32_e32 v188, 0xff, v188
	v_lshl_or_b32 v190, v187, 8, v186
	v_lshl_or_b32 v190, v188, 16, v190
	v_lshl_or_b32 v190, v189, 24, v190
	ds_write_b32 v139, v190 offset:576
	v_mul_f32_e32 v186, v24, v228
	v_rndne_f32_e32 v186, v186
	v_cvt_i32_f32_e32 v186, v186
	v_mul_f32_e32 v187, v28, v228
	v_rndne_f32_e32 v187, v187
	v_cvt_i32_f32_e32 v187, v187
	v_mul_f32_e32 v188, v32, v228
	v_rndne_f32_e32 v188, v188
	v_cvt_i32_f32_e32 v188, v188
	v_mul_f32_e32 v189, v36, v228
	v_rndne_f32_e32 v189, v189
	v_cvt_i32_f32_e32 v189, v189
	v_and_b32_e32 v186, 0xff, v186
	v_and_b32_e32 v187, 0xff, v187
	v_and_b32_e32 v188, 0xff, v188
	v_lshl_or_b32 v190, v187, 8, v186
	v_lshl_or_b32 v190, v188, 16, v190
	v_lshl_or_b32 v190, v189, 24, v190
	ds_write_b32 v139, v190 offset:1088
	v_mul_f32_e32 v186, v25, v229
	v_rndne_f32_e32 v186, v186
	v_cvt_i32_f32_e32 v186, v186
	v_mul_f32_e32 v187, v29, v229
	v_rndne_f32_e32 v187, v187
	v_cvt_i32_f32_e32 v187, v187
	v_mul_f32_e32 v188, v33, v229
	v_rndne_f32_e32 v188, v188
	v_cvt_i32_f32_e32 v188, v188
	v_mul_f32_e32 v189, v37, v229
	v_rndne_f32_e32 v189, v189
	v_cvt_i32_f32_e32 v189, v189
	v_and_b32_e32 v186, 0xff, v186
	v_and_b32_e32 v187, 0xff, v187
	v_and_b32_e32 v188, 0xff, v188
	v_lshl_or_b32 v190, v187, 8, v186
	v_lshl_or_b32 v190, v188, 16, v190
	v_lshl_or_b32 v190, v189, 24, v190
	ds_write_b32 v139, v190 offset:1600
	v_mul_f32_e32 v186, v38, v226
	v_rndne_f32_e32 v186, v186
	v_cvt_i32_f32_e32 v186, v186
	v_mul_f32_e32 v187, v42, v226
	v_rndne_f32_e32 v187, v187
	v_cvt_i32_f32_e32 v187, v187
	v_mul_f32_e32 v188, v46, v226
	v_rndne_f32_e32 v188, v188
	v_cvt_i32_f32_e32 v188, v188
	v_mul_f32_e32 v189, v50, v226
	v_rndne_f32_e32 v189, v189
	v_cvt_i32_f32_e32 v189, v189
	v_and_b32_e32 v186, 0xff, v186
	v_and_b32_e32 v187, 0xff, v187
	v_and_b32_e32 v188, 0xff, v188
	v_lshl_or_b32 v190, v187, 8, v186
	v_lshl_or_b32 v190, v188, 16, v190
	v_lshl_or_b32 v190, v189, 24, v190
	ds_write_b32 v139, v190 offset:128
	v_mul_f32_e32 v186, v39, v227
	v_rndne_f32_e32 v186, v186
	v_cvt_i32_f32_e32 v186, v186
	v_mul_f32_e32 v187, v43, v227
	v_rndne_f32_e32 v187, v187
	v_cvt_i32_f32_e32 v187, v187
	v_mul_f32_e32 v188, v47, v227
	v_rndne_f32_e32 v188, v188
	v_cvt_i32_f32_e32 v188, v188
	v_mul_f32_e32 v189, v51, v227
	v_rndne_f32_e32 v189, v189
	v_cvt_i32_f32_e32 v189, v189
	v_and_b32_e32 v186, 0xff, v186
	v_and_b32_e32 v187, 0xff, v187
	v_and_b32_e32 v188, 0xff, v188
	v_lshl_or_b32 v190, v187, 8, v186
	v_lshl_or_b32 v190, v188, 16, v190
	v_lshl_or_b32 v190, v189, 24, v190
	ds_write_b32 v139, v190 offset:640
	v_mul_f32_e32 v186, v40, v228
	v_rndne_f32_e32 v186, v186
	v_cvt_i32_f32_e32 v186, v186
	v_mul_f32_e32 v187, v44, v228
	v_rndne_f32_e32 v187, v187
	v_cvt_i32_f32_e32 v187, v187
	v_mul_f32_e32 v188, v48, v228
	v_rndne_f32_e32 v188, v188
	v_cvt_i32_f32_e32 v188, v188
	v_mul_f32_e32 v189, v52, v228
	v_rndne_f32_e32 v189, v189
	v_cvt_i32_f32_e32 v189, v189
	v_and_b32_e32 v186, 0xff, v186
	v_and_b32_e32 v187, 0xff, v187
	v_and_b32_e32 v188, 0xff, v188
	v_lshl_or_b32 v190, v187, 8, v186
	v_lshl_or_b32 v190, v188, 16, v190
	v_lshl_or_b32 v190, v189, 24, v190
	ds_write_b32 v139, v190 offset:1152
	v_mul_f32_e32 v186, v41, v229
	v_rndne_f32_e32 v186, v186
	v_cvt_i32_f32_e32 v186, v186
	v_mul_f32_e32 v187, v45, v229
	v_rndne_f32_e32 v187, v187
	v_cvt_i32_f32_e32 v187, v187
	v_mul_f32_e32 v188, v49, v229
	v_rndne_f32_e32 v188, v188
	v_cvt_i32_f32_e32 v188, v188
	v_mul_f32_e32 v189, v53, v229
	v_rndne_f32_e32 v189, v189
	v_cvt_i32_f32_e32 v189, v189
	v_and_b32_e32 v186, 0xff, v186
	v_and_b32_e32 v187, 0xff, v187
	v_and_b32_e32 v188, 0xff, v188
	v_lshl_or_b32 v190, v187, 8, v186
	v_lshl_or_b32 v190, v188, 16, v190
	v_lshl_or_b32 v190, v189, 24, v190
	ds_write_b32 v139, v190 offset:1664
	v_mul_f32_e32 v186, v54, v226
	v_rndne_f32_e32 v186, v186
	v_cvt_i32_f32_e32 v186, v186
	v_mul_f32_e32 v187, v58, v226
	v_rndne_f32_e32 v187, v187
	v_cvt_i32_f32_e32 v187, v187
	v_mul_f32_e32 v188, v62, v226
	v_rndne_f32_e32 v188, v188
	v_cvt_i32_f32_e32 v188, v188
	v_mul_f32_e32 v189, v66, v226
	v_rndne_f32_e32 v189, v189
	v_cvt_i32_f32_e32 v189, v189
	v_and_b32_e32 v186, 0xff, v186
	v_and_b32_e32 v187, 0xff, v187
	v_and_b32_e32 v188, 0xff, v188
	v_lshl_or_b32 v190, v187, 8, v186
	v_lshl_or_b32 v190, v188, 16, v190
	v_lshl_or_b32 v190, v189, 24, v190
	ds_write_b32 v139, v190 offset:192
	v_mul_f32_e32 v186, v55, v227
	v_rndne_f32_e32 v186, v186
	v_cvt_i32_f32_e32 v186, v186
	v_mul_f32_e32 v187, v59, v227
	v_rndne_f32_e32 v187, v187
	v_cvt_i32_f32_e32 v187, v187
	v_mul_f32_e32 v188, v63, v227
	v_rndne_f32_e32 v188, v188
	v_cvt_i32_f32_e32 v188, v188
	v_mul_f32_e32 v189, v67, v227
	v_rndne_f32_e32 v189, v189
	v_cvt_i32_f32_e32 v189, v189
	v_and_b32_e32 v186, 0xff, v186
	v_and_b32_e32 v187, 0xff, v187
	v_and_b32_e32 v188, 0xff, v188
	v_lshl_or_b32 v190, v187, 8, v186
	v_lshl_or_b32 v190, v188, 16, v190
	v_lshl_or_b32 v190, v189, 24, v190
	ds_write_b32 v139, v190 offset:704
	v_mul_f32_e32 v186, v56, v228
	v_rndne_f32_e32 v186, v186
	v_cvt_i32_f32_e32 v186, v186
	v_mul_f32_e32 v187, v60, v228
	v_rndne_f32_e32 v187, v187
	v_cvt_i32_f32_e32 v187, v187
	v_mul_f32_e32 v188, v64, v228
	v_rndne_f32_e32 v188, v188
	v_cvt_i32_f32_e32 v188, v188
	v_mul_f32_e32 v189, v68, v228
	v_rndne_f32_e32 v189, v189
	v_cvt_i32_f32_e32 v189, v189
	v_and_b32_e32 v186, 0xff, v186
	v_and_b32_e32 v187, 0xff, v187
	v_and_b32_e32 v188, 0xff, v188
	v_lshl_or_b32 v190, v187, 8, v186
	v_lshl_or_b32 v190, v188, 16, v190
	v_lshl_or_b32 v190, v189, 24, v190
	ds_write_b32 v139, v190 offset:1216
	v_mul_f32_e32 v186, v57, v229
	v_rndne_f32_e32 v186, v186
	v_cvt_i32_f32_e32 v186, v186
	v_mul_f32_e32 v187, v61, v229
	v_rndne_f32_e32 v187, v187
	v_cvt_i32_f32_e32 v187, v187
	v_mul_f32_e32 v188, v65, v229
	v_rndne_f32_e32 v188, v188
	v_cvt_i32_f32_e32 v188, v188
	v_mul_f32_e32 v189, v69, v229
	v_rndne_f32_e32 v189, v189
	v_cvt_i32_f32_e32 v189, v189
	v_and_b32_e32 v186, 0xff, v186
	v_and_b32_e32 v187, 0xff, v187
	v_and_b32_e32 v188, 0xff, v188
	v_lshl_or_b32 v190, v187, 8, v186
	v_lshl_or_b32 v190, v188, 16, v190
	v_lshl_or_b32 v190, v189, 24, v190
	ds_write_b32 v139, v190 offset:1728
	v_mul_f32_e32 v186, v70, v226
	v_rndne_f32_e32 v186, v186
	v_cvt_i32_f32_e32 v186, v186
	v_mul_f32_e32 v187, v74, v226
	v_rndne_f32_e32 v187, v187
	v_cvt_i32_f32_e32 v187, v187
	v_mul_f32_e32 v188, v78, v226
	v_rndne_f32_e32 v188, v188
	v_cvt_i32_f32_e32 v188, v188
	v_mul_f32_e32 v189, v82, v226
	v_rndne_f32_e32 v189, v189
	v_cvt_i32_f32_e32 v189, v189
	v_and_b32_e32 v186, 0xff, v186
	v_and_b32_e32 v187, 0xff, v187
	v_and_b32_e32 v188, 0xff, v188
	v_lshl_or_b32 v190, v187, 8, v186
	v_lshl_or_b32 v190, v188, 16, v190
	v_lshl_or_b32 v190, v189, 24, v190
	ds_write_b32 v139, v190 offset:256
	v_mul_f32_e32 v186, v71, v227
	v_rndne_f32_e32 v186, v186
	v_cvt_i32_f32_e32 v186, v186
	v_mul_f32_e32 v187, v75, v227
	v_rndne_f32_e32 v187, v187
	v_cvt_i32_f32_e32 v187, v187
	v_mul_f32_e32 v188, v79, v227
	v_rndne_f32_e32 v188, v188
	v_cvt_i32_f32_e32 v188, v188
	v_mul_f32_e32 v189, v83, v227
	v_rndne_f32_e32 v189, v189
	v_cvt_i32_f32_e32 v189, v189
	v_and_b32_e32 v186, 0xff, v186
	v_and_b32_e32 v187, 0xff, v187
	v_and_b32_e32 v188, 0xff, v188
	v_lshl_or_b32 v190, v187, 8, v186
	v_lshl_or_b32 v190, v188, 16, v190
	v_lshl_or_b32 v190, v189, 24, v190
	ds_write_b32 v139, v190 offset:768
	v_mul_f32_e32 v186, v72, v228
	v_rndne_f32_e32 v186, v186
	v_cvt_i32_f32_e32 v186, v186
	v_mul_f32_e32 v187, v76, v228
	v_rndne_f32_e32 v187, v187
	v_cvt_i32_f32_e32 v187, v187
	v_mul_f32_e32 v188, v80, v228
	v_rndne_f32_e32 v188, v188
	v_cvt_i32_f32_e32 v188, v188
	v_mul_f32_e32 v189, v84, v228
	v_rndne_f32_e32 v189, v189
	v_cvt_i32_f32_e32 v189, v189
	v_and_b32_e32 v186, 0xff, v186
	v_and_b32_e32 v187, 0xff, v187
	v_and_b32_e32 v188, 0xff, v188
	v_lshl_or_b32 v190, v187, 8, v186
	v_lshl_or_b32 v190, v188, 16, v190
	v_lshl_or_b32 v190, v189, 24, v190
	ds_write_b32 v139, v190 offset:1280
	v_mul_f32_e32 v186, v73, v229
	v_rndne_f32_e32 v186, v186
	v_cvt_i32_f32_e32 v186, v186
	v_mul_f32_e32 v187, v77, v229
	v_rndne_f32_e32 v187, v187
	v_cvt_i32_f32_e32 v187, v187
	v_mul_f32_e32 v188, v81, v229
	v_rndne_f32_e32 v188, v188
	v_cvt_i32_f32_e32 v188, v188
	v_mul_f32_e32 v189, v85, v229
	v_rndne_f32_e32 v189, v189
	v_cvt_i32_f32_e32 v189, v189
	v_and_b32_e32 v186, 0xff, v186
	v_and_b32_e32 v187, 0xff, v187
	v_and_b32_e32 v188, 0xff, v188
	v_lshl_or_b32 v190, v187, 8, v186
	v_lshl_or_b32 v190, v188, 16, v190
	v_lshl_or_b32 v190, v189, 24, v190
	ds_write_b32 v139, v190 offset:1792
	v_mul_f32_e32 v186, v86, v226
	v_rndne_f32_e32 v186, v186
	v_cvt_i32_f32_e32 v186, v186
	v_mul_f32_e32 v187, v90, v226
	v_rndne_f32_e32 v187, v187
	v_cvt_i32_f32_e32 v187, v187
	v_mul_f32_e32 v188, v94, v226
	v_rndne_f32_e32 v188, v188
	v_cvt_i32_f32_e32 v188, v188
	v_mul_f32_e32 v189, v98, v226
	v_rndne_f32_e32 v189, v189
	v_cvt_i32_f32_e32 v189, v189
	v_and_b32_e32 v186, 0xff, v186
	v_and_b32_e32 v187, 0xff, v187
	v_and_b32_e32 v188, 0xff, v188
	v_lshl_or_b32 v190, v187, 8, v186
	v_lshl_or_b32 v190, v188, 16, v190
	v_lshl_or_b32 v190, v189, 24, v190
	ds_write_b32 v139, v190 offset:320
	v_mul_f32_e32 v186, v87, v227
	v_rndne_f32_e32 v186, v186
	v_cvt_i32_f32_e32 v186, v186
	v_mul_f32_e32 v187, v91, v227
	v_rndne_f32_e32 v187, v187
	v_cvt_i32_f32_e32 v187, v187
	v_mul_f32_e32 v188, v95, v227
	v_rndne_f32_e32 v188, v188
	v_cvt_i32_f32_e32 v188, v188
	v_mul_f32_e32 v189, v99, v227
	v_rndne_f32_e32 v189, v189
	v_cvt_i32_f32_e32 v189, v189
	v_and_b32_e32 v186, 0xff, v186
	v_and_b32_e32 v187, 0xff, v187
	v_and_b32_e32 v188, 0xff, v188
	v_lshl_or_b32 v190, v187, 8, v186
	v_lshl_or_b32 v190, v188, 16, v190
	v_lshl_or_b32 v190, v189, 24, v190
	ds_write_b32 v139, v190 offset:832
	v_mul_f32_e32 v186, v88, v228
	v_rndne_f32_e32 v186, v186
	v_cvt_i32_f32_e32 v186, v186
	v_mul_f32_e32 v187, v92, v228
	v_rndne_f32_e32 v187, v187
	v_cvt_i32_f32_e32 v187, v187
	v_mul_f32_e32 v188, v96, v228
	v_rndne_f32_e32 v188, v188
	v_cvt_i32_f32_e32 v188, v188
	v_mul_f32_e32 v189, v100, v228
	v_rndne_f32_e32 v189, v189
	v_cvt_i32_f32_e32 v189, v189
	v_and_b32_e32 v186, 0xff, v186
	v_and_b32_e32 v187, 0xff, v187
	v_and_b32_e32 v188, 0xff, v188
	v_lshl_or_b32 v190, v187, 8, v186
	v_lshl_or_b32 v190, v188, 16, v190
	v_lshl_or_b32 v190, v189, 24, v190
	ds_write_b32 v139, v190 offset:1344
	v_mul_f32_e32 v186, v89, v229
	v_rndne_f32_e32 v186, v186
	v_cvt_i32_f32_e32 v186, v186
	v_mul_f32_e32 v187, v93, v229
	v_rndne_f32_e32 v187, v187
	v_cvt_i32_f32_e32 v187, v187
	v_mul_f32_e32 v188, v97, v229
	v_rndne_f32_e32 v188, v188
	v_cvt_i32_f32_e32 v188, v188
	v_mul_f32_e32 v189, v101, v229
	v_rndne_f32_e32 v189, v189
	v_cvt_i32_f32_e32 v189, v189
	v_and_b32_e32 v186, 0xff, v186
	v_and_b32_e32 v187, 0xff, v187
	v_and_b32_e32 v188, 0xff, v188
	v_lshl_or_b32 v190, v187, 8, v186
	v_lshl_or_b32 v190, v188, 16, v190
	v_lshl_or_b32 v190, v189, 24, v190
	ds_write_b32 v139, v190 offset:1856
	v_mul_f32_e32 v186, v102, v226
	v_rndne_f32_e32 v186, v186
	v_cvt_i32_f32_e32 v186, v186
	v_mul_f32_e32 v187, v106, v226
	v_rndne_f32_e32 v187, v187
	v_cvt_i32_f32_e32 v187, v187
	v_mul_f32_e32 v188, v110, v226
	v_rndne_f32_e32 v188, v188
	v_cvt_i32_f32_e32 v188, v188
	v_mul_f32_e32 v189, v114, v226
	v_rndne_f32_e32 v189, v189
	v_cvt_i32_f32_e32 v189, v189
	v_and_b32_e32 v186, 0xff, v186
	v_and_b32_e32 v187, 0xff, v187
	v_and_b32_e32 v188, 0xff, v188
	v_lshl_or_b32 v190, v187, 8, v186
	v_lshl_or_b32 v190, v188, 16, v190
	v_lshl_or_b32 v190, v189, 24, v190
	ds_write_b32 v139, v190 offset:384
	v_mul_f32_e32 v186, v103, v227
	v_rndne_f32_e32 v186, v186
	v_cvt_i32_f32_e32 v186, v186
	v_mul_f32_e32 v187, v107, v227
	v_rndne_f32_e32 v187, v187
	v_cvt_i32_f32_e32 v187, v187
	v_mul_f32_e32 v188, v111, v227
	v_rndne_f32_e32 v188, v188
	v_cvt_i32_f32_e32 v188, v188
	v_mul_f32_e32 v189, v115, v227
	v_rndne_f32_e32 v189, v189
	v_cvt_i32_f32_e32 v189, v189
	v_and_b32_e32 v186, 0xff, v186
	v_and_b32_e32 v187, 0xff, v187
	v_and_b32_e32 v188, 0xff, v188
	v_lshl_or_b32 v190, v187, 8, v186
	v_lshl_or_b32 v190, v188, 16, v190
	v_lshl_or_b32 v190, v189, 24, v190
	ds_write_b32 v139, v190 offset:896
	v_mul_f32_e32 v186, v104, v228
	v_rndne_f32_e32 v186, v186
	v_cvt_i32_f32_e32 v186, v186
	v_mul_f32_e32 v187, v108, v228
	v_rndne_f32_e32 v187, v187
	v_cvt_i32_f32_e32 v187, v187
	v_mul_f32_e32 v188, v112, v228
	v_rndne_f32_e32 v188, v188
	v_cvt_i32_f32_e32 v188, v188
	v_mul_f32_e32 v189, v116, v228
	v_rndne_f32_e32 v189, v189
	v_cvt_i32_f32_e32 v189, v189
	v_and_b32_e32 v186, 0xff, v186
	v_and_b32_e32 v187, 0xff, v187
	v_and_b32_e32 v188, 0xff, v188
	v_lshl_or_b32 v190, v187, 8, v186
	v_lshl_or_b32 v190, v188, 16, v190
	v_lshl_or_b32 v190, v189, 24, v190
	ds_write_b32 v139, v190 offset:1408
	v_mul_f32_e32 v186, v105, v229
	v_rndne_f32_e32 v186, v186
	v_cvt_i32_f32_e32 v186, v186
	v_mul_f32_e32 v187, v109, v229
	v_rndne_f32_e32 v187, v187
	v_cvt_i32_f32_e32 v187, v187
	v_mul_f32_e32 v188, v113, v229
	v_rndne_f32_e32 v188, v188
	v_cvt_i32_f32_e32 v188, v188
	v_mul_f32_e32 v189, v117, v229
	v_rndne_f32_e32 v189, v189
	v_cvt_i32_f32_e32 v189, v189
	v_and_b32_e32 v186, 0xff, v186
	v_and_b32_e32 v187, 0xff, v187
	v_and_b32_e32 v188, 0xff, v188
	v_lshl_or_b32 v190, v187, 8, v186
	v_lshl_or_b32 v190, v188, 16, v190
	v_lshl_or_b32 v190, v189, 24, v190
	ds_write_b32 v139, v190 offset:1920
	v_mul_f32_e32 v186, v118, v226
	v_rndne_f32_e32 v186, v186
	v_cvt_i32_f32_e32 v186, v186
	v_mul_f32_e32 v187, v122, v226
	v_rndne_f32_e32 v187, v187
	v_cvt_i32_f32_e32 v187, v187
	v_mul_f32_e32 v188, v126, v226
	v_rndne_f32_e32 v188, v188
	v_cvt_i32_f32_e32 v188, v188
	v_mul_f32_e32 v189, v130, v226
	v_rndne_f32_e32 v189, v189
	v_cvt_i32_f32_e32 v189, v189
	v_and_b32_e32 v186, 0xff, v186
	v_and_b32_e32 v187, 0xff, v187
	v_and_b32_e32 v188, 0xff, v188
	v_lshl_or_b32 v190, v187, 8, v186
	v_lshl_or_b32 v190, v188, 16, v190
	v_lshl_or_b32 v190, v189, 24, v190
	ds_write_b32 v139, v190 offset:448
	v_mul_f32_e32 v186, v119, v227
	v_rndne_f32_e32 v186, v186
	v_cvt_i32_f32_e32 v186, v186
	v_mul_f32_e32 v187, v123, v227
	v_rndne_f32_e32 v187, v187
	v_cvt_i32_f32_e32 v187, v187
	v_mul_f32_e32 v188, v127, v227
	v_rndne_f32_e32 v188, v188
	v_cvt_i32_f32_e32 v188, v188
	v_mul_f32_e32 v189, v131, v227
	v_rndne_f32_e32 v189, v189
	v_cvt_i32_f32_e32 v189, v189
	v_and_b32_e32 v186, 0xff, v186
	v_and_b32_e32 v187, 0xff, v187
	v_and_b32_e32 v188, 0xff, v188
	v_lshl_or_b32 v190, v187, 8, v186
	v_lshl_or_b32 v190, v188, 16, v190
	v_lshl_or_b32 v190, v189, 24, v190
	ds_write_b32 v139, v190 offset:960
	v_mul_f32_e32 v186, v120, v228
	v_rndne_f32_e32 v186, v186
	v_cvt_i32_f32_e32 v186, v186
	v_mul_f32_e32 v187, v124, v228
	v_rndne_f32_e32 v187, v187
	v_cvt_i32_f32_e32 v187, v187
	v_mul_f32_e32 v188, v128, v228
	v_rndne_f32_e32 v188, v188
	v_cvt_i32_f32_e32 v188, v188
	v_mul_f32_e32 v189, v132, v228
	v_rndne_f32_e32 v189, v189
	v_cvt_i32_f32_e32 v189, v189
	v_and_b32_e32 v186, 0xff, v186
	v_and_b32_e32 v187, 0xff, v187
	v_and_b32_e32 v188, 0xff, v188
	v_lshl_or_b32 v190, v187, 8, v186
	v_lshl_or_b32 v190, v188, 16, v190
	v_lshl_or_b32 v190, v189, 24, v190
	ds_write_b32 v139, v190 offset:1472
	v_mul_f32_e32 v186, v121, v229
	v_rndne_f32_e32 v186, v186
	v_cvt_i32_f32_e32 v186, v186
	v_mul_f32_e32 v187, v125, v229
	v_rndne_f32_e32 v187, v187
	v_cvt_i32_f32_e32 v187, v187
	v_mul_f32_e32 v188, v129, v229
	v_rndne_f32_e32 v188, v188
	v_cvt_i32_f32_e32 v188, v188
	v_mul_f32_e32 v189, v133, v229
	v_rndne_f32_e32 v189, v189
	v_cvt_i32_f32_e32 v189, v189
	v_and_b32_e32 v186, 0xff, v186
	v_and_b32_e32 v187, 0xff, v187
	v_and_b32_e32 v188, 0xff, v188
	v_lshl_or_b32 v190, v187, 8, v186
	v_lshl_or_b32 v190, v188, 16, v190
	v_lshl_or_b32 v190, v189, 24, v190
	ds_write_b32 v139, v190 offset:1984
	s_waitcnt lgkmcnt(0)
	s_lshl_b32 s3, s60, 12
	s_lshl_b32 s10, s1, 9
	s_add_u32 s3, s3, s10
	s_add_u32 s58, s50, s3
	s_addc_u32 s59, s51, 0
	ds_read_b128 v[204:207], v212 offset:0
	s_waitcnt lgkmcnt(0)
	global_store_dwordx4 v213, v[204:207], s[58:59]
	s_add_u32 s58, s58, 0x2000
	s_addc_u32 s59, s59, 0
	ds_read_b128 v[208:211], v212 offset:1024
	s_waitcnt lgkmcnt(0)
	global_store_dwordx4 v213, v[208:211], s[58:59]
	s_add_u32 s58, s58, 0x2000
	s_addc_u32 s59, s59, 0
	ds_read_b128 v[204:207], v212 offset:2048
	s_waitcnt lgkmcnt(0)
	global_store_dwordx4 v213, v[204:207], s[58:59]
	s_add_u32 s58, s58, 0x2000
	s_addc_u32 s59, s59, 0
	ds_read_b128 v[208:211], v212 offset:3072
	s_waitcnt lgkmcnt(0)
	global_store_dwordx4 v213, v[208:211], s[58:59]
	s_add_u32 s58, s58, 0x2000
	s_addc_u32 s59, s59, 0
	ds_read_b128 v[204:207], v212 offset:4096
	s_waitcnt lgkmcnt(0)
	global_store_dwordx4 v213, v[204:207], s[58:59]
	s_add_u32 s58, s58, 0x2000
	s_addc_u32 s59, s59, 0
	ds_read_b128 v[208:211], v212 offset:5120
	s_waitcnt lgkmcnt(0)
	global_store_dwordx4 v213, v[208:211], s[58:59]
	s_add_u32 s58, s58, 0x2000
	s_addc_u32 s59, s59, 0
	ds_read_b128 v[204:207], v212 offset:6144
	s_waitcnt lgkmcnt(0)
	global_store_dwordx4 v213, v[204:207], s[58:59]
	s_add_u32 s58, s58, 0x2000
	s_addc_u32 s59, s59, 0
	ds_read_b128 v[208:211], v212 offset:7168
	s_waitcnt lgkmcnt(0)
	global_store_dwordx4 v213, v[208:211], s[58:59]
	s_xor_b32 s11, s11, 1
	s_add_u32 s0, s0, s33
	s_branch .Lc16_gates_loop
.Lc16_gates_done:
	v_readlane_b32 s48, v255, 19
	v_readlane_b32 s49, v255, 20
	s_add_u32 s50, s34, 0xe700000
	s_addc_u32 s51, s35, 0
	s_add_u32 s52, s34, 0x40000
	s_addc_u32 s53, s35, 0
	v_mul_u32_u24_e32 v138, 0x56000, v136
	v_lshl_add_u32 v138, v137, 4, v138
	s_mul_i32 s3, s1, 0x2b00000
	s_nop 1
	s_add_u32 s48, s48, s3
	s_addc_u32 s49, s49, 0
	s_mov_b32 s0, s72
	s_movk_i32 s61, 0x560
.Lc16_ffn1_loop:
	s_cmp_ge_u32 s0, s61
	s_cbranch_scc1 .Lc16_ffn1_done
	s_lshl_b32 s2, s0, 4
	s_lshl_b32 s3, s0, 6
	s_add_u32 s56, s48, s3
	s_addc_u32 s57, s49, 0
	global_load_dwordx4 v[6:9], v138, s[56:57] nt
	s_add_u32 s56, s56, 0x15800
	s_addc_u32 s57, s57, 0
	global_load_dwordx4 v[10:13], v138, s[56:57] nt
	s_add_u32 s56, s56, 0x15800
	s_addc_u32 s57, s57, 0
	global_load_dwordx4 v[14:17], v138, s[56:57] nt
	s_add_u32 s56, s56, 0x15800
	s_addc_u32 s57, s57, 0
	global_load_dwordx4 v[18:21], v138, s[56:57] nt
	s_add_u32 s56, s56, 0x51f800
	s_addc_u32 s57, s57, 0
	global_load_dwordx4 v[22:25], v138, s[56:57] nt
	s_add_u32 s56, s56, 0x15800
	s_addc_u32 s57, s57, 0
	global_load_dwordx4 v[26:29], v138, s[56:57] nt
	s_add_u32 s56, s56, 0x15800
	s_addc_u32 s57, s57, 0
	global_load_dwordx4 v[30:33], v138, s[56:57] nt
	s_add_u32 s56, s56, 0x15800
	s_addc_u32 s57, s57, 0
	global_load_dwordx4 v[34:37], v138, s[56:57] nt
	s_add_u32 s56, s56, 0x51f800
	s_addc_u32 s57, s57, 0
	global_load_dwordx4 v[38:41], v138, s[56:57] nt
	s_add_u32 s56, s56, 0x15800
	s_addc_u32 s57, s57, 0
	global_load_dwordx4 v[42:45], v138, s[56:57] nt
	s_add_u32 s56, s56, 0x15800
	s_addc_u32 s57, s57, 0
	global_load_dwordx4 v[46:49], v138, s[56:57] nt
	s_add_u32 s56, s56, 0x15800
	s_addc_u32 s57, s57, 0
	global_load_dwordx4 v[50:53], v138, s[56:57] nt
	s_add_u32 s56, s56, 0x51f800
	s_addc_u32 s57, s57, 0
	global_load_dwordx4 v[54:57], v138, s[56:57] nt
	s_add_u32 s56, s56, 0x15800
	s_addc_u32 s57, s57, 0
	global_load_dwordx4 v[58:61], v138, s[56:57] nt
	s_add_u32 s56, s56, 0x15800
	s_addc_u32 s57, s57, 0
	global_load_dwordx4 v[62:65], v138, s[56:57] nt
	s_add_u32 s56, s56, 0x15800
	s_addc_u32 s57, s57, 0
	global_load_dwordx4 v[66:69], v138, s[56:57] nt
	s_add_u32 s56, s56, 0x51f800
	s_addc_u32 s57, s57, 0
	global_load_dwordx4 v[70:73], v138, s[56:57] nt
	s_add_u32 s56, s56, 0x15800
	s_addc_u32 s57, s57, 0
	global_load_dwordx4 v[74:77], v138, s[56:57] nt
	s_add_u32 s56, s56, 0x15800
	s_addc_u32 s57, s57, 0
	global_load_dwordx4 v[78:81], v138, s[56:57] nt
	s_add_u32 s56, s56, 0x15800
	s_addc_u32 s57, s57, 0
	global_load_dwordx4 v[82:85], v138, s[56:57] nt
	s_add_u32 s56, s56, 0x51f800
	s_addc_u32 s57, s57, 0
	global_load_dwordx4 v[86:89], v138, s[56:57] nt
	s_add_u32 s56, s56, 0x15800
	s_addc_u32 s57, s57, 0
	global_load_dwordx4 v[90:93], v138, s[56:57] nt
	s_add_u32 s56, s56, 0x15800
	s_addc_u32 s57, s57, 0
	global_load_dwordx4 v[94:97], v138, s[56:57] nt
	s_add_u32 s56, s56, 0x15800
	s_addc_u32 s57, s57, 0
	global_load_dwordx4 v[98:101], v138, s[56:57] nt
	s_add_u32 s56, s56, 0x51f800
	s_addc_u32 s57, s57, 0
	global_load_dwordx4 v[102:105], v138, s[56:57] nt
	s_add_u32 s56, s56, 0x15800
	s_addc_u32 s57, s57, 0
	global_load_dwordx4 v[106:109], v138, s[56:57] nt
	s_add_u32 s56, s56, 0x15800
	s_addc_u32 s57, s57, 0
	global_load_dwordx4 v[110:113], v138, s[56:57] nt
	s_add_u32 s56, s56, 0x15800
	s_addc_u32 s57, s57, 0
	global_load_dwordx4 v[114:117], v138, s[56:57] nt
	s_add_u32 s56, s56, 0x51f800
	s_addc_u32 s57, s57, 0
	global_load_dwordx4 v[118:121], v138, s[56:57] nt
	s_add_u32 s56, s56, 0x15800
	s_addc_u32 s57, s57, 0
	global_load_dwordx4 v[122:125], v138, s[56:57] nt
	s_add_u32 s56, s56, 0x15800
	s_addc_u32 s57, s57, 0
	global_load_dwordx4 v[126:129], v138, s[56:57] nt
	s_add_u32 s56, s56, 0x15800
	s_addc_u32 s57, s57, 0
	global_load_dwordx4 v[130:133], v138, s[56:57] nt
	s_cmp_ge_u32 s2, 0x2b00
	s_cselect_b32 s75, 128, 0
	s_cselect_b32 s3, 0x2b00, 0
	s_sub_u32 s3, s2, s3
	s_lshr_b32 s60, s3, 7
	s_lshl_b32 s60, s60, 8
	s_and_b32 s3, s3, 127
	s_add_u32 s60, s60, s3
	s_add_u32 s60, s60, s75
	s_lshl_b32 s63, s11, 9
	s_add_u32 s63, s63, 0x21000
	s_lshl_b32 s3, s1, 6
	s_add_u32 s3, s3, s63
	v_add_u32_e32 v172, s3, v230
	v_add_u32_e32 v173, s63, v230
	s_waitcnt vmcnt(0)
	v_max3_f32 v216, |v6|, |v10|, |v14|
	v_max3_f32 v216, v216, |v18|, |v22|
	v_max3_f32 v216, v216, |v26|, |v30|
	v_max3_f32 v216, v216, |v34|, |v38|
	v_max3_f32 v216, v216, |v42|, |v46|
	v_max3_f32 v216, v216, |v50|, |v54|
	v_max3_f32 v216, v216, |v58|, |v62|
	v_max3_f32 v216, v216, |v66|, |v70|
	v_max3_f32 v216, v216, |v74|, |v78|
	v_max3_f32 v216, v216, |v82|, |v86|
	v_max3_f32 v216, v216, |v90|, |v94|
	v_max3_f32 v216, v216, |v98|, |v102|
	v_max3_f32 v216, v216, |v106|, |v110|
	v_max3_f32 v216, v216, |v114|, |v118|
	v_max3_f32 v216, v216, |v122|, |v126|
	v_max_f32_e64 v216, v216, |v130|
	v_max3_f32 v217, |v7|, |v11|, |v15|
	v_max3_f32 v217, v217, |v19|, |v23|
	v_max3_f32 v217, v217, |v27|, |v31|
	v_max3_f32 v217, v217, |v35|, |v39|
	v_max3_f32 v217, v217, |v43|, |v47|
	v_max3_f32 v217, v217, |v51|, |v55|
	v_max3_f32 v217, v217, |v59|, |v63|
	v_max3_f32 v217, v217, |v67|, |v71|
	v_max3_f32 v217, v217, |v75|, |v79|
	v_max3_f32 v217, v217, |v83|, |v87|
	v_max3_f32 v217, v217, |v91|, |v95|
	v_max3_f32 v217, v217, |v99|, |v103|
	v_max3_f32 v217, v217, |v107|, |v111|
	v_max3_f32 v217, v217, |v115|, |v119|
	v_max3_f32 v217, v217, |v123|, |v127|
	v_max_f32_e64 v217, v217, |v131|
	v_max3_f32 v218, |v8|, |v12|, |v16|
	v_max3_f32 v218, v218, |v20|, |v24|
	v_max3_f32 v218, v218, |v28|, |v32|
	v_max3_f32 v218, v218, |v36|, |v40|
	v_max3_f32 v218, v218, |v44|, |v48|
	v_max3_f32 v218, v218, |v52|, |v56|
	v_max3_f32 v218, v218, |v60|, |v64|
	v_max3_f32 v218, v218, |v68|, |v72|
	v_max3_f32 v218, v218, |v76|, |v80|
	v_max3_f32 v218, v218, |v84|, |v88|
	v_max3_f32 v218, v218, |v92|, |v96|
	v_max3_f32 v218, v218, |v100|, |v104|
	v_max3_f32 v218, v218, |v108|, |v112|
	v_max3_f32 v218, v218, |v116|, |v120|
	v_max3_f32 v218, v218, |v124|, |v128|
	v_max_f32_e64 v218, v218, |v132|
	v_max3_f32 v219, |v9|, |v13|, |v17|
	v_max3_f32 v219, v219, |v21|, |v25|
	v_max3_f32 v219, v219, |v29|, |v33|
	v_max3_f32 v219, v219, |v37|, |v41|
	v_max3_f32 v219, v219, |v45|, |v49|
	v_max3_f32 v219, v219, |v53|, |v57|
	v_max3_f32 v219, v219, |v61|, |v65|
	v_max3_f32 v219, v219, |v69|, |v73|
	v_max3_f32 v219, v219, |v77|, |v81|
	v_max3_f32 v219, v219, |v85|, |v89|
	v_max3_f32 v219, v219, |v93|, |v97|
	v_max3_f32 v219, v219, |v101|, |v105|
	v_max3_f32 v219, v219, |v109|, |v113|
	v_max3_f32 v219, v219, |v117|, |v121|
	v_max3_f32 v219, v219, |v125|, |v129|
	v_max_f32_e64 v219, v219, |v133|
	ds_bpermute_b32 v174, v192, v216
	ds_bpermute_b32 v175, v192, v217
	ds_bpermute_b32 v176, v192, v218
	ds_bpermute_b32 v177, v192, v219
	s_waitcnt lgkmcnt(0)
	v_max_f32_e32 v216, v216, v174
	v_max_f32_e32 v217, v217, v175
	v_max_f32_e32 v218, v218, v176
	v_max_f32_e32 v219, v219, v177
	ds_bpermute_b32 v174, v193, v216
	ds_bpermute_b32 v175, v193, v217
	ds_bpermute_b32 v176, v193, v218
	ds_bpermute_b32 v177, v193, v219
	s_waitcnt lgkmcnt(0)
	v_max_f32_e32 v216, v216, v174
	v_max_f32_e32 v217, v217, v175
	v_max_f32_e32 v218, v218, v176
	v_max_f32_e32 v219, v219, v177
	ds_bpermute_b32 v174, v194, v216
	ds_bpermute_b32 v175, v194, v217
	ds_bpermute_b32 v176, v194, v218
	ds_bpermute_b32 v177, v194, v219
	s_waitcnt lgkmcnt(0)
	v_max_f32_e32 v216, v216, v174
	v_max_f32_e32 v217, v217, v175
	v_max_f32_e32 v218, v218, v176
	v_max_f32_e32 v219, v219, v177
	ds_bpermute_b32 v174, v195, v216
	ds_bpermute_b32 v175, v195, v217
	ds_bpermute_b32 v176, v195, v218
	ds_bpermute_b32 v177, v195, v219
	s_waitcnt lgkmcnt(0)
	v_max_f32_e32 v216, v216, v174
	v_max_f32_e32 v217, v217, v175
	v_max_f32_e32 v218, v218, v176
	v_max_f32_e32 v219, v219, v177
	s_mov_b64 s[70:71], exec
	s_mov_b64 exec, 15
	ds_write_b128 v172, v[216:219]
	s_mov_b64 exec, s[70:71]
	s_waitcnt lgkmcnt(0)
	s_barrier
	ds_read_b128 v[140:143], v173 offset:0
	ds_read_b128 v[144:147], v173 offset:64
	ds_read_b128 v[148:151], v173 offset:128
	ds_read_b128 v[152:155], v173 offset:192
	ds_read_b128 v[156:159], v173 offset:256
	ds_read_b128 v[160:163], v173 offset:320
	ds_read_b128 v[164:167], v173 offset:384
	ds_read_b128 v[232:235], v173 offset:448
	s_waitcnt lgkmcnt(0)
	v_max3_f32 v220, v140, v144, v148
	v_max3_f32 v220, v220, v152, v156
	v_max3_f32 v220, v220, v160, v164
	v_max_f32_e32 v220, v220, v232
	v_max3_f32 v221, v141, v145, v149
	v_max3_f32 v221, v221, v153, v157
	v_max3_f32 v221, v221, v161, v165
	v_max_f32_e32 v221, v221, v233
	v_max3_f32 v222, v142, v146, v150
	v_max3_f32 v222, v222, v154, v158
	v_max3_f32 v222, v222, v162, v166
	v_max_f32_e32 v222, v222, v234
	v_max3_f32 v223, v143, v147, v151
	v_max3_f32 v223, v223, v155, v159
	v_max3_f32 v223, v223, v163, v167
	v_max_f32_e32 v223, v223, v235
	s_cmp_lg_u32 s1, 0
	s_cbranch_scc1 .Lc16_ffn1_nocm
	s_lshl_b32 s3, s2, 2
	s_add_u32 s56, s52, s3
	s_addc_u32 s57, s53, 0
	s_mov_b64 s[70:71], exec
	s_mov_b64 exec, 15
	global_store_dwordx4 v230, v[220:223], s[56:57]
	s_mov_b64 exec, s[70:71]

.Lc16_ffn1_done:
	v_readlane_b32 s48, v255, 27
	v_readlane_b32 s49, v255, 28
	s_add_u32 s50, s34, 0x100000
	s_addc_u32 s51, s35, 0
	s_add_u32 s52, s34, 0xe0000
	s_addc_u32 s53, s35, 0
	v_mul_u32_u24_e32 v138, 0x28000, v136
	v_lshl_add_u32 v138, v137, 4, v138
	s_mul_i32 s3, s1, 0x1400000
	s_nop 1
	s_add_u32 s48, s48, s3
	s_addc_u32 s49, s49, 0
	s_mov_b32 s0, s72
	s_movk_i32 s61, 0x280
.Lc16_mixer_loop:
	s_cmp_ge_u32 s0, s61
	s_cbranch_scc1 .Lc16_mixer_done
	s_lshl_b32 s2, s0, 4
	s_lshl_b32 s3, s0, 6
	s_add_u32 s56, s48, s3
	s_addc_u32 s57, s49, 0
	global_load_dwordx4 v[6:9], v138, s[56:57]
	s_add_u32 s56, s56, 0xa000
	s_addc_u32 s57, s57, 0
	global_load_dwordx4 v[10:13], v138, s[56:57]
	s_add_u32 s56, s56, 0xa000
	s_addc_u32 s57, s57, 0
	global_load_dwordx4 v[14:17], v138, s[56:57]
	s_add_u32 s56, s56, 0xa000
	s_addc_u32 s57, s57, 0
	global_load_dwordx4 v[18:21], v138, s[56:57]
	s_add_u32 s56, s56, 0x262000
	s_addc_u32 s57, s57, 0
	global_load_dwordx4 v[22:25], v138, s[56:57]
	s_add_u32 s56, s56, 0xa000
	s_addc_u32 s57, s57, 0
	global_load_dwordx4 v[26:29], v138, s[56:57]
	s_add_u32 s56, s56, 0xa000
	s_addc_u32 s57, s57, 0
	global_load_dwordx4 v[30:33], v138, s[56:57]
	s_add_u32 s56, s56, 0xa000
	s_addc_u32 s57, s57, 0
	global_load_dwordx4 v[34:37], v138, s[56:57]
	s_add_u32 s56, s56, 0x262000
	s_addc_u32 s57, s57, 0
	global_load_dwordx4 v[38:41], v138, s[56:57]
	s_add_u32 s56, s56, 0xa000
	s_addc_u32 s57, s57, 0
	global_load_dwordx4 v[42:45], v138, s[56:57]
	s_add_u32 s56, s56, 0xa000
	s_addc_u32 s57, s57, 0
	global_load_dwordx4 v[46:49], v138, s[56:57]
	s_add_u32 s56, s56, 0xa000
	s_addc_u32 s57, s57, 0
	global_load_dwordx4 v[50:53], v138, s[56:57]
	s_add_u32 s56, s56, 0x262000
	s_addc_u32 s57, s57, 0
	global_load_dwordx4 v[54:57], v138, s[56:57]
	s_add_u32 s56, s56, 0xa000
	s_addc_u32 s57, s57, 0
	global_load_dwordx4 v[58:61], v138, s[56:57]
	s_add_u32 s56, s56, 0xa000
	s_addc_u32 s57, s57, 0
	global_load_dwordx4 v[62:65], v138, s[56:57]
	s_add_u32 s56, s56, 0xa000
	s_addc_u32 s57, s57, 0
	global_load_dwordx4 v[66:69], v138, s[56:57]
	s_add_u32 s56, s56, 0x262000
	s_addc_u32 s57, s57, 0
	global_load_dwordx4 v[70:73], v138, s[56:57]
	s_add_u32 s56, s56, 0xa000
	s_addc_u32 s57, s57, 0
	global_load_dwordx4 v[74:77], v138, s[56:57]
	s_add_u32 s56, s56, 0xa000
	s_addc_u32 s57, s57, 0
	global_load_dwordx4 v[78:81], v138, s[56:57]
	s_add_u32 s56, s56, 0xa000
	s_addc_u32 s57, s57, 0
	global_load_dwordx4 v[82:85], v138, s[56:57]
	s_add_u32 s56, s56, 0x262000
	s_addc_u32 s57, s57, 0
	global_load_dwordx4 v[86:89], v138, s[56:57]
	s_add_u32 s56, s56, 0xa000
	s_addc_u32 s57, s57, 0
	global_load_dwordx4 v[90:93], v138, s[56:57]
	s_add_u32 s56, s56, 0xa000
	s_addc_u32 s57, s57, 0
	global_load_dwordx4 v[94:97], v138, s[56:57]
	s_add_u32 s56, s56, 0xa000
	s_addc_u32 s57, s57, 0
	global_load_dwordx4 v[98:101], v138, s[56:57]
	s_add_u32 s56, s56, 0x262000
	s_addc_u32 s57, s57, 0
	global_load_dwordx4 v[102:105], v138, s[56:57]
	s_add_u32 s56, s56, 0xa000
	s_addc_u32 s57, s57, 0
	global_load_dwordx4 v[106:109], v138, s[56:57]
	s_add_u32 s56, s56, 0xa000
	s_addc_u32 s57, s57, 0
	global_load_dwordx4 v[110:113], v138, s[56:57]
	s_add_u32 s56, s56, 0xa000
	s_addc_u32 s57, s57, 0
	global_load_dwordx4 v[114:117], v138, s[56:57]
	s_add_u32 s56, s56, 0x262000
	s_addc_u32 s57, s57, 0
	global_load_dwordx4 v[118:121], v138, s[56:57]
	s_add_u32 s56, s56, 0xa000
	s_addc_u32 s57, s57, 0
	global_load_dwordx4 v[122:125], v138, s[56:57]
	s_add_u32 s56, s56, 0xa000
	s_addc_u32 s57, s57, 0
	global_load_dwordx4 v[126:129], v138, s[56:57]
	s_add_u32 s56, s56, 0xa000
	s_addc_u32 s57, s57, 0
	global_load_dwordx4 v[130:133], v138, s[56:57]
	s_mov_b32 s60, s2
	s_lshl_b32 s63, s11, 9
	s_add_u32 s63, s63, 0x21000
	s_lshl_b32 s3, s1, 6
	s_add_u32 s3, s3, s63
	v_add_u32_e32 v172, s3, v230
	v_add_u32_e32 v173, s63, v230
	s_waitcnt vmcnt(0)
	v_max3_f32 v216, |v6|, |v10|, |v14|
	v_max3_f32 v216, v216, |v18|, |v22|
	v_max3_f32 v216, v216, |v26|, |v30|
	v_max3_f32 v216, v216, |v34|, |v38|
	v_max3_f32 v216, v216, |v42|, |v46|
	v_max3_f32 v216, v216, |v50|, |v54|
	v_max3_f32 v216, v216, |v58|, |v62|
	v_max3_f32 v216, v216, |v66|, |v70|
	v_max3_f32 v216, v216, |v74|, |v78|
	v_max3_f32 v216, v216, |v82|, |v86|
	v_max3_f32 v216, v216, |v90|, |v94|
	v_max3_f32 v216, v216, |v98|, |v102|
	v_max3_f32 v216, v216, |v106|, |v110|
	v_max3_f32 v216, v216, |v114|, |v118|
	v_max3_f32 v216, v216, |v122|, |v126|
	v_max_f32_e64 v216, v216, |v130|
	v_max3_f32 v217, |v7|, |v11|, |v15|
	v_max3_f32 v217, v217, |v19|, |v23|
	v_max3_f32 v217, v217, |v27|, |v31|
	v_max3_f32 v217, v217, |v35|, |v39|
	v_max3_f32 v217, v217, |v43|, |v47|
	v_max3_f32 v217, v217, |v51|, |v55|
	v_max3_f32 v217, v217, |v59|, |v63|
	v_max3_f32 v217, v217, |v67|, |v71|
	v_max3_f32 v217, v217, |v75|, |v79|
	v_max3_f32 v217, v217, |v83|, |v87|
	v_max3_f32 v217, v217, |v91|, |v95|
	v_max3_f32 v217, v217, |v99|, |v103|
	v_max3_f32 v217, v217, |v107|, |v111|
	v_max3_f32 v217, v217, |v115|, |v119|
	v_max3_f32 v217, v217, |v123|, |v127|
	v_max_f32_e64 v217, v217, |v131|
	v_max3_f32 v218, |v8|, |v12|, |v16|
	v_max3_f32 v218, v218, |v20|, |v24|
	v_max3_f32 v218, v218, |v28|, |v32|
	v_max3_f32 v218, v218, |v36|, |v40|
	v_max3_f32 v218, v218, |v44|, |v48|
	v_max3_f32 v218, v218, |v52|, |v56|
	v_max3_f32 v218, v218, |v60|, |v64|
	v_max3_f32 v218, v218, |v68|, |v72|
	v_max3_f32 v218, v218, |v76|, |v80|
	v_max3_f32 v218, v218, |v84|, |v88|
	v_max3_f32 v218, v218, |v92|, |v96|
	v_max3_f32 v218, v218, |v100|, |v104|
	v_max3_f32 v218, v218, |v108|, |v112|
	v_max3_f32 v218, v218, |v116|, |v120|
	v_max3_f32 v218, v218, |v124|, |v128|
	v_max_f32_e64 v218, v218, |v132|
	v_max3_f32 v219, |v9|, |v13|, |v17|
	v_max3_f32 v219, v219, |v21|, |v25|
	v_max3_f32 v219, v219, |v29|, |v33|
	v_max3_f32 v219, v219, |v37|, |v41|
	v_max3_f32 v219, v219, |v45|, |v49|
	v_max3_f32 v219, v219, |v53|, |v57|
	v_max3_f32 v219, v219, |v61|, |v65|
	v_max3_f32 v219, v219, |v69|, |v73|
	v_max3_f32 v219, v219, |v77|, |v81|
	v_max3_f32 v219, v219, |v85|, |v89|
	v_max3_f32 v219, v219, |v93|, |v97|
	v_max3_f32 v219, v219, |v101|, |v105|
	v_max3_f32 v219, v219, |v109|, |v113|
	v_max3_f32 v219, v219, |v117|, |v121|
	v_max3_f32 v219, v219, |v125|, |v129|
	v_max_f32_e64 v219, v219, |v133|
	ds_bpermute_b32 v174, v192, v216
	ds_bpermute_b32 v175, v192, v217
	ds_bpermute_b32 v176, v192, v218
	ds_bpermute_b32 v177, v192, v219
	s_waitcnt lgkmcnt(0)
	v_max_f32_e32 v216, v216, v174
	v_max_f32_e32 v217, v217, v175
	v_max_f32_e32 v218, v218, v176
	v_max_f32_e32 v219, v219, v177
	ds_bpermute_b32 v174, v193, v216
	ds_bpermute_b32 v175, v193, v217
	ds_bpermute_b32 v176, v193, v218
	ds_bpermute_b32 v177, v193, v219
	s_waitcnt lgkmcnt(0)
	v_max_f32_e32 v216, v216, v174
	v_max_f32_e32 v217, v217, v175
	v_max_f32_e32 v218, v218, v176
	v_max_f32_e32 v219, v219, v177
	ds_bpermute_b32 v174, v194, v216
	ds_bpermute_b32 v175, v194, v217
	ds_bpermute_b32 v176, v194, v218
	ds_bpermute_b32 v177, v194, v219
	s_waitcnt lgkmcnt(0)
	v_max_f32_e32 v216, v216, v174
	v_max_f32_e32 v217, v217, v175
	v_max_f32_e32 v218, v218, v176
	v_max_f32_e32 v219, v219, v177
	ds_bpermute_b32 v174, v195, v216
	ds_bpermute_b32 v175, v195, v217
	ds_bpermute_b32 v176, v195, v218
	ds_bpermute_b32 v177, v195, v219
	s_waitcnt lgkmcnt(0)
	v_max_f32_e32 v216, v216, v174
	v_max_f32_e32 v217, v217, v175
	v_max_f32_e32 v218, v218, v176
	v_max_f32_e32 v219, v219, v177
	s_mov_b64 s[70:71], exec
	s_mov_b64 exec, 15
	ds_write_b128 v172, v[216:219]
	s_mov_b64 exec, s[70:71]
	s_waitcnt lgkmcnt(0)
	s_barrier
	ds_read_b128 v[140:143], v173 offset:0
	ds_read_b128 v[144:147], v173 offset:64
	ds_read_b128 v[148:151], v173 offset:128
	ds_read_b128 v[152:155], v173 offset:192
	ds_read_b128 v[156:159], v173 offset:256
	ds_read_b128 v[160:163], v173 offset:320
	ds_read_b128 v[164:167], v173 offset:384
	ds_read_b128 v[232:235], v173 offset:448
	s_waitcnt lgkmcnt(0)
	v_max3_f32 v220, v140, v144, v148
	v_max3_f32 v220, v220, v152, v156
	v_max3_f32 v220, v220, v160, v164
	v_max_f32_e32 v220, v220, v232
	v_max3_f32 v221, v141, v145, v149
	v_max3_f32 v221, v221, v153, v157
	v_max3_f32 v221, v221, v161, v165
	v_max_f32_e32 v221, v221, v233
	v_max3_f32 v222, v142, v146, v150
	v_max3_f32 v222, v222, v154, v158
	v_max3_f32 v222, v222, v162, v166
	v_max_f32_e32 v222, v222, v234
	v_max3_f32 v223, v143, v147, v151
	v_max3_f32 v223, v223, v155, v159
	v_max3_f32 v223, v223, v163, v167
	v_max_f32_e32 v223, v223, v235
	s_cmp_lg_u32 s1, 0
	s_cbranch_scc1 .Lc16_mixer_nocm
	s_lshl_b32 s3, s2, 2
	s_add_u32 s56, s52, s3
	s_addc_u32 s57, s53, 0
	s_mov_b64 s[70:71], exec
	s_mov_b64 exec, 15
	global_store_dwordx4 v230, v[220:223], s[56:57]
	s_mov_b64 exec, s[70:71]

.Lc16_mixer_done:
	v_ashrrev_i32_e32 v1, 4, v134
	v_lshlrev_b32_e32 v136, 2, v1
	v_readlane_b32 s2, v254, 17
	v_lshlrev_b32_e32 v2, 4, v134
	v_lshlrev_b32_e32 v135, 1, v1
	v_add_u32_e32 v1, s2, v136
	v_and_b32_e32 v114, 0x70, v2
	s_movk_i32 s1, 0x50
	v_ashrrev_i32_e32 v146, 3, v134
	s_movk_i32 s0, 0x70
	v_xad_u32 v143, v114, s1, v1
	s_movk_i32 s1, 0x60
	v_bitop3_b32 v2, v146, 28, v4 bitop3:0x48
	v_add_u32_e32 v148, 8, v146
	v_add_u32_e32 v137, v1, v114
	v_xad_u32 v139, v114, 16, v1
	v_xad_u32 v140, v114, 32, v1
	v_xad_u32 v141, v114, 48, v1
	v_xad_u32 v142, v114, 64, v1
	v_xad_u32 v144, v114, s1, v1
	v_xad_u32 v145, v114, s0, v1
	v_lshlrev_b32_e32 v1, 7, v146
	v_lshlrev_b32_e32 v2, 2, v2
	v_bitop3_b32 v3, v148, 28, v4 bitop3:0x48
	v_add3_u32 v147, s2, v1, v2
	v_lshlrev_b32_e32 v1, 7, v148
	v_lshlrev_b32_e32 v3, 2, v3
	v_add_u32_e32 v150, 16, v146
	v_add3_u32 v149, s2, v1, v3
	v_bitop3_b32 v3, v150, 28, v4 bitop3:0x48
	v_lshlrev_b32_e32 v1, 7, v150
	v_lshlrev_b32_e32 v3, 2, v3
	v_add_u32_e32 v152, 24, v146
	v_add3_u32 v151, s2, v1, v3
	v_bitop3_b32 v3, v152, 28, v4 bitop3:0x48
	v_lshlrev_b32_e32 v1, 7, v152
	v_lshlrev_b32_e32 v3, 2, v3
	v_add_u32_e32 v154, 32, v146
	v_add3_u32 v153, s2, v1, v3
	v_lshlrev_b32_e32 v1, 7, v154
	v_add_u32_e32 v156, 40, v146
	v_add3_u32 v155, s2, v1, v2
	v_bitop3_b32 v2, v156, 28, v4 bitop3:0x48
	v_lshlrev_b32_e32 v1, 7, v156
	v_lshlrev_b32_e32 v2, 2, v2
	v_add_u32_e32 v158, 48, v146
	v_add3_u32 v157, s2, v1, v2
	v_bitop3_b32 v2, v158, 28, v4 bitop3:0x48
	v_lshlrev_b32_e32 v1, 7, v158
	v_lshlrev_b32_e32 v2, 2, v2
	v_add_u32_e32 v160, 56, v146
	v_readlane_b32 s0, v254, 18
	v_mov_b32_e32 v115, 0
	v_add3_u32 v159, s2, v1, v2
	v_bitop3_b32 v2, v160, 28, v4 bitop3:0x48
	v_readlane_b32 s1, v254, 19
	v_and_b32_e32 v0, 60, v4
	v_lshlrev_b32_e32 v1, 7, v160
	v_lshlrev_b32_e32 v2, 2, v2
	v_lshl_add_u64 v[122:123], s[0:1], 0, v[114:115]
	v_readlane_b32 s0, v254, 13
	v_add3_u32 v161, s2, v1, v2
	v_lshlrev_b32_e32 v2, 2, v0
	v_mov_b32_e32 v3, v115
	v_readlane_b32 s1, v254, 14
	v_readlane_b32 s4, v254, 15
	v_readlane_b32 s3, v254, 16
	v_lshl_add_u64 v[124:125], s[0:1], 0, v[2:3]
	v_readlane_b32 s0, v254, 20
	s_bfe_u32 s0, s0, 0x20006
	s_lshl_b32 s1, s0, 6
	s_lshl_b32 s0, s0, 7
	s_or_b32 s0, s0, s1
	s_or_b32 s15, s0, 0x80
	s_lshl_b32 s0, s4, 7
	s_lshl_b32 s2, s3, 4
	s_add_i32 s17, s0, s2
	s_lshl_b32 s0, s3, 6
	s_add_i32 s23, s21, s0
	s_lshl_b32 s0, s4, 10
	s_lshl_b32 s2, s3, 7
	s_add_i32 s29, s0, s2
	s_lshl_b32 s0, s4, 6
	s_lshl_b32 s2, s3, 3
	s_add_i32 s31, s0, s2
	s_lshl_b32 s0, s14, 6
	v_lshlrev_b32_e32 v138, 7, v0
	v_lshl_add_u64 v[116:117], s[92:93], 0, v[114:115]
	v_lshl_add_u64 v[118:119], s[24:25], 0, v[114:115]
	v_lshl_add_u64 v[120:121], s[64:65], 0, v[2:3]
	v_lshl_add_u64 v[126:127], s[68:69], 0, v[114:115]
	v_lshl_add_u64 v[128:129], s[76:77], 0, v[114:115]
	v_lshl_add_u64 v[130:131], s[40:41], 0, v[2:3]
	v_lshl_add_u64 v[132:133], s[8:9], 0, v[114:115]
	s_lshl_b32 s22, s33, 7
	s_lshl_b32 s30, s33, 10
	s_lshl_b32 s70, s33, 6
	s_add_i32 s71, s14, 0xc400
	s_add_i32 s72, s0, 0xfff50000
	v_add_u32_e32 v162, 0xfff50020, v146
	v_add_u32_e32 v163, 0xfffb0020, v146
	s_add_i32 s73, s14, 0xec00
	v_add_u32_e32 v164, s23, v146
	s_lshl_b32 s18, s1, 2
	s_movk_i32 s20, 0x2000
	s_movk_i32 s36, 0x4000
	s_movk_i32 s37, 0x6000
	s_mov_b32 s79, 0x8000
	s_mov_b32 s80, 0xa000
	s_mov_b32 s38, 0xc000
	s_mov_b32 s39, 0xe000
	s_mov_b32 s85, 0x10000
	s_mov_b32 s86, 0x14000
	s_mov_b32 s87, 0x18000
	s_mov_b32 s88, 0x198000
	v_lshlrev_b32_e32 v114, 2, v0
	s_mov_b32 s89, 0x42fe0000
	s_mov_b32 s90, 0x40c0c00
	s_mov_b32 s91, 0x190000
	s_mov_b32 s94, 0x280000
	s_mov_b32 s95, 0xa0000
	s_mov_b32 s74, 0xaa000
	s_mov_b32 s78, 0x140000
	s_mov_b32 s84, 0x14a000
	s_mov_b32 s16, 0x1e0000
	s_mov_b32 s75, 0x1ea000
	s_mov_b32 s81, 0
	s_mov_b32 s4, s14
	s_mov_b32 s11, 0
	s_branch .LBB0_91

.LBB0_104:
	s_andn2_b64 vcc, exec, s[0:1]
	s_branch .LBB0_106
	s_and_b32 s0, 0xffff, s71
	s_mul_hi_u32 s0, s0, 0xbe82fb
	s_mul_i32 s1, s0, 0xfffffea8
	s_add_i32 s2, s4, 0xffffc400
	s_mulk_i32 s0, 0x5600
	s_mul_i32 s3, s2, 0xbe83
	s_add_i32 s2, s2, s1
	s_add_i32 s1, s23, s81
	s_sub_i32 s0, s1, s0
	s_add_i32 s0, s0, 0xfff10000
	s_cmpk_lt_i32 s2, 0xac
	s_cselect_b32 s1, 0, 0xffffd500
	s_cselect_b32 s2, 0, 0x80
	s_add_i32 s1, s0, s1
	s_lshl_b32 s1, s1, 1
	s_and_b32 s5, s0, 64
	s_and_b32 s1, s1, 0xffffff00
	s_or_b32 s2, s5, s2
	s_or_b32 s2, s2, s1
	s_lshr_b32 s1, s3, 24
	v_readlane_b32 s48, v255, 7
	s_lshl_b32 s10, s1, 7
	v_readlane_b32 s60, v255, 19
	v_readlane_b32 s61, v255, 20
	v_add_u32_e32 v2, s10, v136
	s_mov_b32 s1, 0x15800
	v_mov_b64_e32 v[0:1], s[60:61]
	v_mad_i64_i32 v[0:1], s[6:7], v2, s1, v[0:1]
	s_ashr_i32 s1, s0, 31
	s_lshl_b64 s[0:1], s[0:1], 2
	v_lshl_add_u64 v[0:1], v[0:1], 0, s[0:1]
	v_lshl_add_u64 v[24:25], v[0:1], 0, v[114:115]
	s_mov_b32 s3, 0x15000
	v_add_co_u32_e32 v0, vcc, s3, v24
	s_mov_b32 s3, 0x2b000
	s_nop 0
	v_addc_co_u32_e32 v1, vcc, 0, v25, vcc
	global_load_dwordx4 v[74:77], v[24:25], off nt
	global_load_dwordx4 v[64:67], v[0:1], off offset:2048 nt
	v_add_co_u32_e32 v0, vcc, s3, v24
	s_mov_b32 s3, 0x40000
	s_nop 0
	v_addc_co_u32_e32 v1, vcc, 0, v25, vcc
	v_add_co_u32_e32 v2, vcc, s3, v24
	s_mov_b32 s3, 0x158000
	s_nop 0
	v_addc_co_u32_e32 v3, vcc, 0, v25, vcc
	global_load_dwordx4 v[70:73], v[0:1], off nt
	global_load_dwordx4 v[110:113], v[2:3], off offset:2048 nt
	v_add_co_u32_e32 v0, vcc, s3, v24
	s_mov_b32 s3, 0x16d000
	s_nop 0
	v_addc_co_u32_e32 v1, vcc, 0, v25, vcc
	v_add_co_u32_e32 v2, vcc, s3, v24
	s_mov_b32 s3, 0x183000
	s_nop 0
	v_addc_co_u32_e32 v3, vcc, 0, v25, vcc
	global_load_dwordx4 v[80:83], v[0:1], off nt
	global_load_dwordx4 v[84:87], v[2:3], off offset:2048 nt
	v_add_co_u32_e32 v0, vcc, s3, v24
	s_mov_b32 s3, 0x2b0000
	s_nop 0
	v_addc_co_u32_e32 v1, vcc, 0, v25, vcc
	v_add_co_u32_e32 v2, vcc, s88, v24
	v_readlane_b32 s49, v255, 8
	s_nop 0
	v_addc_co_u32_e32 v3, vcc, 0, v25, vcc
	global_load_dwordx4 v[96:99], v[0:1], off nt
	global_load_dwordx4 v[100:103], v[2:3], off offset:2048 nt
	v_add_co_u32_e32 v0, vcc, s3, v24
	s_mov_b32 s3, 0x2c5000
	s_nop 0
	v_addc_co_u32_e32 v1, vcc, 0, v25, vcc
	v_add_co_u32_e32 v2, vcc, s3, v24
	s_mov_b32 s3, 0x2db000
	s_nop 0
	v_addc_co_u32_e32 v3, vcc, 0, v25, vcc
	global_load_dwordx4 v[48:51], v[0:1], off nt
	global_load_dwordx4 v[52:55], v[2:3], off offset:2048 nt
	v_add_co_u32_e32 v0, vcc, s3, v24
	s_mov_b32 s3, 0x2f0000
	s_nop 0
	v_addc_co_u32_e32 v1, vcc, 0, v25, vcc
	v_add_co_u32_e32 v2, vcc, s3, v24
	s_mov_b32 s3, 0x408000
	s_nop 0
	v_addc_co_u32_e32 v3, vcc, 0, v25, vcc
	global_load_dwordx4 v[56:59], v[0:1], off nt
	global_load_dwordx4 v[60:63], v[2:3], off offset:2048 nt
	v_add_co_u32_e32 v0, vcc, s3, v24
	s_mov_b32 s3, 0x41d000
	s_nop 0
	v_addc_co_u32_e32 v1, vcc, 0, v25, vcc
	v_add_co_u32_e32 v2, vcc, s3, v24
	v_readlane_b32 s50, v255, 9
	s_nop 0
	v_addc_co_u32_e32 v3, vcc, 0, v25, vcc
	global_load_dwordx4 v[16:19], v[0:1], off nt
	global_load_dwordx4 v[20:23], v[2:3], off offset:2048 nt
	v_lshl_add_u64 v[0:1], v[120:121], 0, s[0:1]
	global_load_dwordx4 v[104:107], v[0:1], off
	s_mov_b32 s0, 0x433000
	v_add_co_u32_e32 v0, vcc, s0, v24
	s_mov_b32 s0, 0x448000
	s_nop 0
	v_addc_co_u32_e32 v1, vcc, 0, v25, vcc
	v_add_co_u32_e32 v2, vcc, s0, v24
	s_mov_b32 s0, 0x560000
	s_nop 0
	v_addc_co_u32_e32 v3, vcc, 0, v25, vcc
	global_load_dwordx4 v[92:95], v[0:1], off nt
	global_load_dwordx4 v[88:91], v[2:3], off offset:2048 nt
	v_add_co_u32_e32 v0, vcc, s0, v24
	s_mov_b32 s0, 0x575000
	s_nop 0
	v_addc_co_u32_e32 v1, vcc, 0, v25, vcc
	v_add_co_u32_e32 v2, vcc, s0, v24
	s_mov_b32 s0, 0x58b000
	s_nop 0
	v_addc_co_u32_e32 v3, vcc, 0, v25, vcc
	global_load_dwordx4 v[36:39], v[0:1], off nt
	global_load_dwordx4 v[32:35], v[2:3], off offset:2048 nt
	v_add_co_u32_e32 v0, vcc, s0, v24
	s_mov_b32 s0, 0x5a0000
	s_nop 0
	v_addc_co_u32_e32 v1, vcc, 0, v25, vcc
	v_add_co_u32_e32 v2, vcc, s0, v24
	s_mov_b32 s0, 0x6b8000
	s_nop 0
	v_addc_co_u32_e32 v3, vcc, 0, v25, vcc
	global_load_dwordx4 v[44:47], v[0:1], off nt
	global_load_dwordx4 v[40:43], v[2:3], off offset:2048 nt
	v_add_co_u32_e32 v0, vcc, s0, v24
	s_mov_b32 s0, 0x6cd000
	s_nop 0
	v_addc_co_u32_e32 v1, vcc, 0, v25, vcc
	v_add_co_u32_e32 v2, vcc, s0, v24
	s_mov_b32 s0, 0x6e3000
	s_nop 0
	v_addc_co_u32_e32 v3, vcc, 0, v25, vcc
	v_add_co_u32_e32 v8, vcc, s0, v24
	s_mov_b32 s0, 0x6f8000
	s_nop 0
	v_addc_co_u32_e32 v9, vcc, 0, v25, vcc
	v_add_co_u32_e32 v10, vcc, s0, v24
	s_mov_b32 s0, 0x810000
	s_nop 0
	v_addc_co_u32_e32 v11, vcc, 0, v25, vcc
	v_add_co_u32_e32 v26, vcc, s0, v24
	s_mov_b32 s0, 0x825000
	s_nop 0
	v_addc_co_u32_e32 v27, vcc, 0, v25, vcc
	v_add_co_u32_e32 v68, vcc, s0, v24
	s_mov_b32 s0, 0x83b000
	s_nop 0
	v_addc_co_u32_e32 v69, vcc, 0, v25, vcc
	v_add_co_u32_e32 v78, vcc, s0, v24
	s_mov_b32 s0, 0x850000
	s_nop 0
	v_addc_co_u32_e32 v79, vcc, 0, v25, vcc
	v_add_co_u32_e32 v168, vcc, s0, v24
	s_mov_b32 s0, 0x968000
	s_nop 0
	v_addc_co_u32_e32 v169, vcc, 0, v25, vcc
	v_add_co_u32_e32 v170, vcc, s0, v24
	s_mov_b32 s0, 0x97d000
	s_nop 0
	v_addc_co_u32_e32 v171, vcc, 0, v25, vcc
	v_add_co_u32_e32 v172, vcc, s0, v24
	s_mov_b32 s0, 0x993000
	s_nop 0
	v_addc_co_u32_e32 v173, vcc, 0, v25, vcc
	v_add_co_u32_e32 v174, vcc, s0, v24
	s_waitcnt vmcnt(6)
	v_div_scale_f32 v28, s[0:1], v104, v104, s89
	v_rcp_f32_e32 v29, v28
	v_addc_co_u32_e32 v175, vcc, 0, v25, vcc
	s_mov_b32 s0, 0x9a8000
	v_add_co_u32_e32 v176, vcc, s0, v24
	v_fma_f32 v24, -v28, v29, 1.0
	s_nop 0
	v_addc_co_u32_e32 v177, vcc, 0, v25, vcc
	v_fmac_f32_e32 v29, v24, v29
	v_div_scale_f32 v24, vcc, s89, v104, s89
	v_mul_f32_e32 v25, v24, v29
	v_fma_f32 v30, -v28, v25, v24
	v_fmac_f32_e32 v25, v30, v29
	v_div_scale_f32 v30, s[0:1], v105, v105, s89
	v_rcp_f32_e32 v31, v30
	v_fma_f32 v24, -v28, v25, v24
	v_div_fmas_f32 v108, v24, v29, v25
	global_load_dwordx4 v[4:7], v[0:1], off nt
	s_nop 0
	global_load_dwordx4 v[0:3], v[2:3], off offset:2048 nt
	v_fma_f32 v24, -v30, v31, 1.0
	v_fmac_f32_e32 v31, v24, v31
	v_div_scale_f32 v24, vcc, s89, v105, s89
	v_mul_f32_e32 v25, v24, v31
	v_fma_f32 v28, -v30, v25, v24
	v_fmac_f32_e32 v25, v28, v31
	v_div_scale_f32 v28, s[0:1], v106, v106, s89
	v_rcp_f32_e32 v29, v28
	v_fma_f32 v24, -v30, v25, v24
	v_div_fmas_f32 v109, v24, v31, v25
	global_load_dwordx4 v[12:15], v[8:9], off nt
	s_nop 0
	global_load_dwordx4 v[8:11], v[10:11], off offset:2048 nt
	v_fma_f32 v24, -v28, v29, 1.0
	v_fmac_f32_e32 v29, v24, v29
	v_div_scale_f32 v24, vcc, s89, v106, s89
	v_mul_f32_e32 v25, v24, v29
	v_fma_f32 v30, -v28, v25, v24
	v_fmac_f32_e32 v25, v30, v29
	v_div_scale_f32 v30, s[0:1], v107, v107, s89
	v_rcp_f32_e32 v31, v30
	v_fma_f32 v24, -v28, v25, v24
	v_div_fmas_f32 v167, v24, v29, v25
	v_readlane_b32 s51, v255, 10
	v_fma_f32 v24, -v30, v31, 1.0
	v_fmac_f32_e32 v31, v24, v31
	v_div_scale_f32 v24, vcc, s89, v107, s89
	v_mul_f32_e32 v25, v24, v31
	v_fma_f32 v28, -v30, v25, v24
	v_fmac_f32_e32 v25, v28, v31
	v_fma_f32 v24, -v30, v25, v24
	v_div_fmas_f32 v178, v24, v31, v25
	global_load_dwordx4 v[28:31], v[26:27], off nt
	s_nop 0
	global_load_dwordx4 v[24:27], v[68:69], off offset:2048 nt
	v_div_fixup_f32 v68, v108, v104, s89
	v_cmp_lt_f32_e32 vcc, 0, v104
	v_div_fixup_f32 v69, v178, v107, s89
	v_add_u32_e32 v178, v137, v138
	v_cndmask_b32_e32 v166, 0, v68, vcc
	v_mul_f32_e32 v64, v64, v166
	v_mul_f32_e32 v74, v74, v166
	v_rndne_f32_e32 v64, v64
	v_mul_f32_e32 v70, v70, v166
	v_mul_f32_e32 v104, v110, v166
	v_rndne_f32_e32 v74, v74
	v_cvt_i32_f32_e32 v64, v64
	v_rndne_f32_e32 v70, v70
	v_rndne_f32_e32 v104, v104
	v_cvt_i32_f32_e32 v74, v74
	v_cvt_i32_f32_sdwa v70, v70 dst_sel:WORD_1 dst_unused:UNUSED_PAD src0_sel:DWORD
	v_cvt_i32_f32_e32 v104, v104
	v_div_fixup_f32 v68, v109, v105, s89
	v_cmp_lt_f32_e32 vcc, 0, v105
	v_lshlrev_b32_e32 v64, 8, v64
	v_and_b32_e32 v64, 0xff00, v64
	v_cndmask_b32_e32 v165, 0, v68, vcc
	v_and_b32_e32 v70, 0xff0000, v70
	v_perm_b32 v74, v104, v74, s90
	v_mul_f32_e32 v65, v65, v165
	v_or3_b32 v64, v74, v64, v70
	v_mul_f32_e32 v70, v75, v165
	v_mul_f32_e32 v74, v111, v165
	v_rndne_f32_e32 v65, v65
	v_mul_f32_e32 v71, v71, v165
	v_mul_f32_e32 v84, v84, v166
	v_mul_f32_e32 v52, v52, v166
	v_rndne_f32_e32 v70, v70
	v_rndne_f32_e32 v74, v74
	v_cvt_i32_f32_e32 v65, v65
	v_rndne_f32_e32 v71, v71
	v_mul_f32_e32 v80, v80, v166
	v_rndne_f32_e32 v84, v84
	v_mul_f32_e32 v96, v96, v166
	v_mul_f32_e32 v100, v100, v166
	v_mul_f32_e32 v48, v48, v166
	v_rndne_f32_e32 v52, v52
	v_mul_f32_e32 v56, v56, v166
	v_mul_f32_e32 v60, v60, v166
	v_cvt_i32_f32_e32 v70, v70
	v_cvt_i32_f32_e32 v74, v74
	v_cvt_i32_f32_sdwa v71, v71 dst_sel:WORD_1 dst_unused:UNUSED_PAD src0_sel:DWORD
	v_rndne_f32_e32 v80, v80
	v_cvt_i32_f32_e32 v84, v84
	v_rndne_f32_e32 v96, v96
	v_rndne_f32_e32 v100, v100
	v_rndne_f32_e32 v48, v48
	v_cvt_i32_f32_e32 v52, v52
	v_rndne_f32_e32 v56, v56
	v_rndne_f32_e32 v60, v60
	v_cvt_i32_f32_e32 v80, v80
	v_cvt_i32_f32_sdwa v96, v96 dst_sel:WORD_1 dst_unused:UNUSED_PAD src0_sel:DWORD
	v_cvt_i32_f32_e32 v100, v100
	v_cvt_i32_f32_e32 v48, v48
	v_cvt_i32_f32_sdwa v56, v56 dst_sel:WORD_1 dst_unused:UNUSED_PAD src0_sel:DWORD
	v_cvt_i32_f32_e32 v60, v60
	v_div_fixup_f32 v68, v167, v106, s89
	v_cmp_lt_f32_e32 vcc, 0, v106
	v_lshlrev_b32_e32 v65, 8, v65
	v_perm_b32 v70, v74, v70, s90
	v_cndmask_b32_e32 v167, 0, v68, vcc
	v_and_b32_e32 v65, 0xff00, v65
	v_and_b32_e32 v68, 0xff0000, v71
	v_lshlrev_b32_e32 v84, 8, v84
	v_lshlrev_b32_e32 v52, 8, v52
	v_or3_b32 v65, v70, v65, v68
	v_and_b32_e32 v84, 0xff00, v84
	v_and_b32_e32 v96, 0xff0000, v96
	v_perm_b32 v80, v100, v80, s90
	v_mul_f32_e32 v85, v85, v165
	v_and_b32_e32 v52, 0xff00, v52
	v_and_b32_e32 v56, 0xff0000, v56
	v_perm_b32 v48, v60, v48, s90
	v_mul_f32_e32 v53, v53, v165
	ds_write2_b32 v178, v64, v65 offset1:32
	v_mul_f32_e32 v65, v66, v167
	v_or3_b32 v80, v80, v84, v96
	v_mul_f32_e32 v81, v81, v165
	v_rndne_f32_e32 v85, v85
	v_mul_f32_e32 v96, v97, v165
	v_mul_f32_e32 v97, v101, v165
	v_or3_b32 v48, v48, v52, v56
	v_mul_f32_e32 v49, v49, v165
	v_rndne_f32_e32 v53, v53
	v_mul_f32_e32 v56, v57, v165
	v_mul_f32_e32 v57, v61, v165
	v_mul_f32_e32 v71, v76, v167
	v_mul_f32_e32 v74, v112, v167
	v_rndne_f32_e32 v65, v65
	v_mul_f32_e32 v66, v72, v167
	v_rndne_f32_e32 v81, v81
	v_cvt_i32_f32_e32 v85, v85
	v_rndne_f32_e32 v96, v96
	v_rndne_f32_e32 v97, v97
	v_rndne_f32_e32 v49, v49
	v_cvt_i32_f32_e32 v53, v53
	v_rndne_f32_e32 v56, v56
	v_rndne_f32_e32 v57, v57
	v_rndne_f32_e32 v71, v71
	v_rndne_f32_e32 v74, v74
	v_cvt_i32_f32_e32 v65, v65
	v_rndne_f32_e32 v66, v66
	v_cvt_i32_f32_e32 v81, v81
	v_cvt_i32_f32_sdwa v96, v96 dst_sel:WORD_1 dst_unused:UNUSED_PAD src0_sel:DWORD
	v_cvt_i32_f32_e32 v97, v97
	v_cvt_i32_f32_e32 v49, v49
	v_cvt_i32_f32_sdwa v56, v56 dst_sel:WORD_1 dst_unused:UNUSED_PAD src0_sel:DWORD
	v_cvt_i32_f32_e32 v57, v57
	v_cvt_i32_f32_e32 v71, v71
	v_cvt_i32_f32_e32 v74, v74
	v_cvt_i32_f32_sdwa v66, v66 dst_sel:WORD_1 dst_unused:UNUSED_PAD src0_sel:DWORD
	v_lshlrev_b32_e32 v85, 8, v85
	v_lshlrev_b32_e32 v53, 8, v53
	v_cmp_lt_f32_e32 vcc, 0, v107
	v_lshlrev_b32_e32 v65, 8, v65
	v_and_b32_e32 v85, 0xff00, v85
	v_and_b32_e32 v96, 0xff0000, v96
	v_perm_b32 v81, v97, v81, s90
	v_and_b32_e32 v53, 0xff00, v53
	v_and_b32_e32 v56, 0xff0000, v56
	v_perm_b32 v49, v57, v49, s90
	v_perm_b32 v64, v74, v71, s90
	v_cndmask_b32_e32 v112, 0, v69, vcc
	v_and_b32_e32 v65, 0xff00, v65
	v_and_b32_e32 v66, 0xff0000, v66
	v_add_u32_e32 v84, v139, v138
	v_or3_b32 v81, v81, v85, v96
	v_add_u32_e32 v52, v140, v138
	v_or3_b32 v49, v49, v53, v56
	v_mul_f32_e32 v179, v77, v112
	global_load_dwordx4 v[108:111], v[78:79], off nt
	global_load_dwordx4 v[104:107], v[168:169], off offset:2048 nt
	v_or3_b32 v168, v64, v65, v66
	v_mul_f32_e32 v169, v67, v112
	global_load_dwordx4 v[76:79], v[170:171], off nt
	global_load_dwordx4 v[68:71], v[172:173], off offset:2048 nt
	v_mul_f32_e32 v170, v73, v112
	global_load_dwordx4 v[72:75], v[174:175], off nt
	global_load_dwordx4 v[64:67], v[176:177], off offset:2048 nt
	ds_write2_b32 v84, v80, v81 offset1:32
	v_mul_f32_e32 v81, v86, v167
	ds_write2_b32 v52, v48, v49 offset1:32
	v_mul_f32_e32 v49, v54, v167
	v_mul_f32_e32 v80, v82, v167
	v_rndne_f32_e32 v81, v81
	v_mul_f32_e32 v82, v98, v167
	v_mul_f32_e32 v85, v102, v167
	v_mul_f32_e32 v48, v50, v167
	v_rndne_f32_e32 v49, v49
	v_mul_f32_e32 v50, v58, v167
	v_mul_f32_e32 v53, v62, v167
	v_rndne_f32_e32 v80, v80
	v_cvt_i32_f32_e32 v81, v81
	v_rndne_f32_e32 v82, v82
	v_rndne_f32_e32 v85, v85
	v_rndne_f32_e32 v48, v48
	v_cvt_i32_f32_e32 v49, v49
	v_rndne_f32_e32 v50, v50
	v_rndne_f32_e32 v53, v53
	v_cvt_i32_f32_e32 v80, v80
	v_cvt_i32_f32_sdwa v82, v82 dst_sel:WORD_1 dst_unused:UNUSED_PAD src0_sel:DWORD
	v_cvt_i32_f32_e32 v85, v85
	v_cvt_i32_f32_e32 v48, v48
	v_cvt_i32_f32_sdwa v50, v50 dst_sel:WORD_1 dst_unused:UNUSED_PAD src0_sel:DWORD
	v_cvt_i32_f32_e32 v53, v53
	v_lshlrev_b32_e32 v81, 8, v81
	v_lshlrev_b32_e32 v49, 8, v49
	v_and_b32_e32 v81, 0xff00, v81
	v_and_b32_e32 v82, 0xff0000, v82
	v_perm_b32 v80, v85, v80, s90
	v_and_b32_e32 v49, 0xff00, v49
	v_and_b32_e32 v50, 0xff0000, v50
	v_perm_b32 v48, v53, v48, s90
	v_or3_b32 v80, v80, v81, v82
	v_mul_f32_e32 v82, v87, v112
	v_or3_b32 v48, v48, v49, v50
	v_mul_f32_e32 v50, v55, v112
	v_rndne_f32_e32 v169, v169
	v_mul_f32_e32 v113, v113, v112
	v_mul_f32_e32 v81, v83, v112
	v_rndne_f32_e32 v82, v82
	v_mul_f32_e32 v83, v99, v112
	v_mul_f32_e32 v85, v103, v112
	v_mul_f32_e32 v49, v51, v112
	v_rndne_f32_e32 v50, v50
	v_mul_f32_e32 v51, v59, v112
	v_mul_f32_e32 v53, v63, v112
	v_rndne_f32_e32 v171, v179
	v_cvt_i32_f32_e32 v169, v169
	v_rndne_f32_e32 v170, v170
	v_rndne_f32_e32 v113, v113
	v_rndne_f32_e32 v81, v81
	v_cvt_i32_f32_e32 v82, v82
	v_rndne_f32_e32 v83, v83
	v_rndne_f32_e32 v85, v85
	v_rndne_f32_e32 v49, v49
	v_cvt_i32_f32_e32 v50, v50
	v_rndne_f32_e32 v51, v51
	v_rndne_f32_e32 v53, v53
	v_cvt_i32_f32_e32 v171, v171
	v_cvt_i32_f32_sdwa v170, v170 dst_sel:WORD_1 dst_unused:UNUSED_PAD src0_sel:DWORD
	v_cvt_i32_f32_e32 v113, v113
	v_cvt_i32_f32_e32 v81, v81
	v_cvt_i32_f32_sdwa v83, v83 dst_sel:WORD_1 dst_unused:UNUSED_PAD src0_sel:DWORD
	v_cvt_i32_f32_e32 v85, v85
	v_cvt_i32_f32_e32 v49, v49
	v_cvt_i32_f32_sdwa v51, v51 dst_sel:WORD_1 dst_unused:UNUSED_PAD src0_sel:DWORD
	v_cvt_i32_f32_e32 v53, v53
	v_lshlrev_b32_e32 v169, 8, v169
	v_lshlrev_b32_e32 v82, 8, v82
	v_lshlrev_b32_e32 v50, 8, v50
	v_and_b32_e32 v169, 0xff00, v169
	v_and_b32_e32 v170, 0xff0000, v170
	v_perm_b32 v113, v113, v171, s90
	v_and_b32_e32 v82, 0xff00, v82
	v_and_b32_e32 v83, 0xff0000, v83
	v_perm_b32 v81, v85, v81, s90
	v_and_b32_e32 v50, 0xff00, v50
	v_and_b32_e32 v51, 0xff0000, v51
	v_perm_b32 v49, v53, v49, s90
	v_or3_b32 v113, v113, v169, v170
	v_or3_b32 v81, v81, v82, v83
	v_or3_b32 v49, v49, v50, v51
	v_mul_f32_e32 v20, v20, v166
	ds_write2_b32 v178, v168, v113 offset0:64 offset1:96
	ds_write2_b32 v84, v80, v81 offset0:64 offset1:96
	ds_write2_b32 v52, v48, v49 offset0:64 offset1:96
	v_mul_f32_e32 v16, v16, v166
	v_rndne_f32_e32 v20, v20
	s_waitcnt vmcnt(17)
	v_mul_f32_e32 v48, v92, v166
	s_waitcnt vmcnt(16)
	v_mul_f32_e32 v49, v88, v166
	v_rndne_f32_e32 v16, v16
	v_cvt_i32_f32_e32 v20, v20
	v_rndne_f32_e32 v48, v48
	v_rndne_f32_e32 v49, v49
	v_cvt_i32_f32_e32 v16, v16
	v_cvt_i32_f32_sdwa v48, v48 dst_sel:WORD_1 dst_unused:UNUSED_PAD src0_sel:DWORD
	v_cvt_i32_f32_e32 v49, v49
	v_lshlrev_b32_e32 v20, 8, v20
	v_and_b32_e32 v20, 0xff00, v20
	v_and_b32_e32 v48, 0xff0000, v48
	v_perm_b32 v16, v49, v16, s90
	v_mul_f32_e32 v21, v21, v165
	v_or3_b32 v16, v16, v20, v48
	v_mul_f32_e32 v17, v17, v165
	v_rndne_f32_e32 v21, v21
	v_mul_f32_e32 v48, v93, v165
	v_mul_f32_e32 v49, v89, v165
	v_rndne_f32_e32 v17, v17
	v_cvt_i32_f32_e32 v21, v21
	v_rndne_f32_e32 v48, v48
	v_rndne_f32_e32 v49, v49
	v_cvt_i32_f32_e32 v17, v17
	v_cvt_i32_f32_sdwa v48, v48 dst_sel:WORD_1 dst_unused:UNUSED_PAD src0_sel:DWORD
	v_cvt_i32_f32_e32 v49, v49
	v_lshlrev_b32_e32 v21, 8, v21
	v_and_b32_e32 v21, 0xff00, v21
	v_and_b32_e32 v48, 0xff0000, v48
	v_perm_b32 v17, v49, v17, s90
	v_add_u32_e32 v20, v141, v138
	v_or3_b32 v17, v17, v21, v48
	ds_write2_b32 v20, v16, v17 offset1:32
	v_mul_f32_e32 v17, v22, v167
	v_mul_f32_e32 v16, v18, v167
	v_rndne_f32_e32 v17, v17
	v_mul_f32_e32 v18, v94, v167
	v_mul_f32_e32 v21, v90, v167
	v_rndne_f32_e32 v16, v16
	v_cvt_i32_f32_e32 v17, v17
	v_rndne_f32_e32 v18, v18
	v_rndne_f32_e32 v21, v21
	v_cvt_i32_f32_e32 v16, v16
	v_cvt_i32_f32_sdwa v18, v18 dst_sel:WORD_1 dst_unused:UNUSED_PAD src0_sel:DWORD
	v_cvt_i32_f32_e32 v21, v21
	v_lshlrev_b32_e32 v17, 8, v17
	v_and_b32_e32 v17, 0xff00, v17
	v_and_b32_e32 v18, 0xff0000, v18
	v_perm_b32 v16, v21, v16, s90
	v_or3_b32 v16, v16, v17, v18
	v_mul_f32_e32 v18, v23, v112
	v_mul_f32_e32 v17, v19, v112
	v_rndne_f32_e32 v18, v18
	v_mul_f32_e32 v19, v95, v112
	v_mul_f32_e32 v21, v91, v112
	v_rndne_f32_e32 v17, v17
	v_cvt_i32_f32_e32 v18, v18
	v_rndne_f32_e32 v19, v19
	v_rndne_f32_e32 v21, v21
	v_cvt_i32_f32_e32 v17, v17
	v_cvt_i32_f32_sdwa v19, v19 dst_sel:WORD_1 dst_unused:UNUSED_PAD src0_sel:DWORD
	v_cvt_i32_f32_e32 v21, v21
	v_lshlrev_b32_e32 v18, 8, v18
	v_and_b32_e32 v18, 0xff00, v18
	v_and_b32_e32 v19, 0xff0000, v19
	v_perm_b32 v17, v21, v17, s90
	v_or3_b32 v17, v17, v18, v19
	ds_write2_b32 v20, v16, v17 offset0:64 offset1:96
	s_waitcnt vmcnt(14)
	v_mul_f32_e32 v17, v32, v166
	v_mul_f32_e32 v16, v36, v166
	v_rndne_f32_e32 v17, v17
	s_waitcnt vmcnt(13)
	v_mul_f32_e32 v18, v44, v166
	s_waitcnt vmcnt(12)
	v_mul_f32_e32 v19, v40, v166
	v_rndne_f32_e32 v16, v16
	v_cvt_i32_f32_e32 v17, v17
	v_rndne_f32_e32 v18, v18
	v_rndne_f32_e32 v19, v19
	s_waitcnt vmcnt(11)
	v_mul_f32_e32 v4, v4, v166
	s_waitcnt vmcnt(8)
	v_mul_f32_e32 v8, v8, v166
	v_cvt_i32_f32_e32 v16, v16
	v_cvt_i32_f32_sdwa v18, v18 dst_sel:WORD_1 dst_unused:UNUSED_PAD src0_sel:DWORD
	v_cvt_i32_f32_e32 v19, v19
	v_rndne_f32_e32 v4, v4
	v_rndne_f32_e32 v8, v8
	v_cvt_i32_f32_e32 v4, v4
	v_cvt_i32_f32_e32 v8, v8
	v_lshlrev_b32_e32 v17, 8, v17
	v_and_b32_e32 v17, 0xff00, v17
	v_and_b32_e32 v18, 0xff0000, v18
	v_perm_b32 v16, v19, v16, s90
	v_mul_f32_e32 v19, v33, v165
	v_mul_f32_e32 v0, v0, v166
	v_mul_f32_e32 v1, v1, v165
	v_or3_b32 v16, v16, v17, v18
	v_mul_f32_e32 v18, v37, v165
	v_rndne_f32_e32 v19, v19
	v_mul_f32_e32 v20, v45, v165
	v_mul_f32_e32 v21, v41, v165
	v_rndne_f32_e32 v0, v0
	v_mul_f32_e32 v12, v12, v166
	v_perm_b32 v4, v8, v4, s90
	v_mul_f32_e32 v5, v5, v165
	v_rndne_f32_e32 v1, v1
	v_mul_f32_e32 v8, v13, v165
	v_mul_f32_e32 v9, v9, v165
	v_rndne_f32_e32 v18, v18
	v_cvt_i32_f32_e32 v19, v19
	v_rndne_f32_e32 v20, v20
	v_rndne_f32_e32 v21, v21
	v_cvt_i32_f32_e32 v0, v0
	v_rndne_f32_e32 v12, v12
	v_rndne_f32_e32 v5, v5
	v_cvt_i32_f32_e32 v1, v1
	v_rndne_f32_e32 v8, v8
	v_rndne_f32_e32 v9, v9
	v_cvt_i32_f32_e32 v18, v18
	v_cvt_i32_f32_sdwa v20, v20 dst_sel:WORD_1 dst_unused:UNUSED_PAD src0_sel:DWORD
	v_cvt_i32_f32_e32 v21, v21
	v_cvt_i32_f32_sdwa v12, v12 dst_sel:WORD_1 dst_unused:UNUSED_PAD src0_sel:DWORD
	v_cvt_i32_f32_e32 v5, v5
	v_cvt_i32_f32_sdwa v8, v8 dst_sel:WORD_1 dst_unused:UNUSED_PAD src0_sel:DWORD
	v_cvt_i32_f32_e32 v9, v9
	v_lshlrev_b32_e32 v19, 8, v19
	v_lshlrev_b32_e32 v0, 8, v0
	v_lshlrev_b32_e32 v1, 8, v1
	v_and_b32_e32 v19, 0xff00, v19
	v_and_b32_e32 v20, 0xff0000, v20
	v_perm_b32 v18, v21, v18, s90
	v_and_b32_e32 v0, 0xff00, v0
	v_and_b32_e32 v12, 0xff0000, v12
	v_and_b32_e32 v1, 0xff00, v1
	v_and_b32_e32 v8, 0xff0000, v8
	v_perm_b32 v5, v9, v5, s90
	v_add_u32_e32 v17, v142, v138
	v_or3_b32 v18, v18, v19, v20
	v_or3_b32 v0, v4, v0, v12
	v_add_u32_e32 v4, v143, v138
	v_or3_b32 v1, v5, v1, v8
	ds_write2_b32 v17, v16, v18 offset1:32
	v_mul_f32_e32 v18, v34, v167
	ds_write2_b32 v4, v0, v1 offset1:32
	v_mul_f32_e32 v1, v2, v167
	v_mul_f32_e32 v16, v38, v167
	v_rndne_f32_e32 v18, v18
	v_mul_f32_e32 v19, v46, v167
	v_mul_f32_e32 v20, v42, v167
	v_mul_f32_e32 v0, v6, v167
	v_rndne_f32_e32 v1, v1
	v_mul_f32_e32 v2, v14, v167
	v_mul_f32_e32 v5, v10, v167
	v_rndne_f32_e32 v16, v16
	v_cvt_i32_f32_e32 v18, v18
	v_rndne_f32_e32 v19, v19
	v_rndne_f32_e32 v20, v20
	v_rndne_f32_e32 v0, v0
	v_cvt_i32_f32_e32 v1, v1
	v_rndne_f32_e32 v2, v2
	v_rndne_f32_e32 v5, v5
	v_cvt_i32_f32_e32 v16, v16
	v_cvt_i32_f32_sdwa v19, v19 dst_sel:WORD_1 dst_unused:UNUSED_PAD src0_sel:DWORD
	v_cvt_i32_f32_e32 v20, v20
	v_cvt_i32_f32_e32 v0, v0
	v_cvt_i32_f32_sdwa v2, v2 dst_sel:WORD_1 dst_unused:UNUSED_PAD src0_sel:DWORD
	v_cvt_i32_f32_e32 v5, v5
	v_lshlrev_b32_e32 v18, 8, v18
	v_lshlrev_b32_e32 v1, 8, v1
	v_and_b32_e32 v18, 0xff00, v18
	v_and_b32_e32 v19, 0xff0000, v19
	v_perm_b32 v16, v20, v16, s90
	v_and_b32_e32 v1, 0xff00, v1
	v_and_b32_e32 v2, 0xff0000, v2
	v_perm_b32 v0, v5, v0, s90
	v_or3_b32 v16, v16, v18, v19
	v_mul_f32_e32 v19, v35, v112
	v_or3_b32 v0, v0, v1, v2
	v_mul_f32_e32 v2, v3, v112
	v_mul_f32_e32 v18, v39, v112
	v_rndne_f32_e32 v19, v19
	v_mul_f32_e32 v20, v47, v112
	v_mul_f32_e32 v21, v43, v112
	v_mul_f32_e32 v1, v7, v112
	v_rndne_f32_e32 v2, v2
	v_mul_f32_e32 v3, v15, v112
	v_mul_f32_e32 v5, v11, v112
	v_rndne_f32_e32 v18, v18
	v_cvt_i32_f32_e32 v19, v19
	v_rndne_f32_e32 v20, v20
	v_rndne_f32_e32 v21, v21
	v_rndne_f32_e32 v1, v1
	v_cvt_i32_f32_e32 v2, v2
	v_rndne_f32_e32 v3, v3
	v_rndne_f32_e32 v5, v5
	v_cvt_i32_f32_e32 v18, v18
	v_cvt_i32_f32_sdwa v20, v20 dst_sel:WORD_1 dst_unused:UNUSED_PAD src0_sel:DWORD
	v_cvt_i32_f32_e32 v21, v21
	v_cvt_i32_f32_e32 v1, v1
	v_cvt_i32_f32_sdwa v3, v3 dst_sel:WORD_1 dst_unused:UNUSED_PAD src0_sel:DWORD
	v_cvt_i32_f32_e32 v5, v5
	v_lshlrev_b32_e32 v19, 8, v19
	v_lshlrev_b32_e32 v2, 8, v2
	v_and_b32_e32 v19, 0xff00, v19
	v_and_b32_e32 v20, 0xff0000, v20
	v_perm_b32 v18, v21, v18, s90
	v_and_b32_e32 v2, 0xff00, v2
	v_and_b32_e32 v3, 0xff0000, v3
	v_perm_b32 v1, v5, v1, s90
	v_or3_b32 v18, v18, v19, v20
	v_or3_b32 v1, v1, v2, v3
	ds_write2_b32 v17, v16, v18 offset0:64 offset1:96
	ds_write2_b32 v4, v0, v1 offset0:64 offset1:96
	s_waitcnt vmcnt(6)
	v_mul_f32_e32 v1, v24, v166
	v_mul_f32_e32 v0, v28, v166
	v_rndne_f32_e32 v1, v1
	s_waitcnt vmcnt(5)
	v_mul_f32_e32 v2, v108, v166
	s_waitcnt vmcnt(4)
	v_mul_f32_e32 v3, v104, v166
	v_rndne_f32_e32 v0, v0
	v_cvt_i32_f32_e32 v1, v1
	v_rndne_f32_e32 v2, v2
	v_rndne_f32_e32 v3, v3
	v_cvt_i32_f32_e32 v0, v0
	v_cvt_i32_f32_sdwa v2, v2 dst_sel:WORD_1 dst_unused:UNUSED_PAD src0_sel:DWORD
	v_cvt_i32_f32_e32 v3, v3
	v_lshlrev_b32_e32 v1, 8, v1
	v_and_b32_e32 v1, 0xff00, v1
	v_and_b32_e32 v2, 0xff0000, v2
	v_perm_b32 v0, v3, v0, s90
	v_mul_f32_e32 v3, v25, v165
	v_or3_b32 v0, v0, v1, v2
	v_mul_f32_e32 v2, v29, v165
	v_rndne_f32_e32 v3, v3
	v_mul_f32_e32 v4, v109, v165
	v_mul_f32_e32 v5, v105, v165
	v_rndne_f32_e32 v2, v2
	v_cvt_i32_f32_e32 v3, v3
	v_rndne_f32_e32 v4, v4
	v_rndne_f32_e32 v5, v5
	v_cvt_i32_f32_e32 v2, v2
	v_cvt_i32_f32_sdwa v4, v4 dst_sel:WORD_1 dst_unused:UNUSED_PAD src0_sel:DWORD
	v_cvt_i32_f32_e32 v5, v5
	v_lshlrev_b32_e32 v3, 8, v3
	v_and_b32_e32 v3, 0xff00, v3
	v_and_b32_e32 v4, 0xff0000, v4
	v_perm_b32 v2, v5, v2, s90
	v_add_u32_e32 v1, v144, v138
	v_or3_b32 v2, v2, v3, v4
	ds_write2_b32 v1, v0, v2 offset1:32
	v_mul_f32_e32 v2, v26, v167
	v_mul_f32_e32 v0, v30, v167
	v_rndne_f32_e32 v2, v2
	v_mul_f32_e32 v3, v110, v167
	v_mul_f32_e32 v4, v106, v167
	v_rndne_f32_e32 v0, v0
	v_cvt_i32_f32_e32 v2, v2
	v_rndne_f32_e32 v3, v3
	v_rndne_f32_e32 v4, v4
	v_cvt_i32_f32_e32 v0, v0
	v_cvt_i32_f32_sdwa v3, v3 dst_sel:WORD_1 dst_unused:UNUSED_PAD src0_sel:DWORD
	v_cvt_i32_f32_e32 v4, v4
	v_lshlrev_b32_e32 v2, 8, v2
	v_and_b32_e32 v2, 0xff00, v2
	v_and_b32_e32 v3, 0xff0000, v3
	v_perm_b32 v0, v4, v0, s90
	v_or3_b32 v0, v0, v2, v3
	v_mul_f32_e32 v3, v27, v112
	v_mul_f32_e32 v2, v31, v112
	v_rndne_f32_e32 v3, v3
	v_mul_f32_e32 v4, v111, v112
	v_mul_f32_e32 v5, v107, v112
	v_rndne_f32_e32 v2, v2
	v_cvt_i32_f32_e32 v3, v3
	v_rndne_f32_e32 v4, v4
	v_rndne_f32_e32 v5, v5
	v_cvt_i32_f32_e32 v2, v2
	v_cvt_i32_f32_sdwa v4, v4 dst_sel:WORD_1 dst_unused:UNUSED_PAD src0_sel:DWORD
	v_cvt_i32_f32_e32 v5, v5
	v_lshlrev_b32_e32 v3, 8, v3
	v_and_b32_e32 v3, 0xff00, v3
	v_and_b32_e32 v4, 0xff0000, v4
	v_perm_b32 v2, v5, v2, s90
	v_or3_b32 v2, v2, v3, v4
	ds_write2_b32 v1, v0, v2 offset0:64 offset1:96
	s_waitcnt vmcnt(2)
	v_mul_f32_e32 v1, v68, v166
	v_mul_f32_e32 v0, v76, v166
	v_rndne_f32_e32 v1, v1
	s_waitcnt vmcnt(1)
	v_mul_f32_e32 v2, v72, v166
	s_waitcnt vmcnt(0)
	v_mul_f32_e32 v3, v64, v166
	v_rndne_f32_e32 v0, v0
	v_cvt_i32_f32_e32 v1, v1
	v_rndne_f32_e32 v2, v2
	v_rndne_f32_e32 v3, v3
	v_cvt_i32_f32_e32 v0, v0
	v_cvt_i32_f32_sdwa v2, v2 dst_sel:WORD_1 dst_unused:UNUSED_PAD src0_sel:DWORD
	v_cvt_i32_f32_e32 v3, v3
	v_lshlrev_b32_e32 v1, 8, v1
	v_and_b32_e32 v1, 0xff00, v1
	v_and_b32_e32 v2, 0xff0000, v2
	v_perm_b32 v0, v3, v0, s90
	v_mul_f32_e32 v3, v69, v165
	v_or3_b32 v0, v0, v1, v2
	v_mul_f32_e32 v2, v77, v165
	v_rndne_f32_e32 v3, v3
	v_mul_f32_e32 v4, v73, v165
	v_mul_f32_e32 v5, v65, v165
	v_rndne_f32_e32 v2, v2
	v_cvt_i32_f32_e32 v3, v3
	v_rndne_f32_e32 v4, v4
	v_rndne_f32_e32 v5, v5
	v_cvt_i32_f32_e32 v2, v2
	v_cvt_i32_f32_sdwa v4, v4 dst_sel:WORD_1 dst_unused:UNUSED_PAD src0_sel:DWORD
	v_cvt_i32_f32_e32 v5, v5
	v_lshlrev_b32_e32 v3, 8, v3
	v_and_b32_e32 v3, 0xff00, v3
	v_and_b32_e32 v4, 0xff0000, v4
	v_perm_b32 v2, v5, v2, s90
	v_add_u32_e32 v1, v145, v138
	v_or3_b32 v2, v2, v3, v4
	ds_write2_b32 v1, v0, v2 offset1:32
	v_mul_f32_e32 v2, v70, v167
	v_mul_f32_e32 v0, v78, v167
	v_rndne_f32_e32 v2, v2
	v_mul_f32_e32 v3, v74, v167
	v_mul_f32_e32 v4, v66, v167
	v_rndne_f32_e32 v0, v0
	v_cvt_i32_f32_e32 v2, v2
	v_rndne_f32_e32 v3, v3
	v_rndne_f32_e32 v4, v4
	v_cvt_i32_f32_e32 v0, v0
	v_cvt_i32_f32_sdwa v3, v3 dst_sel:WORD_1 dst_unused:UNUSED_PAD src0_sel:DWORD
	v_cvt_i32_f32_e32 v4, v4
	v_lshlrev_b32_e32 v2, 8, v2
	v_and_b32_e32 v2, 0xff00, v2
	v_and_b32_e32 v3, 0xff0000, v3
	v_perm_b32 v0, v4, v0, s90
	v_or3_b32 v0, v0, v2, v3
	v_mul_f32_e32 v3, v71, v112
	v_mul_f32_e32 v2, v79, v112
	v_rndne_f32_e32 v3, v3
	v_mul_f32_e32 v4, v75, v112
	v_mul_f32_e32 v5, v67, v112
	v_rndne_f32_e32 v2, v2
	v_cvt_i32_f32_e32 v3, v3
	v_rndne_f32_e32 v4, v4
	v_rndne_f32_e32 v5, v5
	v_cvt_i32_f32_e32 v2, v2
	v_cvt_i32_f32_sdwa v4, v4 dst_sel:WORD_1 dst_unused:UNUSED_PAD src0_sel:DWORD
	v_cvt_i32_f32_e32 v5, v5
	v_lshlrev_b32_e32 v3, 8, v3
	v_and_b32_e32 v3, 0xff00, v3
	v_and_b32_e32 v4, 0xff0000, v4
	v_perm_b32 v2, v5, v2, s90
	v_or3_b32 v2, v2, v3, v4
	ds_write2_b32 v1, v0, v2 offset0:64 offset1:96
	s_waitcnt lgkmcnt(0)
	ds_read_b128 v[0:3], v147
	v_add_u32_e32 v4, s2, v146
	v_ashrrev_i32_e32 v5, 31, v4
	v_lshl_add_u64 v[8:9], v[122:123], 0, s[10:11]
	v_lshlrev_b64 v[4:5], 12, v[4:5]
	v_lshl_add_u64 v[10:11], v[8:9], 0, v[4:5]
	ds_read_b128 v[4:7], v149
	s_waitcnt lgkmcnt(1)
	global_store_dwordx4 v[10:11], v[0:3], off
	v_readlane_b32 s52, v255, 11
	v_readlane_b32 s53, v255, 12
	v_add_u32_e32 v0, s2, v148
	v_ashrrev_i32_e32 v1, 31, v0
	v_lshlrev_b64 v[0:1], 12, v[0:1]
	v_lshl_add_u64 v[0:1], v[8:9], 0, v[0:1]
	s_waitcnt lgkmcnt(0)
	global_store_dwordx4 v[0:1], v[4:7], off
	ds_read_b128 v[0:3], v151
	v_readlane_b32 s54, v255, 13
	v_add_u32_e32 v4, s2, v150
	v_ashrrev_i32_e32 v5, 31, v4
	v_lshlrev_b64 v[4:5], 12, v[4:5]
	v_lshl_add_u64 v[10:11], v[8:9], 0, v[4:5]
	ds_read_b128 v[4:7], v153
	s_waitcnt lgkmcnt(1)
	global_store_dwordx4 v[10:11], v[0:3], off
	v_readlane_b32 s55, v255, 14
	v_readlane_b32 s56, v255, 15
	v_add_u32_e32 v0, s2, v152
	v_ashrrev_i32_e32 v1, 31, v0
	v_lshlrev_b64 v[0:1], 12, v[0:1]
	v_lshl_add_u64 v[0:1], v[8:9], 0, v[0:1]
	s_waitcnt lgkmcnt(0)
	global_store_dwordx4 v[0:1], v[4:7], off
	ds_read_b128 v[0:3], v155
	v_readlane_b32 s57, v255, 16
	v_add_u32_e32 v4, s2, v154
	v_ashrrev_i32_e32 v5, 31, v4
	v_lshlrev_b64 v[4:5], 12, v[4:5]
	v_lshl_add_u64 v[10:11], v[8:9], 0, v[4:5]
	ds_read_b128 v[4:7], v157
	s_waitcnt lgkmcnt(1)
	global_store_dwordx4 v[10:11], v[0:3], off
	v_readlane_b32 s58, v255, 17
	v_readlane_b32 s59, v255, 18
	v_add_u32_e32 v0, s2, v156
	v_ashrrev_i32_e32 v1, 31, v0
	v_lshlrev_b64 v[0:1], 12, v[0:1]
	v_lshl_add_u64 v[0:1], v[8:9], 0, v[0:1]
	s_waitcnt lgkmcnt(0)
	global_store_dwordx4 v[0:1], v[4:7], off
	ds_read_b128 v[0:3], v159
	v_readlane_b32 s62, v255, 21
	v_add_u32_e32 v4, s2, v158
	v_ashrrev_i32_e32 v5, 31, v4
	v_lshlrev_b64 v[4:5], 12, v[4:5]
	v_lshl_add_u64 v[10:11], v[8:9], 0, v[4:5]
	ds_read_b128 v[4:7], v161
	s_waitcnt lgkmcnt(1)
	global_store_dwordx4 v[10:11], v[0:3], off
	v_readlane_b32 s63, v255, 22
	s_nop 0
	v_add_u32_e32 v0, s2, v160
	v_ashrrev_i32_e32 v1, 31, v0
	v_lshlrev_b64 v[0:1], 12, v[0:1]
	v_lshl_add_u64 v[0:1], v[8:9], 0, v[0:1]
	s_waitcnt lgkmcnt(0)
	global_store_dwordx4 v[0:1], v[4:7], off
	s_waitcnt lgkmcnt(0)

.LBB0_107:
	s_andn2_b64 vcc, exec, s[0:1]
	s_branch .LBB0_109
	s_and_b32 s0, s72, 0x7fffe000
	s_add_i32 s2, s4, 0xffffd400
	s_sub_i32 s1, s23, s0
	s_and_b32 s10, s2, 0xffffff80
	v_subrev_u32_e32 v104, s0, v162
	s_add_i32 s0, s81, s1
	v_add_u32_e32 v0, s10, v136
	s_add_i32 s0, s0, 0xfff50000
	v_ashrrev_i32_e32 v1, 31, v0
	v_readlane_b32 s48, v255, 39
	v_lshlrev_b64 v[0:1], 15, v[0:1]
	v_readlane_b32 s56, v255, 47
	v_readlane_b32 s57, v255, 48
	s_ashr_i32 s1, s0, 31
	s_lshl_b64 s[0:1], s[0:1], 2
	v_lshl_add_u64 v[0:1], s[56:57], 0, v[0:1]
	v_lshl_add_u64 v[0:1], v[0:1], 0, s[0:1]
	v_lshl_add_u64 v[44:45], v[0:1], 0, v[114:115]
	v_add_co_u32_e32 v0, vcc, s79, v44
	s_mov_b32 s2, 0x80000
	s_nop 0
	v_addc_co_u32_e32 v1, vcc, 0, v45, vcc
	global_load_dwordx4 v[36:39], v[44:45], off nt
	global_load_dwordx4 v[32:35], v[0:1], off nt
	v_add_co_u32_e32 v0, vcc, s85, v44
	v_lshl_add_u64 v[40:41], v[124:125], 0, s[0:1]
	s_nop 0
	v_addc_co_u32_e32 v1, vcc, 0, v45, vcc
	v_add_co_u32_e32 v2, vcc, s87, v44
	s_mov_b32 s0, 0x118000
	s_nop 0
	v_addc_co_u32_e32 v3, vcc, 0, v45, vcc
	global_load_dwordx4 v[28:31], v[0:1], off nt
	global_load_dwordx4 v[24:27], v[2:3], off nt
	v_add_co_u32_e32 v0, vcc, s2, v44
	s_mov_b32 s2, 0x88000
	s_nop 0
	v_addc_co_u32_e32 v1, vcc, 0, v45, vcc
	v_add_co_u32_e32 v2, vcc, s2, v44
	s_mov_b32 s2, 0x90000
	s_nop 0
	v_addc_co_u32_e32 v3, vcc, 0, v45, vcc
	global_load_dwordx4 v[20:23], v[0:1], off nt
	global_load_dwordx4 v[12:15], v[2:3], off nt
	v_add_co_u32_e32 v0, vcc, s2, v44
	s_mov_b32 s2, 0x98000
	s_nop 0
	v_addc_co_u32_e32 v1, vcc, 0, v45, vcc
	v_add_co_u32_e32 v2, vcc, s2, v44
	s_mov_b32 s2, 0x100000
	s_nop 0
	v_addc_co_u32_e32 v3, vcc, 0, v45, vcc
	global_load_dwordx4 v[16:19], v[0:1], off nt
	global_load_dwordx4 v[8:11], v[2:3], off nt
	v_add_co_u32_e32 v0, vcc, s2, v44
	s_mov_b32 s2, 0x108000
	s_nop 0
	v_addc_co_u32_e32 v1, vcc, 0, v45, vcc
	v_add_co_u32_e32 v2, vcc, s2, v44
	s_mov_b32 s2, 0x110000
	s_nop 0
	v_addc_co_u32_e32 v3, vcc, 0, v45, vcc
	global_load_dwordx4 v[4:7], v[0:1], off nt
	s_nop 0
	global_load_dwordx4 v[0:3], v[2:3], off nt
	v_add_co_u32_e32 v46, vcc, s2, v44
	global_load_dwordx4 v[40:43], v[40:41], off
	s_nop 0
	v_addc_co_u32_e32 v47, vcc, 0, v45, vcc
	v_add_co_u32_e32 v48, vcc, s0, v44
	s_mov_b32 s0, 0x180000
	s_nop 0
	v_addc_co_u32_e32 v49, vcc, 0, v45, vcc
	v_add_co_u32_e32 v50, vcc, s0, v44
	s_mov_b32 s0, 0x188000
	s_nop 0
	v_addc_co_u32_e32 v51, vcc, 0, v45, vcc
	v_add_co_u32_e32 v52, vcc, s0, v44
	s_mov_b32 s0, 0x200000
	s_nop 0
	v_addc_co_u32_e32 v53, vcc, 0, v45, vcc
	v_add_co_u32_e32 v54, vcc, s91, v44
	global_load_dwordx4 v[76:79], v[46:47], off nt
	global_load_dwordx4 v[72:75], v[48:49], off nt
	v_addc_co_u32_e32 v55, vcc, 0, v45, vcc
	v_add_co_u32_e32 v80, vcc, s88, v44
	v_readlane_b32 s49, v255, 40
	s_nop 0
	v_addc_co_u32_e32 v81, vcc, 0, v45, vcc
	v_add_co_u32_e32 v110, vcc, s0, v44
	s_mov_b32 s0, 0x208000
	s_nop 0
	v_addc_co_u32_e32 v111, vcc, 0, v45, vcc
	v_add_co_u32_e32 v112, vcc, s0, v44
	s_mov_b32 s0, 0x210000
	s_nop 0
	v_addc_co_u32_e32 v113, vcc, 0, v45, vcc
	v_add_co_u32_e32 v166, vcc, s0, v44
	s_mov_b32 s0, 0x218000
	s_nop 0
	v_addc_co_u32_e32 v167, vcc, 0, v45, vcc
	v_add_co_u32_e32 v168, vcc, s0, v44
	s_mov_b32 s0, 0x288000
	s_nop 0
	v_addc_co_u32_e32 v169, vcc, 0, v45, vcc
	v_add_co_u32_e32 v60, vcc, s94, v44
	v_readlane_b32 s50, v255, 41
	s_nop 0
	v_addc_co_u32_e32 v61, vcc, 0, v45, vcc
	v_add_co_u32_e32 v62, vcc, s0, v44
	s_mov_b32 s0, 0x290000
	s_nop 0
	v_addc_co_u32_e32 v63, vcc, 0, v45, vcc
	v_add_co_u32_e32 v56, vcc, s0, v44
	s_mov_b32 s0, 0x298000
	s_nop 0
	v_addc_co_u32_e32 v57, vcc, 0, v45, vcc
	v_add_co_u32_e32 v58, vcc, s0, v44
	s_mov_b32 s0, 0x300000
	s_nop 0
	v_addc_co_u32_e32 v59, vcc, 0, v45, vcc
	v_add_co_u32_e32 v96, vcc, s0, v44
	s_mov_b32 s0, 0x308000
	s_nop 0
	v_addc_co_u32_e32 v97, vcc, 0, v45, vcc
	v_add_co_u32_e32 v100, vcc, s0, v44
	s_mov_b32 s0, 0x310000
	s_nop 0
	v_addc_co_u32_e32 v101, vcc, 0, v45, vcc
	v_add_co_u32_e32 v98, vcc, s0, v44
	s_mov_b32 s0, 0x318000
	s_nop 0
	v_addc_co_u32_e32 v99, vcc, 0, v45, vcc
	v_add_co_u32_e32 v102, vcc, s0, v44
	s_mov_b32 s0, 0x380000
	s_nop 0
	v_addc_co_u32_e32 v103, vcc, 0, v45, vcc
	v_add_co_u32_e32 v92, vcc, s0, v44
	s_mov_b32 s0, 0x388000
	s_nop 0
	v_addc_co_u32_e32 v93, vcc, 0, v45, vcc
	v_add_co_u32_e32 v94, vcc, s0, v44
	s_mov_b32 s0, 0x390000
	s_nop 0
	v_addc_co_u32_e32 v95, vcc, 0, v45, vcc
	v_add_co_u32_e32 v88, vcc, s0, v44
	s_waitcnt vmcnt(2)
	v_div_scale_f32 v64, s[0:1], v40, v40, s89
	v_rcp_f32_e32 v65, v64
	v_addc_co_u32_e32 v89, vcc, 0, v45, vcc
	s_mov_b32 s0, 0x398000
	v_add_co_u32_e32 v90, vcc, s0, v44
	v_fma_f32 v44, -v64, v65, 1.0
	s_nop 0
	v_addc_co_u32_e32 v91, vcc, 0, v45, vcc
	v_fmac_f32_e32 v65, v44, v65
	v_div_scale_f32 v44, vcc, s89, v40, s89
	v_mul_f32_e32 v45, v44, v65
	v_fma_f32 v66, -v64, v45, v44
	v_fmac_f32_e32 v45, v66, v65
	v_div_scale_f32 v66, s[0:1], v41, v41, s89
	v_rcp_f32_e32 v67, v66
	v_fma_f32 v44, -v64, v45, v44
	v_div_fmas_f32 v44, v44, v65, v45
	v_div_fixup_f32 v44, v44, v40, s89
	v_fma_f32 v45, -v66, v67, 1.0
	v_fmac_f32_e32 v67, v45, v67
	v_div_scale_f32 v45, vcc, s89, v41, s89
	v_mul_f32_e32 v64, v45, v67
	v_fma_f32 v65, -v66, v64, v45
	v_fmac_f32_e32 v64, v65, v67
	v_div_scale_f32 v65, s[0:1], v42, v42, s89
	v_rcp_f32_e32 v68, v65
	v_fma_f32 v45, -v66, v64, v45
	v_div_fmas_f32 v45, v45, v67, v64
	v_readlane_b32 s51, v255, 42
	v_fma_f32 v64, -v65, v68, 1.0
	v_fmac_f32_e32 v68, v64, v68
	v_div_scale_f32 v64, vcc, s89, v42, s89
	v_mul_f32_e32 v66, v64, v68
	v_fma_f32 v67, -v65, v66, v64
	v_fmac_f32_e32 v66, v67, v68
	v_div_scale_f32 v67, s[0:1], v43, v43, s89
	v_cmp_lt_f32_e64 s[0:1], 0, v40
	v_rcp_f32_e32 v69, v67
	v_div_fixup_f32 v40, v45, v41, s89
	v_cndmask_b32_e64 v106, 0, v44, s[0:1]
	v_mul_f32_e32 v32, v32, v106
	v_mul_f32_e32 v36, v36, v106
	v_rndne_f32_e32 v32, v32
	v_mul_f32_e32 v28, v28, v106
	v_mul_f32_e32 v24, v24, v106
	v_mul_f32_e32 v12, v12, v106
	v_rndne_f32_e32 v36, v36
	v_cvt_i32_f32_e32 v32, v32
	v_rndne_f32_e32 v28, v28
	v_rndne_f32_e32 v24, v24
	v_mul_f32_e32 v20, v20, v106
	v_rndne_f32_e32 v12, v12
	v_mul_f32_e32 v16, v16, v106
	v_mul_f32_e32 v8, v8, v106
	v_cvt_i32_f32_e32 v36, v36
	v_cvt_i32_f32_sdwa v28, v28 dst_sel:WORD_1 dst_unused:UNUSED_PAD src0_sel:DWORD
	v_cvt_i32_f32_e32 v24, v24
	v_rndne_f32_e32 v20, v20
	v_cvt_i32_f32_e32 v12, v12
	v_rndne_f32_e32 v16, v16
	v_rndne_f32_e32 v8, v8
	v_cvt_i32_f32_e32 v20, v20
	v_cvt_i32_f32_sdwa v16, v16 dst_sel:WORD_1 dst_unused:UNUSED_PAD src0_sel:DWORD
	v_cvt_i32_f32_e32 v8, v8
	v_cmp_lt_f32_e64 s[0:1], 0, v41
	v_lshlrev_b32_e32 v32, 8, v32
	v_and_b32_e32 v32, 0xff00, v32
	v_cndmask_b32_e64 v105, 0, v40, s[0:1]
	v_and_b32_e32 v28, 0xff0000, v28
	v_perm_b32 v24, v24, v36, s90
	v_mul_f32_e32 v33, v33, v105
	v_lshlrev_b32_e32 v12, 8, v12
	v_or3_b32 v24, v24, v32, v28
	v_mul_f32_e32 v32, v37, v105
	v_rndne_f32_e32 v33, v33
	v_mul_f32_e32 v29, v29, v105
	v_mul_f32_e32 v25, v25, v105
	v_and_b32_e32 v12, 0xff00, v12
	v_and_b32_e32 v16, 0xff0000, v16
	v_perm_b32 v8, v8, v20, s90
	v_mul_f32_e32 v13, v13, v105
	v_fma_f32 v64, -v65, v66, v64
	v_fma_f32 v65, -v67, v69, 1.0
	v_rndne_f32_e32 v32, v32
	v_cvt_i32_f32_e32 v33, v33
	v_rndne_f32_e32 v29, v29
	v_rndne_f32_e32 v25, v25
	v_or3_b32 v8, v8, v12, v16
	v_mul_f32_e32 v16, v21, v105
	v_rndne_f32_e32 v13, v13
	v_mul_f32_e32 v17, v17, v105
	v_mul_f32_e32 v9, v9, v105
	v_div_fmas_f32 v64, v64, v68, v66
	v_fmac_f32_e32 v69, v65, v69
	v_div_scale_f32 v65, vcc, s89, v43, s89
	v_cvt_i32_f32_e32 v32, v32
	v_cvt_i32_f32_sdwa v29, v29 dst_sel:WORD_1 dst_unused:UNUSED_PAD src0_sel:DWORD
	v_cvt_i32_f32_e32 v25, v25
	v_rndne_f32_e32 v16, v16
	v_cvt_i32_f32_e32 v13, v13
	v_rndne_f32_e32 v17, v17
	v_rndne_f32_e32 v9, v9
	v_mul_f32_e32 v66, v65, v69
	v_cvt_i32_f32_e32 v16, v16
	v_cvt_i32_f32_sdwa v17, v17 dst_sel:WORD_1 dst_unused:UNUSED_PAD src0_sel:DWORD
	v_cvt_i32_f32_e32 v9, v9
	v_fma_f32 v68, -v67, v66, v65
	v_fmac_f32_e32 v66, v68, v69
	v_div_fixup_f32 v40, v64, v42, s89
	v_cmp_lt_f32_e64 s[0:1], 0, v42
	v_lshlrev_b32_e32 v33, 8, v33
	v_fma_f32 v65, -v67, v66, v65
	v_and_b32_e32 v33, 0xff00, v33
	v_and_b32_e32 v29, 0xff0000, v29
	v_perm_b32 v25, v25, v32, s90
	v_cndmask_b32_e64 v108, 0, v40, s[0:1]
	v_lshlrev_b32_e32 v13, 8, v13
	v_div_fmas_f32 v41, v65, v69, v66
	v_add_u32_e32 v28, v137, v138
	v_or3_b32 v25, v25, v33, v29
	v_mul_f32_e32 v29, v34, v108
	v_and_b32_e32 v13, 0xff00, v13
	v_and_b32_e32 v17, 0xff0000, v17
	v_perm_b32 v9, v9, v16, s90
	v_div_fixup_f32 v41, v41, v43, s89
	v_cmp_lt_f32_e32 vcc, 0, v43
	ds_write2_b32 v28, v24, v25 offset1:32
	v_mul_f32_e32 v24, v38, v108
	v_rndne_f32_e32 v29, v29
	v_mul_f32_e32 v26, v26, v108
	v_mul_f32_e32 v30, v30, v108
	v_add_u32_e32 v12, v139, v138
	v_or3_b32 v9, v9, v13, v17
	v_mul_f32_e32 v13, v14, v108
	global_load_dwordx4 v[68:71], v[50:51], off nt
	global_load_dwordx4 v[64:67], v[52:53], off nt
	v_cndmask_b32_e32 v107, 0, v41, vcc
	v_rndne_f32_e32 v24, v24
	v_cvt_i32_f32_e32 v29, v29
	v_rndne_f32_e32 v26, v26
	v_rndne_f32_e32 v30, v30
	global_load_dwordx4 v[84:87], v[54:55], off nt
	s_nop 0
	global_load_dwordx4 v[80:83], v[80:81], off nt
	s_nop 0
	global_load_dwordx4 v[52:55], v[110:111], off nt
	global_load_dwordx4 v[44:47], v[112:113], off nt
	global_load_dwordx4 v[48:51], v[166:167], off nt
	global_load_dwordx4 v[40:43], v[168:169], off nt
	ds_write2_b32 v12, v8, v9 offset1:32
	v_mul_f32_e32 v8, v22, v108
	v_rndne_f32_e32 v13, v13
	v_mul_f32_e32 v10, v10, v108
	v_mul_f32_e32 v14, v18, v108
	v_cvt_i32_f32_e32 v24, v24
	v_cvt_i32_f32_e32 v26, v26
	v_cvt_i32_f32_sdwa v30, v30 dst_sel:WORD_1 dst_unused:UNUSED_PAD src0_sel:DWORD
	v_rndne_f32_e32 v8, v8
	v_cvt_i32_f32_e32 v13, v13
	v_rndne_f32_e32 v10, v10
	v_rndne_f32_e32 v14, v14
	v_cvt_i32_f32_e32 v8, v8
	v_cvt_i32_f32_e32 v10, v10
	v_cvt_i32_f32_sdwa v14, v14 dst_sel:WORD_1 dst_unused:UNUSED_PAD src0_sel:DWORD
	v_lshlrev_b32_e32 v29, 8, v29
	v_perm_b32 v24, v26, v24, s90
	v_mul_f32_e32 v26, v35, v107
	v_and_b32_e32 v29, 0xff00, v29
	v_and_b32_e32 v30, 0xff0000, v30
	v_lshlrev_b32_e32 v13, 8, v13
	v_mul_f32_e32 v25, v39, v107
	v_or3_b32 v24, v24, v29, v30
	v_mul_f32_e32 v29, v31, v107
	v_mul_f32_e32 v27, v27, v107
	v_rndne_f32_e32 v26, v26
	v_perm_b32 v8, v10, v8, s90
	v_mul_f32_e32 v10, v15, v107
	v_and_b32_e32 v13, 0xff00, v13
	v_and_b32_e32 v14, 0xff0000, v14
	v_rndne_f32_e32 v25, v25
	v_cvt_i32_f32_e32 v26, v26
	v_rndne_f32_e32 v29, v29
	v_rndne_f32_e32 v27, v27
	v_mul_f32_e32 v9, v23, v107
	v_or3_b32 v8, v8, v13, v14
	v_mul_f32_e32 v13, v19, v107
	v_mul_f32_e32 v11, v11, v107
	v_rndne_f32_e32 v10, v10
	v_cvt_i32_f32_e32 v25, v25
	v_cvt_i32_f32_sdwa v29, v29 dst_sel:WORD_1 dst_unused:UNUSED_PAD src0_sel:DWORD
	v_cvt_i32_f32_e32 v27, v27
	v_rndne_f32_e32 v9, v9
	v_cvt_i32_f32_e32 v10, v10
	v_rndne_f32_e32 v13, v13
	v_rndne_f32_e32 v11, v11
	v_cvt_i32_f32_e32 v9, v9
	v_cvt_i32_f32_sdwa v13, v13 dst_sel:WORD_1 dst_unused:UNUSED_PAD src0_sel:DWORD
	v_cvt_i32_f32_e32 v11, v11
	v_lshlrev_b32_e32 v26, 8, v26
	v_and_b32_e32 v26, 0xff00, v26
	v_and_b32_e32 v29, 0xff0000, v29
	v_perm_b32 v25, v27, v25, s90
	v_lshlrev_b32_e32 v10, 8, v10
	v_or3_b32 v25, v25, v26, v29
	v_and_b32_e32 v10, 0xff00, v10
	v_and_b32_e32 v13, 0xff0000, v13
	v_perm_b32 v9, v11, v9, s90
	ds_write2_b32 v28, v24, v25 offset0:64 offset1:96
	v_or3_b32 v9, v9, v10, v13
	v_mul_f32_e32 v0, v0, v106
	global_load_dwordx4 v[36:39], v[60:61], off nt
	global_load_dwordx4 v[32:35], v[62:63], off nt
	s_nop 0
	global_load_dwordx4 v[60:63], v[56:57], off nt
	s_nop 0
	global_load_dwordx4 v[56:59], v[58:59], off nt
	s_nop 0
	global_load_dwordx4 v[28:31], v[96:97], off nt
	global_load_dwordx4 v[20:23], v[100:101], off nt
	global_load_dwordx4 v[24:27], v[98:99], off nt
	global_load_dwordx4 v[16:19], v[102:103], off nt
	ds_write2_b32 v12, v8, v9 offset0:64 offset1:96
	v_mul_f32_e32 v4, v4, v106
	v_rndne_f32_e32 v0, v0
	s_waitcnt vmcnt(17)
	v_mul_f32_e32 v8, v76, v106
	s_waitcnt vmcnt(16)
	v_mul_f32_e32 v9, v72, v106
	v_rndne_f32_e32 v4, v4
	v_cvt_i32_f32_e32 v0, v0
	v_rndne_f32_e32 v8, v8
	v_rndne_f32_e32 v9, v9
	v_cvt_i32_f32_e32 v4, v4
	v_cvt_i32_f32_sdwa v8, v8 dst_sel:WORD_1 dst_unused:UNUSED_PAD src0_sel:DWORD
	v_cvt_i32_f32_e32 v9, v9
	v_lshlrev_b32_e32 v0, 8, v0
	v_and_b32_e32 v0, 0xff00, v0
	v_and_b32_e32 v8, 0xff0000, v8
	v_perm_b32 v4, v9, v4, s90
	v_mul_f32_e32 v1, v1, v105
	v_or3_b32 v0, v4, v0, v8
	v_mul_f32_e32 v4, v5, v105
	v_rndne_f32_e32 v1, v1
	v_mul_f32_e32 v5, v77, v105
	v_mul_f32_e32 v8, v73, v105
	v_rndne_f32_e32 v4, v4
	v_cvt_i32_f32_e32 v1, v1
	v_rndne_f32_e32 v5, v5
	v_rndne_f32_e32 v8, v8
	v_cvt_i32_f32_e32 v4, v4
	v_cvt_i32_f32_sdwa v5, v5 dst_sel:WORD_1 dst_unused:UNUSED_PAD src0_sel:DWORD
	v_cvt_i32_f32_e32 v8, v8
	v_lshlrev_b32_e32 v1, 8, v1
	v_and_b32_e32 v1, 0xff00, v1
	v_and_b32_e32 v5, 0xff0000, v5
	v_perm_b32 v4, v8, v4, s90
	v_add_u32_e32 v72, v140, v138
	v_or3_b32 v1, v4, v1, v5
	ds_write2_b32 v72, v0, v1 offset1:32
	v_mul_f32_e32 v1, v2, v108
	v_rndne_f32_e32 v1, v1
	v_mul_f32_e32 v0, v6, v108
	v_cvt_i32_f32_e32 v76, v1
	v_mul_f32_e32 v1, v74, v108
	v_rndne_f32_e32 v0, v0
	v_rndne_f32_e32 v1, v1
	v_cvt_i32_f32_e32 v0, v0
	v_cvt_i32_f32_e32 v1, v1
	v_mul_f32_e32 v2, v78, v108
	global_load_dwordx4 v[12:15], v[92:93], off nt
	global_load_dwordx4 v[8:11], v[94:95], off nt
	v_rndne_f32_e32 v2, v2
	v_mul_f32_e32 v73, v7, v107
	v_cvt_i32_f32_sdwa v74, v2 dst_sel:WORD_1 dst_unused:UNUSED_PAD src0_sel:DWORD
	v_perm_b32 v77, v1, v0, s90
	v_mul_f32_e32 v78, v3, v107
	global_load_dwordx4 v[4:7], v[88:89], off nt
	global_load_dwordx4 v[0:3], v[90:91], off nt
	v_lshlrev_b32_e32 v76, 8, v76
	v_and_b32_e32 v76, 0xff00, v76
	v_and_b32_e32 v74, 0xff0000, v74
	v_or3_b32 v74, v77, v76, v74
	v_rndne_f32_e32 v76, v78
	v_mul_f32_e32 v77, v79, v107
	v_mul_f32_e32 v75, v75, v107
	v_rndne_f32_e32 v73, v73
	v_cvt_i32_f32_e32 v76, v76
	v_rndne_f32_e32 v77, v77
	v_rndne_f32_e32 v75, v75
	v_cvt_i32_f32_e32 v73, v73
	v_cvt_i32_f32_sdwa v77, v77 dst_sel:WORD_1 dst_unused:UNUSED_PAD src0_sel:DWORD
	v_cvt_i32_f32_e32 v75, v75
	v_lshlrev_b32_e32 v76, 8, v76
	v_and_b32_e32 v76, 0xff00, v76
	v_and_b32_e32 v77, 0xff0000, v77
	v_perm_b32 v73, v75, v73, s90
	v_or3_b32 v73, v73, v76, v77
	s_waitcnt vmcnt(18)
	v_mul_f32_e32 v64, v64, v106
	ds_write2_b32 v72, v74, v73 offset0:64 offset1:96
	v_mul_f32_e32 v68, v68, v106
	v_rndne_f32_e32 v64, v64
	s_waitcnt vmcnt(17)
	v_mul_f32_e32 v72, v84, v106
	s_waitcnt vmcnt(16)
	v_mul_f32_e32 v73, v80, v106
	s_waitcnt vmcnt(14)
	v_mul_f32_e32 v44, v44, v106
	v_rndne_f32_e32 v68, v68
	v_cvt_i32_f32_e32 v64, v64
	v_rndne_f32_e32 v72, v72
	v_rndne_f32_e32 v73, v73
	v_mul_f32_e32 v52, v52, v106
	v_rndne_f32_e32 v44, v44
	s_waitcnt vmcnt(13)
	v_mul_f32_e32 v48, v48, v106
	s_waitcnt vmcnt(12)
	v_mul_f32_e32 v40, v40, v106
	v_cvt_i32_f32_e32 v68, v68
	v_cvt_i32_f32_sdwa v72, v72 dst_sel:WORD_1 dst_unused:UNUSED_PAD src0_sel:DWORD
	v_cvt_i32_f32_e32 v73, v73
	v_rndne_f32_e32 v52, v52
	v_cvt_i32_f32_e32 v44, v44
	v_rndne_f32_e32 v48, v48
	v_rndne_f32_e32 v40, v40
	v_cvt_i32_f32_e32 v52, v52
	v_cvt_i32_f32_sdwa v48, v48 dst_sel:WORD_1 dst_unused:UNUSED_PAD src0_sel:DWORD
	v_cvt_i32_f32_e32 v40, v40
	v_lshlrev_b32_e32 v64, 8, v64
	v_and_b32_e32 v64, 0xff00, v64
	v_and_b32_e32 v72, 0xff0000, v72
	v_perm_b32 v68, v73, v68, s90
	v_mul_f32_e32 v65, v65, v105
	v_lshlrev_b32_e32 v44, 8, v44
	v_or3_b32 v64, v68, v64, v72
	v_mul_f32_e32 v69, v69, v105
	v_rndne_f32_e32 v65, v65
	v_mul_f32_e32 v72, v85, v105
	v_mul_f32_e32 v73, v81, v105
	v_and_b32_e32 v44, 0xff00, v44
	v_and_b32_e32 v48, 0xff0000, v48
	v_perm_b32 v40, v40, v52, s90
	v_mul_f32_e32 v45, v45, v105
	v_rndne_f32_e32 v69, v69
	v_cvt_i32_f32_e32 v65, v65
	v_rndne_f32_e32 v72, v72
	v_rndne_f32_e32 v73, v73
	v_or3_b32 v40, v40, v44, v48
	v_mul_f32_e32 v48, v53, v105
	v_rndne_f32_e32 v45, v45
	v_mul_f32_e32 v49, v49, v105
	v_mul_f32_e32 v41, v41, v105
	v_cvt_i32_f32_e32 v69, v69
	v_cvt_i32_f32_sdwa v72, v72 dst_sel:WORD_1 dst_unused:UNUSED_PAD src0_sel:DWORD
	v_cvt_i32_f32_e32 v73, v73
	v_rndne_f32_e32 v48, v48
	v_cvt_i32_f32_e32 v45, v45
	v_rndne_f32_e32 v49, v49
	v_rndne_f32_e32 v41, v41
	v_cvt_i32_f32_e32 v48, v48
	v_cvt_i32_f32_sdwa v49, v49 dst_sel:WORD_1 dst_unused:UNUSED_PAD src0_sel:DWORD
	v_cvt_i32_f32_e32 v41, v41
	v_lshlrev_b32_e32 v65, 8, v65
	v_and_b32_e32 v65, 0xff00, v65
	v_and_b32_e32 v72, 0xff0000, v72
	v_perm_b32 v69, v73, v69, s90
	v_lshlrev_b32_e32 v45, 8, v45
	v_add_u32_e32 v68, v141, v138
	v_or3_b32 v65, v69, v65, v72
	v_and_b32_e32 v45, 0xff00, v45
	v_and_b32_e32 v49, 0xff0000, v49
	v_perm_b32 v41, v41, v48, s90
	ds_write2_b32 v68, v64, v65 offset1:32
	v_mul_f32_e32 v65, v66, v108
	v_add_u32_e32 v44, v142, v138
	v_or3_b32 v41, v41, v45, v49
	v_mul_f32_e32 v64, v70, v108
	v_rndne_f32_e32 v65, v65
	v_mul_f32_e32 v66, v86, v108
	v_mul_f32_e32 v69, v82, v108
	ds_write2_b32 v44, v40, v41 offset1:32
	v_mul_f32_e32 v41, v46, v108
	v_rndne_f32_e32 v64, v64
	v_cvt_i32_f32_e32 v65, v65
	v_rndne_f32_e32 v66, v66
	v_rndne_f32_e32 v69, v69
	v_mul_f32_e32 v40, v54, v108
	v_rndne_f32_e32 v41, v41
	v_mul_f32_e32 v45, v50, v108
	v_mul_f32_e32 v42, v42, v108
	v_cvt_i32_f32_e32 v64, v64
	v_cvt_i32_f32_sdwa v66, v66 dst_sel:WORD_1 dst_unused:UNUSED_PAD src0_sel:DWORD
	v_cvt_i32_f32_e32 v69, v69
	v_rndne_f32_e32 v40, v40
	v_cvt_i32_f32_e32 v41, v41
	v_rndne_f32_e32 v45, v45
	v_rndne_f32_e32 v42, v42
	v_cvt_i32_f32_e32 v40, v40
	v_cvt_i32_f32_sdwa v45, v45 dst_sel:WORD_1 dst_unused:UNUSED_PAD src0_sel:DWORD
	v_cvt_i32_f32_e32 v42, v42
	v_lshlrev_b32_e32 v65, 8, v65
	v_and_b32_e32 v65, 0xff00, v65
	v_and_b32_e32 v66, 0xff0000, v66
	v_perm_b32 v64, v69, v64, s90
	v_lshlrev_b32_e32 v41, 8, v41
	v_or3_b32 v64, v64, v65, v66
	v_mul_f32_e32 v66, v67, v107
	v_and_b32_e32 v41, 0xff00, v41
	v_and_b32_e32 v45, 0xff0000, v45
	v_perm_b32 v40, v42, v40, s90
	v_mul_f32_e32 v42, v47, v107
	v_mul_f32_e32 v65, v71, v107
	v_rndne_f32_e32 v66, v66
	v_mul_f32_e32 v67, v87, v107
	v_mul_f32_e32 v69, v83, v107
	v_or3_b32 v40, v40, v41, v45
	v_mul_f32_e32 v41, v55, v107
	v_rndne_f32_e32 v42, v42
	v_mul_f32_e32 v45, v51, v107
	v_mul_f32_e32 v43, v43, v107
	v_rndne_f32_e32 v65, v65
	v_cvt_i32_f32_e32 v66, v66
	v_rndne_f32_e32 v67, v67
	v_rndne_f32_e32 v69, v69
	v_rndne_f32_e32 v41, v41
	v_cvt_i32_f32_e32 v42, v42
	v_rndne_f32_e32 v45, v45
	v_rndne_f32_e32 v43, v43
	v_cvt_i32_f32_e32 v65, v65
	v_cvt_i32_f32_sdwa v67, v67 dst_sel:WORD_1 dst_unused:UNUSED_PAD src0_sel:DWORD
	v_cvt_i32_f32_e32 v69, v69
	v_cvt_i32_f32_e32 v41, v41
	v_cvt_i32_f32_sdwa v45, v45 dst_sel:WORD_1 dst_unused:UNUSED_PAD src0_sel:DWORD
	v_cvt_i32_f32_e32 v43, v43
	v_lshlrev_b32_e32 v66, 8, v66
	v_lshlrev_b32_e32 v42, 8, v42
	v_and_b32_e32 v66, 0xff00, v66
	v_and_b32_e32 v67, 0xff0000, v67
	v_perm_b32 v65, v69, v65, s90
	v_and_b32_e32 v42, 0xff00, v42
	v_and_b32_e32 v45, 0xff0000, v45
	v_perm_b32 v41, v43, v41, s90
	v_or3_b32 v65, v65, v66, v67
	v_or3_b32 v41, v41, v42, v45
	s_waitcnt vmcnt(10)
	v_mul_f32_e32 v32, v32, v106
	ds_write2_b32 v68, v64, v65 offset0:64 offset1:96
	ds_write2_b32 v44, v40, v41 offset0:64 offset1:96
	v_mul_f32_e32 v36, v36, v106
	v_rndne_f32_e32 v32, v32
	s_waitcnt vmcnt(9)
	v_mul_f32_e32 v40, v60, v106
	s_waitcnt vmcnt(8)
	v_mul_f32_e32 v41, v56, v106
	s_waitcnt vmcnt(6)
	v_mul_f32_e32 v20, v20, v106
	s_waitcnt vmcnt(2)
	v_mul_f32_e32 v8, v8, v106
	v_rndne_f32_e32 v36, v36
	v_cvt_i32_f32_e32 v32, v32
	v_rndne_f32_e32 v40, v40
	v_rndne_f32_e32 v41, v41
	v_mul_f32_e32 v28, v28, v106
	v_rndne_f32_e32 v20, v20
	v_mul_f32_e32 v24, v24, v106
	v_mul_f32_e32 v16, v16, v106
	v_mul_f32_e32 v12, v12, v106
	v_rndne_f32_e32 v8, v8
	s_waitcnt vmcnt(1)
	v_mul_f32_e32 v4, v4, v106
	s_waitcnt vmcnt(0)
	v_mul_f32_e32 v0, v0, v106
	v_cvt_i32_f32_e32 v36, v36
	v_cvt_i32_f32_sdwa v40, v40 dst_sel:WORD_1 dst_unused:UNUSED_PAD src0_sel:DWORD
	v_cvt_i32_f32_e32 v41, v41
	v_rndne_f32_e32 v28, v28
	v_cvt_i32_f32_e32 v20, v20
	v_rndne_f32_e32 v24, v24
	v_rndne_f32_e32 v16, v16
	v_rndne_f32_e32 v12, v12
	v_cvt_i32_f32_e32 v8, v8
	v_rndne_f32_e32 v4, v4
	v_rndne_f32_e32 v0, v0
	v_cvt_i32_f32_e32 v28, v28
	v_cvt_i32_f32_sdwa v24, v24 dst_sel:WORD_1 dst_unused:UNUSED_PAD src0_sel:DWORD
	v_cvt_i32_f32_e32 v16, v16
	v_cvt_i32_f32_e32 v12, v12
	v_cvt_i32_f32_sdwa v4, v4 dst_sel:WORD_1 dst_unused:UNUSED_PAD src0_sel:DWORD
	v_cvt_i32_f32_e32 v0, v0
	v_lshlrev_b32_e32 v32, 8, v32
	v_and_b32_e32 v32, 0xff00, v32
	v_and_b32_e32 v40, 0xff0000, v40
	v_perm_b32 v36, v41, v36, s90
	v_mul_f32_e32 v33, v33, v105
	v_lshlrev_b32_e32 v20, 8, v20
	v_lshlrev_b32_e32 v8, 8, v8
	v_or3_b32 v32, v36, v32, v40
	v_mul_f32_e32 v37, v37, v105
	v_rndne_f32_e32 v33, v33
	v_mul_f32_e32 v40, v61, v105
	v_mul_f32_e32 v41, v57, v105
	v_and_b32_e32 v20, 0xff00, v20
	v_and_b32_e32 v24, 0xff0000, v24
	v_perm_b32 v16, v16, v28, s90
	v_mul_f32_e32 v21, v21, v105
	v_and_b32_e32 v8, 0xff00, v8
	v_and_b32_e32 v4, 0xff0000, v4
	v_perm_b32 v0, v0, v12, s90
	v_mul_f32_e32 v9, v9, v105
	v_rndne_f32_e32 v37, v37
	v_cvt_i32_f32_e32 v33, v33
	v_rndne_f32_e32 v40, v40
	v_rndne_f32_e32 v41, v41
	v_or3_b32 v16, v16, v20, v24
	v_mul_f32_e32 v24, v29, v105
	v_rndne_f32_e32 v21, v21
	v_mul_f32_e32 v25, v25, v105
	v_mul_f32_e32 v17, v17, v105
	v_or3_b32 v0, v0, v8, v4
	v_mul_f32_e32 v8, v13, v105
	v_rndne_f32_e32 v9, v9
	v_mul_f32_e32 v5, v5, v105
	v_mul_f32_e32 v1, v1, v105
	v_cvt_i32_f32_e32 v37, v37
	v_cvt_i32_f32_sdwa v40, v40 dst_sel:WORD_1 dst_unused:UNUSED_PAD src0_sel:DWORD
	v_cvt_i32_f32_e32 v41, v41
	v_rndne_f32_e32 v24, v24
	v_cvt_i32_f32_e32 v21, v21
	v_rndne_f32_e32 v25, v25
	v_rndne_f32_e32 v17, v17
	v_rndne_f32_e32 v8, v8
	v_cvt_i32_f32_e32 v9, v9
	v_rndne_f32_e32 v5, v5
	v_rndne_f32_e32 v1, v1
	v_cvt_i32_f32_e32 v24, v24
	v_cvt_i32_f32_sdwa v25, v25 dst_sel:WORD_1 dst_unused:UNUSED_PAD src0_sel:DWORD
	v_cvt_i32_f32_e32 v17, v17
	v_cvt_i32_f32_e32 v8, v8
	v_cvt_i32_f32_sdwa v5, v5 dst_sel:WORD_1 dst_unused:UNUSED_PAD src0_sel:DWORD
	v_cvt_i32_f32_e32 v1, v1
	v_lshlrev_b32_e32 v33, 8, v33
	v_and_b32_e32 v33, 0xff00, v33
	v_and_b32_e32 v40, 0xff0000, v40
	v_perm_b32 v37, v41, v37, s90
	v_lshlrev_b32_e32 v21, 8, v21
	v_lshlrev_b32_e32 v9, 8, v9
	v_add_u32_e32 v36, v143, v138
	v_or3_b32 v33, v37, v33, v40
	v_and_b32_e32 v21, 0xff00, v21
	v_and_b32_e32 v25, 0xff0000, v25
	v_perm_b32 v17, v17, v24, s90
	v_and_b32_e32 v9, 0xff00, v9
	v_and_b32_e32 v5, 0xff0000, v5
	v_perm_b32 v1, v1, v8, s90
	ds_write2_b32 v36, v32, v33 offset1:32
	v_mul_f32_e32 v33, v34, v108
	v_add_u32_e32 v20, v144, v138
	v_or3_b32 v17, v17, v21, v25
	v_add_u32_e32 v4, v145, v138
	v_or3_b32 v1, v1, v9, v5
	v_mul_f32_e32 v32, v38, v108
	v_rndne_f32_e32 v33, v33
	v_mul_f32_e32 v34, v62, v108
	v_mul_f32_e32 v37, v58, v108
	ds_write2_b32 v20, v16, v17 offset1:32
	v_mul_f32_e32 v17, v22, v108
	ds_write2_b32 v4, v0, v1 offset1:32
	v_mul_f32_e32 v1, v10, v108
	v_rndne_f32_e32 v32, v32
	v_cvt_i32_f32_e32 v33, v33
	v_rndne_f32_e32 v34, v34
	v_rndne_f32_e32 v37, v37
	v_mul_f32_e32 v16, v30, v108
	v_rndne_f32_e32 v17, v17
	v_mul_f32_e32 v21, v26, v108
	v_mul_f32_e32 v18, v18, v108
	v_mul_f32_e32 v0, v14, v108
	v_rndne_f32_e32 v1, v1
	v_mul_f32_e32 v5, v6, v108
	v_mul_f32_e32 v2, v2, v108
	v_cvt_i32_f32_e32 v32, v32
	v_cvt_i32_f32_sdwa v34, v34 dst_sel:WORD_1 dst_unused:UNUSED_PAD src0_sel:DWORD
	v_cvt_i32_f32_e32 v37, v37
	v_rndne_f32_e32 v16, v16
	v_cvt_i32_f32_e32 v17, v17
	v_rndne_f32_e32 v21, v21
	v_rndne_f32_e32 v18, v18
	v_rndne_f32_e32 v0, v0
	v_cvt_i32_f32_e32 v1, v1
	v_rndne_f32_e32 v5, v5
	v_rndne_f32_e32 v2, v2
	v_cvt_i32_f32_e32 v16, v16
	v_cvt_i32_f32_sdwa v21, v21 dst_sel:WORD_1 dst_unused:UNUSED_PAD src0_sel:DWORD
	v_cvt_i32_f32_e32 v18, v18
	v_cvt_i32_f32_e32 v0, v0
	v_cvt_i32_f32_sdwa v5, v5 dst_sel:WORD_1 dst_unused:UNUSED_PAD src0_sel:DWORD
	v_cvt_i32_f32_e32 v2, v2
	v_lshlrev_b32_e32 v33, 8, v33
	v_and_b32_e32 v33, 0xff00, v33
	v_and_b32_e32 v34, 0xff0000, v34
	v_perm_b32 v32, v37, v32, s90
	v_lshlrev_b32_e32 v17, 8, v17
	v_lshlrev_b32_e32 v1, 8, v1
	v_or3_b32 v32, v32, v33, v34
	v_mul_f32_e32 v34, v35, v107
	v_and_b32_e32 v17, 0xff00, v17
	v_and_b32_e32 v21, 0xff0000, v21
	v_perm_b32 v16, v18, v16, s90
	v_mul_f32_e32 v18, v23, v107
	v_and_b32_e32 v1, 0xff00, v1
	v_and_b32_e32 v5, 0xff0000, v5
	v_perm_b32 v0, v2, v0, s90
	v_mul_f32_e32 v2, v11, v107
	v_mul_f32_e32 v33, v39, v107
	v_rndne_f32_e32 v34, v34
	v_mul_f32_e32 v35, v63, v107
	v_mul_f32_e32 v37, v59, v107
	v_or3_b32 v16, v16, v17, v21
	v_mul_f32_e32 v17, v31, v107
	v_rndne_f32_e32 v18, v18
	v_mul_f32_e32 v21, v27, v107
	v_mul_f32_e32 v19, v19, v107
	v_or3_b32 v0, v0, v1, v5
	v_mul_f32_e32 v1, v15, v107
	v_rndne_f32_e32 v2, v2
	v_mul_f32_e32 v5, v7, v107
	v_mul_f32_e32 v3, v3, v107
	v_rndne_f32_e32 v33, v33
	v_cvt_i32_f32_e32 v34, v34
	v_rndne_f32_e32 v35, v35
	v_rndne_f32_e32 v37, v37
	v_rndne_f32_e32 v17, v17
	v_cvt_i32_f32_e32 v18, v18
	v_rndne_f32_e32 v21, v21
	v_rndne_f32_e32 v19, v19
	v_rndne_f32_e32 v1, v1
	v_cvt_i32_f32_e32 v2, v2
	v_rndne_f32_e32 v5, v5
	v_rndne_f32_e32 v3, v3
	v_cvt_i32_f32_e32 v33, v33
	v_cvt_i32_f32_sdwa v35, v35 dst_sel:WORD_1 dst_unused:UNUSED_PAD src0_sel:DWORD
	v_cvt_i32_f32_e32 v37, v37
	v_cvt_i32_f32_e32 v17, v17
	v_cvt_i32_f32_sdwa v21, v21 dst_sel:WORD_1 dst_unused:UNUSED_PAD src0_sel:DWORD
	v_cvt_i32_f32_e32 v19, v19
	v_cvt_i32_f32_e32 v1, v1
	v_cvt_i32_f32_sdwa v5, v5 dst_sel:WORD_1 dst_unused:UNUSED_PAD src0_sel:DWORD
	v_cvt_i32_f32_e32 v3, v3
	v_lshlrev_b32_e32 v34, 8, v34
	v_lshlrev_b32_e32 v18, 8, v18
	v_lshlrev_b32_e32 v2, 8, v2
	v_and_b32_e32 v34, 0xff00, v34
	v_and_b32_e32 v35, 0xff0000, v35
	v_perm_b32 v33, v37, v33, s90
	v_and_b32_e32 v18, 0xff00, v18
	v_and_b32_e32 v21, 0xff0000, v21
	v_perm_b32 v17, v19, v17, s90
	v_and_b32_e32 v2, 0xff00, v2
	v_and_b32_e32 v5, 0xff0000, v5
	v_perm_b32 v1, v3, v1, s90
	v_or3_b32 v33, v33, v34, v35
	v_or3_b32 v17, v17, v18, v21
	v_or3_b32 v1, v1, v2, v5
	ds_write2_b32 v36, v32, v33 offset0:64 offset1:96
	ds_write2_b32 v20, v16, v17 offset0:64 offset1:96
	ds_write2_b32 v4, v0, v1 offset0:64 offset1:96
	s_waitcnt lgkmcnt(0)
	s_add_i32 s0, s23, s81
	ds_read_b128 v[0:3], v147
	v_add_u32_e32 v10, s0, v104
	v_subrev_u32_e32 v4, 32, v10
	v_ashrrev_i32_e32 v5, 31, v4
	v_lshl_add_u64 v[8:9], v[126:127], 0, s[10:11]
	v_lshlrev_b64 v[4:5], 12, v[4:5]
	v_lshl_add_u64 v[12:13], v[8:9], 0, v[4:5]
	ds_read_b128 v[4:7], v149
	s_waitcnt lgkmcnt(1)
	global_store_dwordx4 v[12:13], v[0:3], off
	v_ashrrev_i32_e32 v11, 31, v10
	v_readlane_b32 s52, v255, 43
	v_subrev_u32_e32 v0, 24, v10
	v_ashrrev_i32_e32 v1, 31, v0
	v_lshlrev_b64 v[0:1], 12, v[0:1]
	v_lshl_add_u64 v[0:1], v[8:9], 0, v[0:1]
	s_waitcnt lgkmcnt(0)
	global_store_dwordx4 v[0:1], v[4:7], off
	ds_read_b128 v[0:3], v151
	v_readlane_b32 s53, v255, 44
	v_add_u32_e32 v4, -16, v10
	v_ashrrev_i32_e32 v5, 31, v4
	v_lshlrev_b64 v[4:5], 12, v[4:5]
	v_lshl_add_u64 v[12:13], v[8:9], 0, v[4:5]
	ds_read_b128 v[4:7], v153
	s_waitcnt lgkmcnt(1)
	global_store_dwordx4 v[12:13], v[0:3], off
	v_readlane_b32 s54, v255, 45
	v_readlane_b32 s55, v255, 46
	v_add_u32_e32 v0, -8, v10
	v_ashrrev_i32_e32 v1, 31, v0
	v_lshlrev_b64 v[0:1], 12, v[0:1]
	v_lshl_add_u64 v[0:1], v[8:9], 0, v[0:1]
	s_waitcnt lgkmcnt(0)
	global_store_dwordx4 v[0:1], v[4:7], off
	ds_read_b128 v[0:3], v155
	v_readlane_b32 s58, v255, 49
	v_lshlrev_b64 v[4:5], 12, v[10:11]
	v_lshl_add_u64 v[12:13], v[8:9], 0, v[4:5]
	ds_read_b128 v[4:7], v157
	s_waitcnt lgkmcnt(1)
	global_store_dwordx4 v[12:13], v[0:3], off
	v_readlane_b32 s59, v255, 50
	v_readlane_b32 s60, v255, 51
	v_add_u32_e32 v0, 8, v10
	v_ashrrev_i32_e32 v1, 31, v0
	v_lshlrev_b64 v[0:1], 12, v[0:1]
	v_lshl_add_u64 v[0:1], v[8:9], 0, v[0:1]
	s_waitcnt lgkmcnt(0)
	global_store_dwordx4 v[0:1], v[4:7], off
	ds_read_b128 v[0:3], v159
	v_readlane_b32 s61, v255, 52
	v_add_u32_e32 v4, 16, v10
	v_ashrrev_i32_e32 v5, 31, v4
	v_lshlrev_b64 v[4:5], 12, v[4:5]
	v_lshl_add_u64 v[12:13], v[8:9], 0, v[4:5]
	ds_read_b128 v[4:7], v161
	s_waitcnt lgkmcnt(1)
	global_store_dwordx4 v[12:13], v[0:3], off
	v_readlane_b32 s62, v255, 53
	v_readlane_b32 s63, v255, 54
	v_add_u32_e32 v0, 24, v10
	v_ashrrev_i32_e32 v1, 31, v0
	v_lshlrev_b64 v[0:1], 12, v[0:1]
	v_lshl_add_u64 v[0:1], v[8:9], 0, v[0:1]
	s_waitcnt lgkmcnt(0)
	global_store_dwordx4 v[0:1], v[4:7], off
	s_waitcnt lgkmcnt(0)

.LBB0_113:
	s_andn2_b64 vcc, exec, s[0:1]
	s_branch .LBB0_90
	s_mul_hi_i32 s0, s4, 0x66666667
	s_lshr_b32 s1, s0, 31
	s_ashr_i32 s0, s0, 6
	s_add_i32 s1, s0, s1
	s_mul_i32 s2, s1, 0xffffd800
	s_add_i32 s0, s23, s81
	v_readlane_b32 s48, v255, 23
	s_add_i32 s0, s0, s2
	s_lshl_b32 s12, s1, 7
	v_readlane_b32 s52, v255, 27
	v_readlane_b32 s53, v255, 28
	v_add_u32_e32 v2, s12, v136
	s_ashr_i32 s1, s0, 31
	v_mov_b64_e32 v[0:1], s[52:53]
	v_mad_i64_i32 v[0:1], s[6:7], v2, s80, v[0:1]
	s_lshl_b64 s[0:1], s[0:1], 2
	v_lshl_add_u64 v[0:1], v[0:1], 0, s[0:1]
	v_lshl_add_u64 v[34:35], v[0:1], 0, v[114:115]
	v_add_co_u32_e32 v0, vcc, s80, v34
	v_lshl_add_u64 v[8:9], v[130:131], 0, s[0:1]
	s_nop 0
	v_addc_co_u32_e32 v1, vcc, 0, v35, vcc
	global_load_dwordx4 v[4:7], v[34:35], off nt
	s_nop 0
	global_load_dwordx4 v[0:3], v[0:1], off nt
	s_mov_b32 s0, 0x1e000
	global_load_dwordx4 v[56:59], v[8:9], off
	v_add_co_u32_e32 v8, vcc, s86, v34
	s_add_i32 s2, s2, s81
	s_nop 0
	v_addc_co_u32_e32 v9, vcc, 0, v35, vcc
	v_add_co_u32_e32 v10, vcc, s0, v34
	s_mov_b32 s0, 0xb4000
	s_nop 0
	v_addc_co_u32_e32 v11, vcc, 0, v35, vcc
	v_add_co_u32_e32 v38, vcc, s95, v34
	global_load_dwordx4 v[60:63], v[8:9], off nt
	global_load_dwordx4 v[64:67], v[10:11], off nt
	v_addc_co_u32_e32 v39, vcc, 0, v35, vcc
	v_add_co_u32_e32 v32, vcc, s74, v34
	s_ashr_i32 s13, s12, 31
	s_nop 0
	v_addc_co_u32_e32 v33, vcc, 0, v35, vcc
	v_add_co_u32_e32 v42, vcc, s0, v34
	s_mov_b32 s0, 0xbe000
	s_nop 0
	v_addc_co_u32_e32 v43, vcc, 0, v35, vcc
	v_add_co_u32_e32 v40, vcc, s0, v34
	s_mov_b32 s0, 0x154000
	s_nop 0
	v_addc_co_u32_e32 v41, vcc, 0, v35, vcc
	v_add_co_u32_e32 v50, vcc, s78, v34
	v_readlane_b32 s49, v255, 24
	s_nop 0
	v_addc_co_u32_e32 v51, vcc, 0, v35, vcc
	v_add_co_u32_e32 v48, vcc, s84, v34
	v_readlane_b32 s50, v255, 25
	s_nop 0
	v_addc_co_u32_e32 v49, vcc, 0, v35, vcc
	v_add_co_u32_e32 v46, vcc, s0, v34
	s_mov_b32 s0, 0x15e000
	s_nop 0
	v_addc_co_u32_e32 v47, vcc, 0, v35, vcc
	v_add_co_u32_e32 v44, vcc, s0, v34
	s_mov_b32 s0, 0x1f4000
	s_nop 0
	v_addc_co_u32_e32 v45, vcc, 0, v35, vcc
	v_add_co_u32_e32 v36, vcc, s16, v34
	v_readlane_b32 s51, v255, 26
	s_nop 0
	v_addc_co_u32_e32 v37, vcc, 0, v35, vcc
	v_add_co_u32_e32 v30, vcc, s75, v34
	v_readlane_b32 s54, v255, 29
	s_nop 0
	v_addc_co_u32_e32 v31, vcc, 0, v35, vcc
	v_add_co_u32_e32 v28, vcc, s0, v34
	s_mov_b32 s0, 0x1fe000
	s_nop 0
	v_addc_co_u32_e32 v29, vcc, 0, v35, vcc
	v_add_co_u32_e32 v26, vcc, s0, v34
	s_mov_b32 s0, 0x28a000
	s_nop 0
	v_addc_co_u32_e32 v27, vcc, 0, v35, vcc
	v_add_co_u32_e32 v16, vcc, s94, v34
	v_readlane_b32 s55, v255, 30
	s_nop 0
	v_addc_co_u32_e32 v17, vcc, 0, v35, vcc
	v_add_co_u32_e32 v22, vcc, s0, v34
	s_mov_b32 s0, 0x294000
	s_nop 0
	v_addc_co_u32_e32 v23, vcc, 0, v35, vcc
	v_add_co_u32_e32 v12, vcc, s0, v34
	s_mov_b32 s0, 0x29e000
	s_nop 0
	v_addc_co_u32_e32 v13, vcc, 0, v35, vcc
	v_add_co_u32_e32 v14, vcc, s0, v34
	s_mov_b32 s0, 0x320000
	s_nop 0
	v_addc_co_u32_e32 v15, vcc, 0, v35, vcc
	v_add_co_u32_e32 v8, vcc, s0, v34
	s_waitcnt vmcnt(2)
	v_div_scale_f32 v18, s[0:1], v56, v56, s89
	v_rcp_f32_e32 v19, v18
	v_addc_co_u32_e32 v9, vcc, 0, v35, vcc
	s_mov_b32 s0, 0x32a000
	v_add_co_u32_e32 v10, vcc, s0, v34
	v_fma_f32 v20, -v18, v19, 1.0
	s_nop 0
	v_addc_co_u32_e32 v11, vcc, 0, v35, vcc
	v_fmac_f32_e32 v19, v20, v19
	v_div_scale_f32 v20, vcc, s89, v56, s89
	v_mul_f32_e32 v21, v20, v19
	v_fma_f32 v24, -v18, v21, v20
	v_fmac_f32_e32 v21, v24, v19
	v_div_scale_f32 v24, s[0:1], v57, v57, s89
	v_rcp_f32_e32 v25, v24
	v_fma_f32 v18, -v18, v21, v20
	v_div_fmas_f32 v18, v18, v19, v21
	v_readlane_b32 s56, v255, 31
	v_fma_f32 v19, -v24, v25, 1.0
	v_fmac_f32_e32 v25, v19, v25
	v_div_scale_f32 v19, vcc, s89, v57, s89
	v_mul_f32_e32 v20, v19, v25
	v_fma_f32 v21, -v24, v20, v19
	v_fmac_f32_e32 v20, v21, v25
	v_div_scale_f32 v21, s[0:1], v58, v58, s89
	v_rcp_f32_e32 v52, v21
	v_fma_f32 v19, -v24, v20, v19
	v_div_fmas_f32 v19, v19, v25, v20
	v_div_fixup_f32 v68, v19, v57, s89
	v_fma_f32 v20, -v21, v52, 1.0
	v_fmac_f32_e32 v52, v20, v52
	v_div_scale_f32 v20, vcc, s89, v58, s89
	v_mul_f32_e32 v24, v20, v52
	v_fma_f32 v25, -v21, v24, v20
	v_fmac_f32_e32 v24, v25, v52
	v_div_scale_f32 v25, s[0:1], v59, v59, s89
	v_rcp_f32_e32 v53, v25
	v_fma_f32 v20, -v21, v24, v20
	v_div_fmas_f32 v52, v20, v52, v24
	v_div_scale_f32 v24, vcc, s89, v59, s89
	v_fma_f32 v20, -v25, v53, 1.0
	v_fmac_f32_e32 v53, v20, v53
	v_mul_f32_e32 v54, v24, v53
	v_fma_f32 v20, -v25, v54, v24
	s_mov_b32 s0, 0x334000
	v_fmac_f32_e32 v54, v20, v53
	v_add_co_u32_e64 v20, s[0:1], s0, v34
	v_fma_f32 v24, -v25, v54, v24
	s_nop 0
	v_addc_co_u32_e64 v21, s[0:1], 0, v35, s[0:1]
	s_mov_b32 s0, 0x33e000
	v_div_fmas_f32 v53, v24, v53, v54
	v_add_co_u32_e32 v24, vcc, s0, v34
	s_mov_b32 s0, 0x3c0000
	s_nop 0
	v_addc_co_u32_e32 v25, vcc, 0, v35, vcc
	v_div_fixup_f32 v54, v18, v56, s89
	v_add_co_u32_e32 v18, vcc, s0, v34
	v_div_fixup_f32 v52, v52, v58, s89
	s_nop 0
	v_addc_co_u32_e32 v19, vcc, 0, v35, vcc
	v_cmp_lt_f32_e32 vcc, 0, v56
	v_div_fixup_f32 v69, v53, v59, s89
	s_mov_b32 s0, 0x3ca000
	v_cndmask_b32_e32 v55, 0, v54, vcc
	v_cmp_lt_f32_e32 vcc, 0, v57
	v_mul_f32_e32 v72, v0, v55
	s_waitcnt vmcnt(1)
	v_mul_f32_e32 v76, v60, v55
	v_cndmask_b32_e32 v54, 0, v68, vcc
	v_cmp_lt_f32_e32 vcc, 0, v58
	v_mul_f32_e32 v73, v1, v54
	v_mul_f32_e32 v77, v61, v54
	v_cndmask_b32_e32 v53, 0, v52, vcc
	v_cmp_lt_f32_e32 vcc, 0, v59
	v_mul_f32_e32 v74, v2, v53
	global_load_dwordx4 v[56:59], v[32:33], off nt
	v_cndmask_b32_e32 v52, 0, v69, vcc
	v_mul_f32_e32 v75, v3, v52
	global_load_dwordx4 v[0:3], v[38:39], off nt
	v_mul_f32_e32 v78, v62, v53
	v_mul_f32_e32 v79, v63, v52
	s_waitcnt vmcnt(2)
	v_mul_f32_e32 v80, v64, v55
	v_mul_f32_e32 v81, v65, v54
	v_mul_f32_e32 v82, v66, v53
	v_mul_f32_e32 v83, v67, v52
	global_load_dwordx4 v[60:63], v[40:41], off nt
	global_load_dwordx4 v[64:67], v[42:43], off nt
	v_mul_f32_e32 v68, v4, v55
	v_rndne_f32_e32 v72, v72
	v_rndne_f32_e32 v68, v68
	v_rndne_f32_e32 v80, v80
	v_cvt_i32_f32_e32 v72, v72
	v_rndne_f32_e32 v76, v76
	v_cvt_i32_f32_e32 v68, v68
	v_cvt_i32_f32_e32 v80, v80
	v_cvt_i32_f32_sdwa v76, v76 dst_sel:WORD_1 dst_unused:UNUSED_PAD src0_sel:DWORD
	v_lshlrev_b32_e32 v72, 8, v72
	v_mul_f32_e32 v69, v5, v54
	v_perm_b32 v68, v80, v68, s90
	v_and_b32_e32 v72, 0xff00, v72
	v_and_b32_e32 v76, 0xff0000, v76
	v_or3_b32 v68, v68, v72, v76
	v_rndne_f32_e32 v69, v69
	v_rndne_f32_e32 v72, v81
	v_rndne_f32_e32 v73, v73
	v_cvt_i32_f32_e32 v69, v69
	v_cvt_i32_f32_e32 v72, v72
	v_cvt_i32_f32_e32 v73, v73
	v_rndne_f32_e32 v76, v77
	v_cvt_i32_f32_sdwa v76, v76 dst_sel:WORD_1 dst_unused:UNUSED_PAD src0_sel:DWORD
	v_perm_b32 v69, v72, v69, s90
	v_lshlrev_b32_e32 v72, 8, v73
	v_and_b32_e32 v72, 0xff00, v72
	v_and_b32_e32 v73, 0xff0000, v76
	v_mul_f32_e32 v70, v6, v53
	v_or3_b32 v69, v69, v72, v73
	v_add_u32_e32 v72, v137, v138
	ds_write2_b32 v72, v68, v69 offset1:32
	v_rndne_f32_e32 v68, v70
	v_rndne_f32_e32 v69, v82
	v_rndne_f32_e32 v70, v74
	v_cvt_i32_f32_e32 v68, v68
	v_cvt_i32_f32_e32 v69, v69
	v_cvt_i32_f32_e32 v70, v70
	v_rndne_f32_e32 v73, v78
	v_cvt_i32_f32_sdwa v73, v73 dst_sel:WORD_1 dst_unused:UNUSED_PAD src0_sel:DWORD
	v_perm_b32 v68, v69, v68, s90
	v_lshlrev_b32_e32 v69, 8, v70
	v_mul_f32_e32 v71, v7, v52
	v_and_b32_e32 v69, 0xff00, v69
	v_and_b32_e32 v70, 0xff0000, v73
	v_or3_b32 v73, v68, v69, v70
	v_rndne_f32_e32 v68, v71
	v_rndne_f32_e32 v69, v75
	v_rndne_f32_e32 v70, v83
	v_cvt_i32_f32_e32 v68, v68
	v_cvt_i32_f32_e32 v70, v70
	v_cvt_i32_f32_e32 v69, v69
	v_rndne_f32_e32 v71, v79
	v_cvt_i32_f32_sdwa v74, v71 dst_sel:WORD_1 dst_unused:UNUSED_PAD src0_sel:DWORD
	v_perm_b32 v75, v70, v68, s90
	v_lshlrev_b32_e32 v76, 8, v69
	global_load_dwordx4 v[68:71], v[50:51], off nt
	v_and_b32_e32 v50, 0xff00, v76
	v_and_b32_e32 v51, 0xff0000, v74
	v_or3_b32 v50, v75, v50, v51
	ds_write2_b32 v72, v73, v50 offset0:64 offset1:96
	global_load_dwordx4 v[48:51], v[48:49], off nt
	v_add_co_u32_e32 v6, vcc, s0, v34
	global_load_dwordx4 v[72:75], v[46:47], off nt
	s_nop 0
	v_addc_co_u32_e32 v7, vcc, 0, v35, vcc
	s_mov_b32 s0, 0x3d4000
	v_add_co_u32_e32 v4, vcc, s0, v34
	s_waitcnt vmcnt(6)
	v_mul_f32_e32 v47, v56, v55
	v_mul_f32_e32 v56, v59, v52
	s_waitcnt vmcnt(5)
	v_mul_f32_e32 v76, v0, v55
	v_mul_f32_e32 v77, v1, v54
	v_mul_f32_e32 v78, v2, v53
	v_mul_f32_e32 v46, v3, v52
	global_load_dwordx4 v[0:3], v[44:45], off nt
	v_mul_f32_e32 v45, v58, v53
	v_rndne_f32_e32 v47, v47
	s_waitcnt vmcnt(5)
	v_mul_f32_e32 v58, v60, v55
	s_waitcnt vmcnt(4)
	v_mul_f32_e32 v59, v64, v55
	v_mul_f32_e32 v44, v57, v54
	v_rndne_f32_e32 v57, v76
	v_rndne_f32_e32 v58, v58
	v_cvt_i32_f32_e32 v47, v47
	v_rndne_f32_e32 v59, v59
	v_cvt_i32_f32_e32 v57, v57
	v_cvt_i32_f32_e32 v58, v58
	v_cvt_i32_f32_sdwa v59, v59 dst_sel:WORD_1 dst_unused:UNUSED_PAD src0_sel:DWORD
	v_lshlrev_b32_e32 v47, 8, v47
	v_and_b32_e32 v47, 0xff00, v47
	v_perm_b32 v57, v58, v57, s90
	v_and_b32_e32 v58, 0xff0000, v59
	v_or3_b32 v47, v57, v47, v58
	v_mul_f32_e32 v58, v61, v54
	v_rndne_f32_e32 v44, v44
	v_mul_f32_e32 v59, v65, v54
	v_rndne_f32_e32 v57, v77
	v_rndne_f32_e32 v58, v58
	v_cvt_i32_f32_e32 v44, v44
	v_rndne_f32_e32 v59, v59
	v_cvt_i32_f32_e32 v57, v57
	v_cvt_i32_f32_e32 v58, v58
	v_cvt_i32_f32_sdwa v59, v59 dst_sel:WORD_1 dst_unused:UNUSED_PAD src0_sel:DWORD
	v_lshlrev_b32_e32 v44, 8, v44
	v_and_b32_e32 v44, 0xff00, v44
	v_perm_b32 v57, v58, v57, s90
	v_and_b32_e32 v58, 0xff0000, v59
	v_or3_b32 v44, v57, v44, v58
	v_add_u32_e32 v57, v139, v138
	ds_write2_b32 v57, v47, v44 offset1:32
	v_rndne_f32_e32 v45, v45
	v_mul_f32_e32 v47, v62, v53
	v_mul_f32_e32 v58, v66, v53
	v_rndne_f32_e32 v44, v78
	v_cvt_i32_f32_e32 v45, v45
	v_rndne_f32_e32 v47, v47
	v_rndne_f32_e32 v58, v58
	v_cvt_i32_f32_e32 v44, v44
	v_cvt_i32_f32_e32 v47, v47
	v_cvt_i32_f32_sdwa v58, v58 dst_sel:WORD_1 dst_unused:UNUSED_PAD src0_sel:DWORD
	v_lshlrev_b32_e32 v45, 8, v45
	v_and_b32_e32 v45, 0xff00, v45
	v_perm_b32 v44, v47, v44, s90
	v_and_b32_e32 v58, 0xff0000, v58
	v_or3_b32 v58, v44, v45, v58
	v_mul_f32_e32 v44, v63, v52
	v_mul_f32_e32 v47, v67, v52
	v_rndne_f32_e32 v45, v46
	v_rndne_f32_e32 v46, v56
	v_rndne_f32_e32 v44, v44
	v_cvt_i32_f32_e32 v45, v45
	v_cvt_i32_f32_e32 v44, v44
	v_cvt_i32_f32_e32 v56, v46
	v_rndne_f32_e32 v46, v47
	v_cvt_i32_f32_sdwa v59, v46 dst_sel:WORD_1 dst_unused:UNUSED_PAD src0_sel:DWORD
	v_perm_b32 v60, v44, v45, s90
	global_load_dwordx4 v[44:47], v[36:37], off nt
	v_lshlrev_b32_e32 v36, 8, v56
	v_and_b32_e32 v36, 0xff00, v36
	v_and_b32_e32 v37, 0xff0000, v59
	v_or3_b32 v36, v60, v36, v37
	ds_write2_b32 v57, v58, v36 offset0:64 offset1:96
	s_waitcnt vmcnt(4)
	v_mul_f32_e32 v36, v68, v55
	global_load_dwordx4 v[56:59], v[30:31], off nt
	v_rndne_f32_e32 v30, v36
	v_cvt_i32_f32_e32 v36, v30
	global_load_dwordx4 v[28:31], v[28:29], off nt
	s_waitcnt vmcnt(5)
	v_mul_f32_e32 v37, v48, v55
	global_load_dwordx4 v[60:63], v[26:27], off nt
	v_rndne_f32_e32 v37, v37
	s_waitcnt vmcnt(5)
	v_mul_f32_e32 v27, v72, v55
	v_cvt_i32_f32_e32 v26, v37
	v_rndne_f32_e32 v27, v27
	v_cvt_i32_f32_sdwa v27, v27 dst_sel:WORD_1 dst_unused:UNUSED_PAD src0_sel:DWORD
	v_add_u32_e32 v68, v140, v138
	s_waitcnt vmcnt(4)
	v_mul_f32_e32 v0, v0, v55
	v_rndne_f32_e32 v0, v0
	v_cvt_i32_f32_e32 v0, v0
	v_lshlrev_b32_e32 v26, 8, v26
	v_and_b32_e32 v26, 0xff00, v26
	v_and_b32_e32 v27, 0xff0000, v27
	v_perm_b32 v0, v0, v36, s90
	v_or3_b32 v0, v0, v26, v27
	v_mul_f32_e32 v27, v49, v54
	v_mul_f32_e32 v26, v69, v54
	v_rndne_f32_e32 v27, v27
	v_mul_f32_e32 v36, v73, v54
	v_mul_f32_e32 v1, v1, v54
	v_rndne_f32_e32 v26, v26
	v_cvt_i32_f32_e32 v27, v27
	v_rndne_f32_e32 v36, v36
	v_rndne_f32_e32 v1, v1
	v_cvt_i32_f32_e32 v26, v26
	v_cvt_i32_f32_sdwa v36, v36 dst_sel:WORD_1 dst_unused:UNUSED_PAD src0_sel:DWORD
	v_cvt_i32_f32_e32 v1, v1
	v_lshlrev_b32_e32 v27, 8, v27
	v_and_b32_e32 v27, 0xff00, v27
	v_and_b32_e32 v36, 0xff0000, v36
	v_perm_b32 v1, v1, v26, s90
	v_or3_b32 v1, v1, v27, v36
	v_mul_f32_e32 v26, v70, v53
	v_mul_f32_e32 v36, v50, v53
	ds_write2_b32 v68, v0, v1 offset1:32
	v_rndne_f32_e32 v0, v26
	v_rndne_f32_e32 v1, v36
	v_mul_f32_e32 v2, v2, v53
	v_mul_f32_e32 v26, v74, v53
	v_cvt_i32_f32_e32 v1, v1
	v_rndne_f32_e32 v2, v2
	v_rndne_f32_e32 v26, v26
	v_cvt_i32_f32_e32 v0, v0
	v_cvt_i32_f32_e32 v2, v2
	v_cvt_i32_f32_sdwa v26, v26 dst_sel:WORD_1 dst_unused:UNUSED_PAD src0_sel:DWORD
	v_lshlrev_b32_e32 v1, 8, v1
	v_mul_f32_e32 v37, v51, v52
	v_perm_b32 v0, v2, v0, s90
	global_load_dwordx4 v[48:51], v[16:17], off nt
	global_load_dwordx4 v[64:67], v[22:23], off nt
	v_and_b32_e32 v1, 0xff00, v1
	v_and_b32_e32 v2, 0xff0000, v26
	v_or3_b32 v16, v0, v1, v2
	v_mul_f32_e32 v17, v3, v52
	global_load_dwordx4 v[0:3], v[12:13], off nt
	s_nop 0
	global_load_dwordx4 v[12:15], v[14:15], off nt
	v_mul_f32_e32 v27, v71, v52
	v_mul_f32_e32 v36, v75, v52
	v_rndne_f32_e32 v23, v37
	v_rndne_f32_e32 v22, v27
	v_cvt_i32_f32_e32 v23, v23
	v_rndne_f32_e32 v26, v36
	v_rndne_f32_e32 v17, v17
	v_cvt_i32_f32_e32 v22, v22
	v_cvt_i32_f32_sdwa v26, v26 dst_sel:WORD_1 dst_unused:UNUSED_PAD src0_sel:DWORD
	v_cvt_i32_f32_e32 v17, v17
	v_lshlrev_b32_e32 v23, 8, v23
	v_and_b32_e32 v23, 0xff00, v23
	v_and_b32_e32 v26, 0xff0000, v26
	v_perm_b32 v17, v17, v22, s90
	v_or3_b32 v17, v17, v23, v26
	ds_write2_b32 v68, v16, v17 offset0:64 offset1:96
	s_waitcnt vmcnt(7)
	v_mul_f32_e32 v16, v44, v55
	v_rndne_f32_e32 v16, v16
	v_cvt_i32_f32_e32 v16, v16
	v_mul_f32_e32 v36, v46, v53
	v_addc_co_u32_e32 v5, vcc, 0, v35, vcc
	s_waitcnt vmcnt(6)
	v_mul_f32_e32 v17, v56, v55
	v_rndne_f32_e32 v17, v17
	s_waitcnt vmcnt(5)
	v_mul_f32_e32 v22, v28, v55
	v_cvt_i32_f32_e32 v17, v17
	s_waitcnt vmcnt(4)
	v_mul_f32_e32 v23, v60, v55
	v_rndne_f32_e32 v22, v22
	v_rndne_f32_e32 v23, v23
	v_cvt_i32_f32_sdwa v22, v22 dst_sel:WORD_1 dst_unused:UNUSED_PAD src0_sel:DWORD
	v_cvt_i32_f32_e32 v23, v23
	v_lshlrev_b32_e32 v17, 8, v17
	v_and_b32_e32 v17, 0xff00, v17
	v_and_b32_e32 v22, 0xff0000, v22
	v_perm_b32 v16, v23, v16, s90
	v_or3_b32 v16, v16, v17, v22
	v_mul_f32_e32 v22, v57, v54
	v_mul_f32_e32 v17, v45, v54
	v_rndne_f32_e32 v22, v22
	v_mul_f32_e32 v23, v29, v54
	v_mul_f32_e32 v26, v61, v54
	v_rndne_f32_e32 v17, v17
	v_cvt_i32_f32_e32 v22, v22
	v_rndne_f32_e32 v23, v23
	v_rndne_f32_e32 v26, v26
	v_cvt_i32_f32_e32 v17, v17
	v_cvt_i32_f32_sdwa v23, v23 dst_sel:WORD_1 dst_unused:UNUSED_PAD src0_sel:DWORD
	v_cvt_i32_f32_e32 v26, v26
	v_lshlrev_b32_e32 v22, 8, v22
	v_and_b32_e32 v22, 0xff00, v22
	v_and_b32_e32 v23, 0xff0000, v23
	v_perm_b32 v17, v26, v17, s90
	global_load_dwordx4 v[26:29], v[8:9], off nt
	s_nop 0
	global_load_dwordx4 v[8:11], v[10:11], off nt
	v_or3_b32 v17, v17, v22, v23
	v_mul_f32_e32 v60, v47, v52
	global_load_dwordx4 v[20:23], v[20:21], off nt
	s_nop 0
	global_load_dwordx4 v[44:47], v[24:25], off nt
	v_mul_f32_e32 v37, v58, v53
	v_add_u32_e32 v24, v141, v138
	ds_write2_b32 v24, v16, v17 offset1:32
	v_rndne_f32_e32 v17, v37
	v_cvt_i32_f32_e32 v25, v17
	v_mul_f32_e32 v17, v62, v53
	v_rndne_f32_e32 v16, v36
	v_rndne_f32_e32 v17, v17
	v_mul_f32_e32 v30, v30, v53
	v_cvt_i32_f32_e32 v16, v16
	v_cvt_i32_f32_e32 v17, v17
	v_rndne_f32_e32 v30, v30
	v_cvt_i32_f32_sdwa v30, v30 dst_sel:WORD_1 dst_unused:UNUSED_PAD src0_sel:DWORD
	s_mov_b32 s0, 0x3de000
	v_add_co_u32_e32 v38, vcc, s0, v34
	v_mul_f32_e32 v61, v59, v52
	v_perm_b32 v36, v17, v16, s90
	global_load_dwordx4 v[16:19], v[18:19], off nt
	s_nop 0
	global_load_dwordx4 v[56:59], v[6:7], off nt
	v_lshlrev_b32_e32 v6, 8, v25
	v_addc_co_u32_e32 v39, vcc, 0, v35, vcc
	v_and_b32_e32 v6, 0xff00, v6
	v_and_b32_e32 v7, 0xff0000, v30
	v_mul_f32_e32 v31, v31, v52
	v_or3_b32 v25, v36, v6, v7
	v_mul_f32_e32 v30, v63, v52
	global_load_dwordx4 v[4:7], v[4:5], off nt
	s_nop 0
	global_load_dwordx4 v[36:39], v[38:39], off nt
	v_rndne_f32_e32 v61, v61
	v_rndne_f32_e32 v60, v60
	v_cvt_i32_f32_e32 v61, v61
	v_rndne_f32_e32 v31, v31
	v_rndne_f32_e32 v30, v30
	v_cvt_i32_f32_e32 v60, v60
	v_cvt_i32_f32_sdwa v31, v31 dst_sel:WORD_1 dst_unused:UNUSED_PAD src0_sel:DWORD
	v_cvt_i32_f32_e32 v30, v30
	v_lshlrev_b32_e32 v61, 8, v61
	v_and_b32_e32 v61, 0xff00, v61
	v_and_b32_e32 v31, 0xff0000, v31
	v_perm_b32 v30, v30, v60, s90
	v_or3_b32 v30, v30, v61, v31
	ds_write2_b32 v24, v25, v30 offset0:64 offset1:96
	s_waitcnt vmcnt(10)
	v_mul_f32_e32 v25, v64, v55
	v_mul_f32_e32 v24, v48, v55
	v_rndne_f32_e32 v25, v25
	s_waitcnt vmcnt(9)
	v_mul_f32_e32 v0, v0, v55
	s_waitcnt vmcnt(8)
	v_mul_f32_e32 v12, v12, v55
	v_rndne_f32_e32 v24, v24
	v_cvt_i32_f32_e32 v25, v25
	v_rndne_f32_e32 v0, v0
	v_rndne_f32_e32 v12, v12
	v_cvt_i32_f32_e32 v24, v24
	v_cvt_i32_f32_sdwa v0, v0 dst_sel:WORD_1 dst_unused:UNUSED_PAD src0_sel:DWORD
	v_cvt_i32_f32_e32 v12, v12
	v_lshlrev_b32_e32 v25, 8, v25
	v_and_b32_e32 v25, 0xff00, v25
	v_and_b32_e32 v0, 0xff0000, v0
	v_perm_b32 v12, v12, v24, s90
	v_or3_b32 v0, v12, v25, v0
	v_mul_f32_e32 v25, v65, v54
	v_mul_f32_e32 v24, v49, v54
	v_rndne_f32_e32 v25, v25
	v_mul_f32_e32 v1, v1, v54
	v_mul_f32_e32 v13, v13, v54
	v_rndne_f32_e32 v24, v24
	v_cvt_i32_f32_e32 v25, v25
	v_rndne_f32_e32 v1, v1
	v_rndne_f32_e32 v13, v13
	v_cvt_i32_f32_e32 v24, v24
	v_cvt_i32_f32_sdwa v1, v1 dst_sel:WORD_1 dst_unused:UNUSED_PAD src0_sel:DWORD
	v_cvt_i32_f32_e32 v13, v13
	v_lshlrev_b32_e32 v25, 8, v25
	v_and_b32_e32 v25, 0xff00, v25
	v_and_b32_e32 v1, 0xff0000, v1
	v_perm_b32 v13, v13, v24, s90
	v_add_u32_e32 v12, v142, v138
	v_or3_b32 v1, v13, v25, v1
	s_mov_b32 s0, 0x460000
	ds_write2_b32 v12, v0, v1 offset1:32
	v_mul_f32_e32 v1, v66, v53
	v_add_co_u32_e32 v32, vcc, s0, v34
	v_mul_f32_e32 v0, v50, v53
	v_rndne_f32_e32 v1, v1
	v_mul_f32_e32 v2, v2, v53
	v_mul_f32_e32 v13, v14, v53
	v_addc_co_u32_e32 v33, vcc, 0, v35, vcc
	s_mov_b32 s0, 0x46a000
	v_rndne_f32_e32 v0, v0
	v_cvt_i32_f32_e32 v1, v1
	v_rndne_f32_e32 v2, v2
	v_rndne_f32_e32 v13, v13
	v_add_co_u32_e32 v40, vcc, s0, v34
	v_cvt_i32_f32_e32 v0, v0
	v_cvt_i32_f32_sdwa v2, v2 dst_sel:WORD_1 dst_unused:UNUSED_PAD src0_sel:DWORD
	v_cvt_i32_f32_e32 v13, v13
	v_addc_co_u32_e32 v41, vcc, 0, v35, vcc
	s_mov_b32 s0, 0x474000
	v_add_co_u32_e32 v42, vcc, s0, v34
	s_mov_b32 s0, 0x47e000
	s_nop 0
	v_addc_co_u32_e32 v43, vcc, 0, v35, vcc
	v_lshlrev_b32_e32 v1, 8, v1
	v_add_co_u32_e32 v34, vcc, s0, v34
	v_and_b32_e32 v1, 0xff00, v1
	v_and_b32_e32 v2, 0xff0000, v2
	v_perm_b32 v0, v13, v0, s90
	global_load_dwordx4 v[30:33], v[32:33], off nt
	s_nop 0
	global_load_dwordx4 v[60:63], v[40:41], off nt
	v_addc_co_u32_e32 v35, vcc, 0, v35, vcc
	v_or3_b32 v0, v0, v1, v2
	v_mul_f32_e32 v1, v51, v52
	global_load_dwordx4 v[40:43], v[42:43], off nt
	s_nop 0
	global_load_dwordx4 v[48:51], v[34:35], off nt
	v_mul_f32_e32 v2, v67, v52
	v_rndne_f32_e32 v2, v2
	v_mul_f32_e32 v3, v3, v52
	v_mul_f32_e32 v13, v15, v52
	v_rndne_f32_e32 v1, v1
	v_cvt_i32_f32_e32 v2, v2
	v_rndne_f32_e32 v3, v3
	v_rndne_f32_e32 v13, v13
	v_cvt_i32_f32_e32 v1, v1
	v_cvt_i32_f32_sdwa v3, v3 dst_sel:WORD_1 dst_unused:UNUSED_PAD src0_sel:DWORD
	v_cvt_i32_f32_e32 v13, v13
	v_lshlrev_b32_e32 v2, 8, v2
	v_and_b32_e32 v2, 0xff00, v2
	v_and_b32_e32 v3, 0xff0000, v3
	v_perm_b32 v1, v13, v1, s90
	v_or3_b32 v1, v1, v2, v3
	ds_write2_b32 v12, v0, v1 offset0:64 offset1:96
	s_waitcnt vmcnt(10)
	v_mul_f32_e32 v1, v8, v55
	v_mul_f32_e32 v0, v26, v55
	v_rndne_f32_e32 v1, v1
	s_waitcnt vmcnt(9)
	v_mul_f32_e32 v2, v20, v55
	s_waitcnt vmcnt(8)
	v_mul_f32_e32 v3, v44, v55
	v_rndne_f32_e32 v0, v0
	v_cvt_i32_f32_e32 v1, v1
	v_rndne_f32_e32 v2, v2
	v_rndne_f32_e32 v3, v3
	v_cvt_i32_f32_e32 v0, v0
	v_cvt_i32_f32_sdwa v2, v2 dst_sel:WORD_1 dst_unused:UNUSED_PAD src0_sel:DWORD
	v_cvt_i32_f32_e32 v3, v3
	v_lshlrev_b32_e32 v1, 8, v1
	v_and_b32_e32 v1, 0xff00, v1
	v_and_b32_e32 v2, 0xff0000, v2
	v_perm_b32 v0, v3, v0, s90
	v_mul_f32_e32 v3, v9, v54
	v_or3_b32 v0, v0, v1, v2
	v_mul_f32_e32 v2, v27, v54
	v_rndne_f32_e32 v3, v3
	v_mul_f32_e32 v8, v21, v54
	v_mul_f32_e32 v9, v45, v54
	v_rndne_f32_e32 v2, v2
	v_cvt_i32_f32_e32 v3, v3
	v_rndne_f32_e32 v8, v8
	v_rndne_f32_e32 v9, v9
	v_cvt_i32_f32_e32 v2, v2
	v_cvt_i32_f32_sdwa v8, v8 dst_sel:WORD_1 dst_unused:UNUSED_PAD src0_sel:DWORD
	v_cvt_i32_f32_e32 v9, v9
	v_lshlrev_b32_e32 v3, 8, v3
	v_and_b32_e32 v3, 0xff00, v3
	v_and_b32_e32 v8, 0xff0000, v8
	v_perm_b32 v2, v9, v2, s90
	v_add_u32_e32 v1, v143, v138
	v_or3_b32 v2, v2, v3, v8
	ds_write2_b32 v1, v0, v2 offset1:32
	v_mul_f32_e32 v2, v10, v53
	v_mul_f32_e32 v0, v28, v53
	v_rndne_f32_e32 v2, v2
	v_mul_f32_e32 v3, v22, v53
	v_mul_f32_e32 v8, v46, v53
	v_rndne_f32_e32 v0, v0
	v_cvt_i32_f32_e32 v2, v2
	v_rndne_f32_e32 v3, v3
	v_rndne_f32_e32 v8, v8
	v_cvt_i32_f32_e32 v0, v0
	v_cvt_i32_f32_sdwa v3, v3 dst_sel:WORD_1 dst_unused:UNUSED_PAD src0_sel:DWORD
	v_cvt_i32_f32_e32 v8, v8
	v_lshlrev_b32_e32 v2, 8, v2
	v_and_b32_e32 v2, 0xff00, v2
	v_and_b32_e32 v3, 0xff0000, v3
	v_perm_b32 v0, v8, v0, s90
	v_or3_b32 v0, v0, v2, v3
	v_mul_f32_e32 v3, v11, v52
	v_mul_f32_e32 v2, v29, v52
	v_rndne_f32_e32 v3, v3
	v_mul_f32_e32 v8, v23, v52
	v_mul_f32_e32 v9, v47, v52
	v_rndne_f32_e32 v2, v2
	v_cvt_i32_f32_e32 v3, v3
	v_rndne_f32_e32 v8, v8
	v_rndne_f32_e32 v9, v9
	v_cvt_i32_f32_e32 v2, v2
	v_cvt_i32_f32_sdwa v8, v8 dst_sel:WORD_1 dst_unused:UNUSED_PAD src0_sel:DWORD
	v_cvt_i32_f32_e32 v9, v9
	v_lshlrev_b32_e32 v3, 8, v3
	v_and_b32_e32 v3, 0xff00, v3
	v_and_b32_e32 v8, 0xff0000, v8
	v_perm_b32 v2, v9, v2, s90
	v_or3_b32 v2, v2, v3, v8
	ds_write2_b32 v1, v0, v2 offset0:64 offset1:96
	s_waitcnt vmcnt(6)
	v_mul_f32_e32 v1, v56, v55
	v_mul_f32_e32 v0, v16, v55
	v_rndne_f32_e32 v1, v1
	s_waitcnt vmcnt(5)
	v_mul_f32_e32 v2, v4, v55
	s_waitcnt vmcnt(4)
	v_mul_f32_e32 v3, v36, v55
	v_rndne_f32_e32 v0, v0
	v_cvt_i32_f32_e32 v1, v1
	v_rndne_f32_e32 v2, v2
	v_rndne_f32_e32 v3, v3
	v_cvt_i32_f32_e32 v0, v0
	v_cvt_i32_f32_sdwa v2, v2 dst_sel:WORD_1 dst_unused:UNUSED_PAD src0_sel:DWORD
	v_cvt_i32_f32_e32 v3, v3
	v_lshlrev_b32_e32 v1, 8, v1
	v_and_b32_e32 v1, 0xff00, v1
	v_and_b32_e32 v2, 0xff0000, v2
	v_perm_b32 v0, v3, v0, s90
	v_mul_f32_e32 v3, v57, v54
	v_or3_b32 v0, v0, v1, v2
	v_mul_f32_e32 v2, v17, v54
	v_rndne_f32_e32 v3, v3
	v_mul_f32_e32 v4, v5, v54
	v_mul_f32_e32 v5, v37, v54
	v_rndne_f32_e32 v2, v2
	v_cvt_i32_f32_e32 v3, v3
	v_rndne_f32_e32 v4, v4
	v_rndne_f32_e32 v5, v5
	v_cvt_i32_f32_e32 v2, v2
	v_cvt_i32_f32_sdwa v4, v4 dst_sel:WORD_1 dst_unused:UNUSED_PAD src0_sel:DWORD
	v_cvt_i32_f32_e32 v5, v5
	v_lshlrev_b32_e32 v3, 8, v3
	v_and_b32_e32 v3, 0xff00, v3
	v_and_b32_e32 v4, 0xff0000, v4
	v_perm_b32 v2, v5, v2, s90
	v_add_u32_e32 v1, v144, v138
	v_or3_b32 v2, v2, v3, v4
	ds_write2_b32 v1, v0, v2 offset1:32
	v_mul_f32_e32 v2, v58, v53
	v_mul_f32_e32 v0, v18, v53
	v_rndne_f32_e32 v2, v2
	v_mul_f32_e32 v3, v6, v53
	v_mul_f32_e32 v4, v38, v53
	v_rndne_f32_e32 v0, v0
	v_cvt_i32_f32_e32 v2, v2
	v_rndne_f32_e32 v3, v3
	v_rndne_f32_e32 v4, v4
	v_cvt_i32_f32_e32 v0, v0
	v_cvt_i32_f32_sdwa v3, v3 dst_sel:WORD_1 dst_unused:UNUSED_PAD src0_sel:DWORD
	v_cvt_i32_f32_e32 v4, v4
	v_lshlrev_b32_e32 v2, 8, v2
	v_and_b32_e32 v2, 0xff00, v2
	v_and_b32_e32 v3, 0xff0000, v3
	v_perm_b32 v0, v4, v0, s90
	v_or3_b32 v0, v0, v2, v3
	v_mul_f32_e32 v3, v59, v52
	v_mul_f32_e32 v2, v19, v52
	v_rndne_f32_e32 v3, v3
	v_mul_f32_e32 v4, v7, v52
	v_mul_f32_e32 v5, v39, v52
	v_rndne_f32_e32 v2, v2
	v_cvt_i32_f32_e32 v3, v3
	v_rndne_f32_e32 v4, v4
	v_rndne_f32_e32 v5, v5
	v_cvt_i32_f32_e32 v2, v2
	v_cvt_i32_f32_sdwa v4, v4 dst_sel:WORD_1 dst_unused:UNUSED_PAD src0_sel:DWORD
	v_cvt_i32_f32_e32 v5, v5
	v_lshlrev_b32_e32 v3, 8, v3
	v_and_b32_e32 v3, 0xff00, v3
	v_and_b32_e32 v4, 0xff0000, v4
	v_perm_b32 v2, v5, v2, s90
	v_or3_b32 v2, v2, v3, v4
	ds_write2_b32 v1, v0, v2 offset0:64 offset1:96
	s_waitcnt vmcnt(2)
	v_mul_f32_e32 v1, v60, v55
	v_mul_f32_e32 v0, v30, v55
	v_rndne_f32_e32 v1, v1
	s_waitcnt vmcnt(1)
	v_mul_f32_e32 v2, v40, v55
	s_waitcnt vmcnt(0)
	v_mul_f32_e32 v3, v48, v55
	v_rndne_f32_e32 v0, v0
	v_cvt_i32_f32_e32 v1, v1
	v_rndne_f32_e32 v2, v2
	v_rndne_f32_e32 v3, v3
	v_cvt_i32_f32_e32 v0, v0
	v_cvt_i32_f32_sdwa v2, v2 dst_sel:WORD_1 dst_unused:UNUSED_PAD src0_sel:DWORD
	v_cvt_i32_f32_e32 v3, v3
	v_lshlrev_b32_e32 v1, 8, v1
	v_and_b32_e32 v1, 0xff00, v1
	v_and_b32_e32 v2, 0xff0000, v2
	v_perm_b32 v0, v3, v0, s90
	v_mul_f32_e32 v3, v61, v54
	v_or3_b32 v0, v0, v1, v2
	v_mul_f32_e32 v2, v31, v54
	v_rndne_f32_e32 v3, v3
	v_mul_f32_e32 v4, v41, v54
	v_mul_f32_e32 v5, v49, v54
	v_rndne_f32_e32 v2, v2
	v_cvt_i32_f32_e32 v3, v3
	v_rndne_f32_e32 v4, v4
	v_rndne_f32_e32 v5, v5
	v_cvt_i32_f32_e32 v2, v2
	v_cvt_i32_f32_sdwa v4, v4 dst_sel:WORD_1 dst_unused:UNUSED_PAD src0_sel:DWORD
	v_cvt_i32_f32_e32 v5, v5
	v_lshlrev_b32_e32 v3, 8, v3
	v_and_b32_e32 v3, 0xff00, v3
	v_and_b32_e32 v4, 0xff0000, v4
	v_perm_b32 v2, v5, v2, s90
	v_add_u32_e32 v1, v145, v138
	v_or3_b32 v2, v2, v3, v4
	ds_write2_b32 v1, v0, v2 offset1:32
	v_mul_f32_e32 v2, v62, v53
	v_mul_f32_e32 v0, v32, v53
	v_rndne_f32_e32 v2, v2
	v_mul_f32_e32 v3, v42, v53
	v_mul_f32_e32 v4, v50, v53
	v_rndne_f32_e32 v0, v0
	v_cvt_i32_f32_e32 v2, v2
	v_rndne_f32_e32 v3, v3
	v_rndne_f32_e32 v4, v4
	v_cvt_i32_f32_e32 v0, v0
	v_cvt_i32_f32_sdwa v3, v3 dst_sel:WORD_1 dst_unused:UNUSED_PAD src0_sel:DWORD
	v_cvt_i32_f32_e32 v4, v4
	v_lshlrev_b32_e32 v2, 8, v2
	v_and_b32_e32 v2, 0xff00, v2
	v_and_b32_e32 v3, 0xff0000, v3
	v_perm_b32 v0, v4, v0, s90
	v_or3_b32 v0, v0, v2, v3
	v_mul_f32_e32 v3, v63, v52
	v_mul_f32_e32 v2, v33, v52
	v_rndne_f32_e32 v3, v3
	v_mul_f32_e32 v4, v43, v52
	v_mul_f32_e32 v5, v51, v52
	v_rndne_f32_e32 v2, v2
	v_cvt_i32_f32_e32 v3, v3
	v_rndne_f32_e32 v4, v4
	v_rndne_f32_e32 v5, v5
	v_cvt_i32_f32_e32 v2, v2
	v_cvt_i32_f32_sdwa v4, v4 dst_sel:WORD_1 dst_unused:UNUSED_PAD src0_sel:DWORD
	v_cvt_i32_f32_e32 v5, v5
	v_lshlrev_b32_e32 v3, 8, v3
	v_and_b32_e32 v3, 0xff00, v3
	v_and_b32_e32 v4, 0xff0000, v4
	v_perm_b32 v2, v5, v2, s90
	v_or3_b32 v2, v2, v3, v4
	ds_write2_b32 v1, v0, v2 offset0:64 offset1:96
	s_waitcnt lgkmcnt(0)
	ds_read_b128 v[0:3], v147
	v_add_u32_e32 v10, s2, v164
	v_ashrrev_i32_e32 v11, 31, v10
	v_lshl_add_u64 v[8:9], v[132:133], 0, s[12:13]
	v_lshlrev_b64 v[4:5], 12, v[10:11]
	v_lshl_add_u64 v[12:13], v[8:9], 0, v[4:5]
	ds_read_b128 v[4:7], v149
	s_waitcnt lgkmcnt(1)
	global_store_dwordx4 v[12:13], v[0:3], off
	v_readlane_b32 s57, v255, 32
	v_readlane_b32 s58, v255, 33
	v_add_u32_e32 v0, 8, v10
	v_ashrrev_i32_e32 v1, 31, v0
	v_lshlrev_b64 v[0:1], 12, v[0:1]
	v_lshl_add_u64 v[0:1], v[8:9], 0, v[0:1]
	s_waitcnt lgkmcnt(0)
	global_store_dwordx4 v[0:1], v[4:7], off
	ds_read_b128 v[0:3], v151
	v_readlane_b32 s59, v255, 34
	v_add_u32_e32 v4, 16, v10
	v_ashrrev_i32_e32 v5, 31, v4
	v_lshlrev_b64 v[4:5], 12, v[4:5]
	v_lshl_add_u64 v[12:13], v[8:9], 0, v[4:5]
	ds_read_b128 v[4:7], v153
	s_waitcnt lgkmcnt(1)
	global_store_dwordx4 v[12:13], v[0:3], off
	v_readlane_b32 s60, v255, 35
	v_readlane_b32 s61, v255, 36
	v_add_u32_e32 v0, 24, v10
	v_ashrrev_i32_e32 v1, 31, v0
	v_lshlrev_b64 v[0:1], 12, v[0:1]
	v_lshl_add_u64 v[0:1], v[8:9], 0, v[0:1]
	s_waitcnt lgkmcnt(0)
	global_store_dwordx4 v[0:1], v[4:7], off
	ds_read_b128 v[0:3], v155
	v_readlane_b32 s62, v255, 37
	v_add_u32_e32 v4, 32, v10
	v_ashrrev_i32_e32 v5, 31, v4
	v_lshlrev_b64 v[4:5], 12, v[4:5]
	v_lshl_add_u64 v[12:13], v[8:9], 0, v[4:5]
	ds_read_b128 v[4:7], v157
	s_waitcnt lgkmcnt(1)
	global_store_dwordx4 v[12:13], v[0:3], off
	v_readlane_b32 s63, v255, 38
	s_nop 0
	v_add_u32_e32 v0, 40, v10
	v_ashrrev_i32_e32 v1, 31, v0
	v_lshlrev_b64 v[0:1], 12, v[0:1]
	v_lshl_add_u64 v[0:1], v[8:9], 0, v[0:1]
	s_waitcnt lgkmcnt(0)
	global_store_dwordx4 v[0:1], v[4:7], off
	ds_read_b128 v[0:3], v159
	s_nop 0
	v_add_u32_e32 v4, 48, v10
	v_ashrrev_i32_e32 v5, 31, v4
	v_lshlrev_b64 v[4:5], 12, v[4:5]
	v_lshl_add_u64 v[12:13], v[8:9], 0, v[4:5]
	ds_read_b128 v[4:7], v161
	s_waitcnt lgkmcnt(1)
	global_store_dwordx4 v[12:13], v[0:3], off
	s_nop 1
	v_add_u32_e32 v0, 56, v10
	v_ashrrev_i32_e32 v1, 31, v0
	v_lshlrev_b64 v[0:1], 12, v[0:1]
	v_lshl_add_u64 v[0:1], v[8:9], 0, v[0:1]
	s_waitcnt lgkmcnt(0)
	global_store_dwordx4 v[0:1], v[4:7], off
	s_waitcnt lgkmcnt(0)
	s_branch .LBB0_90
